# all per-segment s_setprio toggles removed from the six GEMM K-loops (static default priority)
# speedup vs baseline: 1.0097x; 1.0012x over previous
; #define LDA(dst, b, h) for (int m = 0; m < 4; ++m) for (int k = 0; k < 2; ++k) \
;     dst[m][k] = *reinterpret_cast<const bf16x8*>((char*)SA(b, h) + lds_byte(wr * 64 + m * 16 + fr, k * 32 + fq * 8))
; #define LDB(dst, b, h) for (int n = 0; n < 2; ++n) for (int k = 0; k < 2; ++k) \
;     dst[n][k] = *reinterpret_cast<const bf16x8*>((char*)SB(b, h) + lds_byte(wc * 32 + n * 16 + fr, k * 32 + fq * 8))
; #define WAIT_L(n) asm volatile("s_waitcnt lgkmcnt(" #n ")" ::: "memory")
; #define BAR __builtin_amdgcn_s_barrier()
; #define SCHED __builtin_amdgcn_sched_barrier(0)
; template <class Epi>
; DEVI void gemm_phase(const Params& p, const u16* __restrict__ A, const u16* __restrict__ Bt, const int M, const int N, const int K, const int Msplit, const Epi& epi) {
;     ...
;       LDB(B0, 0, 0); SCHED; LDA(At, 0, 0); STAGE(SA(1, 1), A, brow + HALF, t + 1);
;       WAIT_L(8); BAR; WAIT_L(0); MMA(0, 0, At, B0); BAR; SCHED;
;       LDB(B1, 0, 1); STAGE(SB(0, 0), Bt, bcol, t + 2);
;       BAR; WAIT_L(0); MMA(0, 1, At, B1); BAR;
;       LDA(At, 0, 1); STAGE(SA(0, 0), A, brow, t + 2);
;       BAR; WAIT_L(0); MMA(1, 0, At, B0); BAR; SCHED;
.LBB0_683:
	ds_read_b128 v[136:139], v208
	ds_read_b128 v[140:143], v208 offset:1024
	ds_read_b128 v[144:147], v208 offset:2048
	ds_read_b128 v[148:151], v208 offset:3072
	s_add_u32 s38, s17, s12
	s_addc_u32 s39, s56, s13
	s_add_u32 s38, s38, 0x80
	s_addc_u32 s39, s39, 0
	s_add_i32 s47, s2, 0xc000
	ds_read_b128 v[152:155], v209
	ds_read_b128 v[156:159], v209 offset:1024
	ds_read_b128 v[160:163], v210
	ds_read_b128 v[164:167], v210 offset:1024
	ds_read_b128 v[168:171], v211
	ds_read_b128 v[172:175], v211 offset:1024
	ds_read_b128 v[176:179], v226
	ds_read_b128 v[180:183], v226 offset:1024
	s_mov_b32 m0, s47
	v_lshl_add_u64 v[184:185], s[38:39], 0, v[206:207]
	s_add_i32 s46, s2, 0xe000
	global_load_lds_dwordx4 v[184:185], off
	v_lshl_add_u64 v[184:185], s[38:39], 0, v[204:205]
	s_mov_b32 m0, s46
	s_nop 0
	global_load_lds_dwordx4 v[184:185], off
	s_waitcnt lgkmcnt(8)
	s_barrier
	s_waitcnt lgkmcnt(0)
	s_waitcnt lgkmcnt(0)
	v_mfma_f32_16x16x32_bf16 v[132:135], v[136:139], v[152:155], v[132:135]
	v_mfma_f32_16x16x32_bf16 v[128:131], v[144:147], v[152:155], v[128:131]
	v_mfma_f32_16x16x32_bf16 v[124:127], v[136:139], v[160:163], v[124:127]
	v_mfma_f32_16x16x32_bf16 v[120:123], v[144:147], v[160:163], v[120:123]
	v_mfma_f32_16x16x32_bf16 v[116:119], v[136:139], v[168:171], v[116:119]
	v_mfma_f32_16x16x32_bf16 v[112:115], v[144:147], v[168:171], v[112:115]
	v_mfma_f32_16x16x32_bf16 v[108:111], v[136:139], v[176:179], v[108:111]
	v_mfma_f32_16x16x32_bf16 v[104:107], v[144:147], v[176:179], v[104:107]
	v_mfma_f32_16x16x32_bf16 v[132:135], v[140:143], v[156:159], v[132:135]
	v_mfma_f32_16x16x32_bf16 v[128:131], v[148:151], v[156:159], v[128:131]
	v_mfma_f32_16x16x32_bf16 v[124:127], v[140:143], v[164:167], v[124:127]
	v_mfma_f32_16x16x32_bf16 v[120:123], v[148:151], v[164:167], v[120:123]
	v_mfma_f32_16x16x32_bf16 v[116:119], v[140:143], v[172:175], v[116:119]
	v_mfma_f32_16x16x32_bf16 v[112:115], v[148:151], v[172:175], v[112:115]
	v_mfma_f32_16x16x32_bf16 v[108:111], v[140:143], v[180:183], v[108:111]
	v_mfma_f32_16x16x32_bf16 v[104:107], v[148:151], v[180:183], v[104:107]
	s_barrier
	s_add_u32 s45, s19, s12
	s_addc_u32 s58, s41, s13
	s_add_u32 s38, s45, 0x100
	s_addc_u32 s39, s58, 0
	s_add_i32 s44, s2, 0x10000
	ds_read_b128 v[184:187], v227
	ds_read_b128 v[188:191], v227 offset:1024
	ds_read_b128 v[192:195], v227 offset:2048
	ds_read_b128 v[196:199], v227 offset:3072
	s_mov_b32 m0, s44
	v_lshl_add_u64 v[200:201], s[38:39], 0, v[206:207]
	s_add_i32 s76, s2, 0x12000
	global_load_lds_dwordx4 v[200:201], off
	v_lshl_add_u64 v[200:201], s[38:39], 0, v[204:205]
	s_mov_b32 m0, s76
	s_nop 0
	global_load_lds_dwordx4 v[200:201], off
	s_barrier
	s_waitcnt lgkmcnt(0)
	s_waitcnt lgkmcnt(0)
	v_mfma_f32_16x16x32_bf16 v[100:103], v[184:187], v[152:155], v[100:103]
	v_mfma_f32_16x16x32_bf16 v[96:99], v[192:195], v[152:155], v[96:99]
	v_mfma_f32_16x16x32_bf16 v[92:95], v[184:187], v[160:163], v[92:95]
	v_mfma_f32_16x16x32_bf16 v[88:91], v[192:195], v[160:163], v[88:91]
	v_mfma_f32_16x16x32_bf16 v[84:87], v[184:187], v[168:171], v[84:87]
	v_mfma_f32_16x16x32_bf16 v[80:83], v[192:195], v[168:171], v[80:83]
	v_mfma_f32_16x16x32_bf16 v[76:79], v[184:187], v[176:179], v[76:79]
	v_mfma_f32_16x16x32_bf16 v[72:75], v[192:195], v[176:179], v[72:75]
	v_mfma_f32_16x16x32_bf16 v[100:103], v[188:191], v[156:159], v[100:103]
	v_mfma_f32_16x16x32_bf16 v[96:99], v[196:199], v[156:159], v[96:99]
	v_mfma_f32_16x16x32_bf16 v[92:95], v[188:191], v[164:167], v[92:95]
	v_mfma_f32_16x16x32_bf16 v[88:91], v[196:199], v[164:167], v[88:91]
	v_mfma_f32_16x16x32_bf16 v[84:87], v[188:191], v[172:175], v[84:87]
	v_mfma_f32_16x16x32_bf16 v[80:83], v[196:199], v[172:175], v[80:83]
	v_mfma_f32_16x16x32_bf16 v[76:79], v[188:191], v[180:183], v[76:79]
	v_mfma_f32_16x16x32_bf16 v[72:75], v[196:199], v[180:183], v[72:75]
	s_add_u32 s59, s42, s12
	s_addc_u32 s77, s43, s13
	s_add_u32 s38, s59, 0x100
	s_addc_u32 s39, s77, 0
	s_mov_b32 m0, s2
	s_barrier
	ds_read_b128 v[152:155], v209 offset:16384
	ds_read_b128 v[156:159], v209 offset:17408
	ds_read_b128 v[160:163], v210 offset:16384
	ds_read_b128 v[164:167], v210 offset:17408
	ds_read_b128 v[168:171], v211 offset:16384
	ds_read_b128 v[172:175], v211 offset:17408
	ds_read_b128 v[176:179], v226 offset:16384
	ds_read_b128 v[180:183], v226 offset:17408
	s_nop 0
	v_lshl_add_u64 v[200:201], s[38:39], 0, v[206:207]
	global_load_lds_dwordx4 v[200:201], off
	v_lshl_add_u64 v[200:201], s[38:39], 0, v[204:205]
	s_mov_b32 m0, s15
	s_nop 0
	global_load_lds_dwordx4 v[200:201], off
	s_barrier
	s_waitcnt lgkmcnt(0)
	s_waitcnt lgkmcnt(0)
	v_mfma_f32_16x16x32_bf16 v[68:71], v[136:139], v[152:155], v[68:71]
	v_mfma_f32_16x16x32_bf16 v[64:67], v[144:147], v[152:155], v[64:67]
	v_mfma_f32_16x16x32_bf16 v[60:63], v[136:139], v[160:163], v[60:63]
	v_mfma_f32_16x16x32_bf16 v[56:59], v[144:147], v[160:163], v[56:59]
	v_mfma_f32_16x16x32_bf16 v[52:55], v[136:139], v[168:171], v[52:55]
	v_mfma_f32_16x16x32_bf16 v[48:51], v[144:147], v[168:171], v[48:51]
	v_mfma_f32_16x16x32_bf16 v[44:47], v[136:139], v[176:179], v[44:47]
	v_mfma_f32_16x16x32_bf16 v[40:43], v[144:147], v[176:179], v[40:43]
	v_mfma_f32_16x16x32_bf16 v[68:71], v[140:143], v[156:159], v[68:71]
	v_mfma_f32_16x16x32_bf16 v[64:67], v[148:151], v[156:159], v[64:67]
	v_mfma_f32_16x16x32_bf16 v[60:63], v[140:143], v[164:167], v[60:63]
	v_mfma_f32_16x16x32_bf16 v[56:59], v[148:151], v[164:167], v[56:59]
	v_mfma_f32_16x16x32_bf16 v[52:55], v[140:143], v[172:175], v[52:55]
	v_mfma_f32_16x16x32_bf16 v[48:51], v[148:151], v[172:175], v[48:51]
	v_mfma_f32_16x16x32_bf16 v[44:47], v[140:143], v[180:183], v[44:47]
	v_mfma_f32_16x16x32_bf16 v[40:43], v[148:151], v[180:183], v[40:43]
	s_barrier
; #define LDA(dst, b, h) for (int m = 0; m < 4; ++m) for (int k = 0; k < 2; ++k) \
;     dst[m][k] = *reinterpret_cast<const bf16x8*>((char*)SA(b, h) + lds_byte(wr * 64 + m * 16 + fr, k * 32 + fq * 8))
; #define LDB(dst, b, h) for (int n = 0; n < 2; ++n) for (int k = 0; k < 2; ++k) \
;     dst[n][k] = *reinterpret_cast<const bf16x8*>((char*)SB(b, h) + lds_byte(wc * 32 + n * 16 + fr, k * 32 + fq * 8))
; #define WAIT_V(n) asm volatile("s_waitcnt vmcnt(" #n ")" ::: "memory")
; #define WAIT_L(n) asm volatile("s_waitcnt lgkmcnt(" #n ")" ::: "memory")
; #define BAR __builtin_amdgcn_s_barrier()
; #define SCHED __builtin_amdgcn_sched_barrier(0)
; template <class Epi>
; DEVI void gemm_phase(const Params& p, const u16* __restrict__ A, const u16* __restrict__ Bt, const int M, const int N, const int K, const int Msplit, const Epi& epi) {
;     ...
;       STAGE(SB(0, 1), Bt, bcol + HALF, t + 2);
;       WAIT_V(6); BAR; MMA(1, 1, At, B1); BAR;
;       LDB(B0, 1, 0); SCHED; LDA(At, 1, 0); STAGE(SA(0, 1), A, brow + HALF, t + 2);
;       WAIT_L(8); BAR; WAIT_L(0); MMA(0, 0, At, B0); BAR; SCHED;
;       LDB(B1, 1, 1); STAGE(SB(1, 0), Bt, bcol, t + 3);
;       BAR; WAIT_L(0); MMA(0, 1, At, B1); BAR;
;       LDA(At, 1, 1); STAGE(SA(1, 0), A, brow, t + 3);
;       BAR; WAIT_L(0); MMA(1, 0, At, B0); BAR; SCHED;
	s_add_u32 s88, s48, s12
	s_addc_u32 s89, s49, s13
	s_add_u32 s54, s88, 0x100
	s_addc_u32 s55, s89, 0
	s_add_i32 s38, s2, 0x14000
	s_mov_b32 m0, s38
	v_lshl_add_u64 v[136:137], s[54:55], 0, v[206:207]
	s_add_i32 s39, s2, 0x16000
	global_load_lds_dwordx4 v[136:137], off
	v_lshl_add_u64 v[136:137], s[54:55], 0, v[204:205]
	s_mov_b32 m0, s39
	s_nop 0
	global_load_lds_dwordx4 v[136:137], off
	s_waitcnt vmcnt(6)
	s_barrier
	v_mfma_f32_16x16x32_bf16 v[36:39], v[184:187], v[152:155], v[36:39]
	v_mfma_f32_16x16x32_bf16 v[32:35], v[192:195], v[152:155], v[32:35]
	v_mfma_f32_16x16x32_bf16 v[28:31], v[184:187], v[160:163], v[28:31]
	v_mfma_f32_16x16x32_bf16 v[24:27], v[192:195], v[160:163], v[24:27]
	v_mfma_f32_16x16x32_bf16 v[20:23], v[184:187], v[168:171], v[20:23]
	v_mfma_f32_16x16x32_bf16 v[16:19], v[192:195], v[168:171], v[16:19]
	v_mfma_f32_16x16x32_bf16 v[12:15], v[184:187], v[176:179], v[12:15]
	v_mfma_f32_16x16x32_bf16 v[8:11], v[192:195], v[176:179], v[8:11]
	v_mfma_f32_16x16x32_bf16 v[36:39], v[188:191], v[156:159], v[36:39]
	v_mfma_f32_16x16x32_bf16 v[32:35], v[196:199], v[156:159], v[32:35]
	v_mfma_f32_16x16x32_bf16 v[28:31], v[188:191], v[164:167], v[28:31]
	v_mfma_f32_16x16x32_bf16 v[24:27], v[196:199], v[164:167], v[24:27]
	v_mfma_f32_16x16x32_bf16 v[20:23], v[188:191], v[172:175], v[20:23]
	v_mfma_f32_16x16x32_bf16 v[16:19], v[196:199], v[172:175], v[16:19]
	v_mfma_f32_16x16x32_bf16 v[12:15], v[188:191], v[180:183], v[12:15]
	v_mfma_f32_16x16x32_bf16 v[8:11], v[196:199], v[180:183], v[8:11]
	s_barrier
	ds_read_b128 v[136:139], v228
	ds_read_b128 v[140:143], v228 offset:1024
	ds_read_b128 v[144:147], v228 offset:2048
	ds_read_b128 v[148:151], v228 offset:3072
	s_add_u32 s54, s52, s12
	s_addc_u32 s55, s53, s13
	s_mov_b32 m0, s24
	ds_read_b128 v[152:155], v209 offset:32768
	ds_read_b128 v[156:159], v209 offset:33792
	ds_read_b128 v[160:163], v210 offset:32768
	ds_read_b128 v[164:167], v210 offset:33792
	ds_read_b128 v[168:171], v211 offset:32768
	ds_read_b128 v[172:175], v211 offset:33792
	ds_read_b128 v[176:179], v226 offset:32768
	ds_read_b128 v[180:183], v226 offset:33792
	s_nop 0
	v_lshl_add_u64 v[184:185], s[54:55], 0, v[206:207]
	global_load_lds_dwordx4 v[184:185], off
	v_lshl_add_u64 v[184:185], s[54:55], 0, v[204:205]
	s_mov_b32 m0, s25
	s_nop 0
	global_load_lds_dwordx4 v[184:185], off
	s_waitcnt lgkmcnt(8)
	s_barrier
	s_waitcnt lgkmcnt(0)
	s_waitcnt lgkmcnt(0)
	v_mfma_f32_16x16x32_bf16 v[132:135], v[136:139], v[152:155], v[132:135]
	v_mfma_f32_16x16x32_bf16 v[128:131], v[144:147], v[152:155], v[128:131]
	v_mfma_f32_16x16x32_bf16 v[124:127], v[136:139], v[160:163], v[124:127]
	v_mfma_f32_16x16x32_bf16 v[120:123], v[144:147], v[160:163], v[120:123]
	v_mfma_f32_16x16x32_bf16 v[116:119], v[136:139], v[168:171], v[116:119]
	v_mfma_f32_16x16x32_bf16 v[112:115], v[144:147], v[168:171], v[112:115]
	v_mfma_f32_16x16x32_bf16 v[108:111], v[136:139], v[176:179], v[108:111]
	v_mfma_f32_16x16x32_bf16 v[104:107], v[144:147], v[176:179], v[104:107]
	v_mfma_f32_16x16x32_bf16 v[132:135], v[140:143], v[156:159], v[132:135]
	v_mfma_f32_16x16x32_bf16 v[128:131], v[148:151], v[156:159], v[128:131]
	v_mfma_f32_16x16x32_bf16 v[124:127], v[140:143], v[164:167], v[124:127]
	v_mfma_f32_16x16x32_bf16 v[120:123], v[148:151], v[164:167], v[120:123]
	v_mfma_f32_16x16x32_bf16 v[116:119], v[140:143], v[172:175], v[116:119]
	v_mfma_f32_16x16x32_bf16 v[112:115], v[148:151], v[172:175], v[112:115]
	v_mfma_f32_16x16x32_bf16 v[108:111], v[140:143], v[180:183], v[108:111]
	v_mfma_f32_16x16x32_bf16 v[104:107], v[148:151], v[180:183], v[104:107]
	s_barrier
	s_add_u32 s54, s45, 0x180
	s_addc_u32 s55, s58, 0
	s_add_i32 s63, s2, 0x18000
	ds_read_b128 v[184:187], v229
	ds_read_b128 v[188:191], v229 offset:1024
	ds_read_b128 v[192:195], v229 offset:2048
	ds_read_b128 v[196:199], v229 offset:3072
	s_mov_b32 m0, s63
	v_lshl_add_u64 v[200:201], s[54:55], 0, v[206:207]
	s_add_i32 s62, s2, 0x1a000
	global_load_lds_dwordx4 v[200:201], off
	v_lshl_add_u64 v[200:201], s[54:55], 0, v[204:205]
	s_mov_b32 m0, s62
	s_nop 0
	global_load_lds_dwordx4 v[200:201], off
	s_barrier
	s_waitcnt lgkmcnt(0)
	s_waitcnt lgkmcnt(0)
	v_mfma_f32_16x16x32_bf16 v[100:103], v[184:187], v[152:155], v[100:103]
	v_mfma_f32_16x16x32_bf16 v[96:99], v[192:195], v[152:155], v[96:99]
	v_mfma_f32_16x16x32_bf16 v[92:95], v[184:187], v[160:163], v[92:95]
	v_mfma_f32_16x16x32_bf16 v[88:91], v[192:195], v[160:163], v[88:91]
	v_mfma_f32_16x16x32_bf16 v[84:87], v[184:187], v[168:171], v[84:87]
	v_mfma_f32_16x16x32_bf16 v[80:83], v[192:195], v[168:171], v[80:83]
	v_mfma_f32_16x16x32_bf16 v[76:79], v[184:187], v[176:179], v[76:79]
	v_mfma_f32_16x16x32_bf16 v[72:75], v[192:195], v[176:179], v[72:75]
	v_mfma_f32_16x16x32_bf16 v[100:103], v[188:191], v[156:159], v[100:103]
	v_mfma_f32_16x16x32_bf16 v[96:99], v[196:199], v[156:159], v[96:99]
	v_mfma_f32_16x16x32_bf16 v[92:95], v[188:191], v[164:167], v[92:95]
	v_mfma_f32_16x16x32_bf16 v[88:91], v[196:199], v[164:167], v[88:91]
	v_mfma_f32_16x16x32_bf16 v[84:87], v[188:191], v[172:175], v[84:87]
	v_mfma_f32_16x16x32_bf16 v[80:83], v[196:199], v[172:175], v[80:83]
	v_mfma_f32_16x16x32_bf16 v[76:79], v[188:191], v[180:183], v[76:79]
	v_mfma_f32_16x16x32_bf16 v[72:75], v[196:199], v[180:183], v[72:75]
	s_add_u32 s54, s59, 0x180
	s_addc_u32 s55, s77, 0
	s_mov_b32 m0, s26
	s_barrier
	ds_read_b128 v[152:155], v209 offset:49152
	ds_read_b128 v[156:159], v209 offset:50176
	ds_read_b128 v[160:163], v210 offset:49152
	ds_read_b128 v[164:167], v210 offset:50176
	ds_read_b128 v[168:171], v211 offset:49152
	ds_read_b128 v[172:175], v211 offset:50176
	ds_read_b128 v[176:179], v226 offset:49152
	ds_read_b128 v[180:183], v226 offset:50176
	s_nop 0
	v_lshl_add_u64 v[200:201], s[54:55], 0, v[206:207]
	global_load_lds_dwordx4 v[200:201], off
	v_lshl_add_u64 v[200:201], s[54:55], 0, v[204:205]
	s_mov_b32 m0, s27
	s_nop 0
	global_load_lds_dwordx4 v[200:201], off
	s_barrier
; #define LDA(dst, b, h) for (int m = 0; m < 4; ++m) for (int k = 0; k < 2; ++k) \
;     dst[m][k] = *reinterpret_cast<const bf16x8*>((char*)SA(b, h) + lds_byte(wr * 64 + m * 16 + fr, k * 32 + fq * 8))
; #define LDB(dst, b, h) for (int n = 0; n < 2; ++n) for (int k = 0; k < 2; ++k) \
;     dst[n][k] = *reinterpret_cast<const bf16x8*>((char*)SB(b, h) + lds_byte(wc * 32 + n * 16 + fr, k * 32 + fq * 8))
; #define WAIT_V(n) asm volatile("s_waitcnt vmcnt(" #n ")" ::: "memory")
; #define WAIT_L(n) asm volatile("s_waitcnt lgkmcnt(" #n ")" ::: "memory")
; #define BAR __builtin_amdgcn_s_barrier()
; #define SCHED __builtin_amdgcn_sched_barrier(0)
; template <class Epi>
; DEVI void gemm_phase(const Params& p, const u16* __restrict__ A, const u16* __restrict__ Bt, const int M, const int N, const int K, const int Msplit, const Epi& epi) {
;     ...
;       BAR; WAIT_L(0); MMA(1, 0, At, B0); BAR; SCHED;
;       STAGE(SB(1, 1), Bt, bcol + HALF, t + 3);
;       WAIT_V(6); BAR; MMA(1, 1, At, B1); BAR;
;     }
;     { LDB(B0, 0, 0); LDA(At, 0, 0); STAGE(SA(1, 1), A, brow + HALF, nt - 1);
;       BAR; WAIT_L(0); MMA(0, 0, At, B0); BAR;
;       LDB(B1, 0, 1); BAR; WAIT_L(0); MMA(0, 1, At, B1); BAR;
	s_waitcnt lgkmcnt(0)
	s_waitcnt lgkmcnt(0)
	v_mfma_f32_16x16x32_bf16 v[68:71], v[136:139], v[152:155], v[68:71]
	v_mfma_f32_16x16x32_bf16 v[64:67], v[144:147], v[152:155], v[64:67]
	v_mfma_f32_16x16x32_bf16 v[60:63], v[136:139], v[160:163], v[60:63]
	v_mfma_f32_16x16x32_bf16 v[56:59], v[144:147], v[160:163], v[56:59]
	v_mfma_f32_16x16x32_bf16 v[52:55], v[136:139], v[168:171], v[52:55]
	v_mfma_f32_16x16x32_bf16 v[48:51], v[144:147], v[168:171], v[48:51]
	v_mfma_f32_16x16x32_bf16 v[44:47], v[136:139], v[176:179], v[44:47]
	v_mfma_f32_16x16x32_bf16 v[40:43], v[144:147], v[176:179], v[40:43]
	v_mfma_f32_16x16x32_bf16 v[68:71], v[140:143], v[156:159], v[68:71]
	v_mfma_f32_16x16x32_bf16 v[64:67], v[148:151], v[156:159], v[64:67]
	v_mfma_f32_16x16x32_bf16 v[60:63], v[140:143], v[164:167], v[60:63]
	v_mfma_f32_16x16x32_bf16 v[56:59], v[148:151], v[164:167], v[56:59]
	v_mfma_f32_16x16x32_bf16 v[52:55], v[140:143], v[172:175], v[52:55]
	v_mfma_f32_16x16x32_bf16 v[48:51], v[148:151], v[172:175], v[48:51]
	v_mfma_f32_16x16x32_bf16 v[44:47], v[140:143], v[180:183], v[44:47]
	v_mfma_f32_16x16x32_bf16 v[40:43], v[148:151], v[180:183], v[40:43]
	s_barrier
	s_add_u32 s54, s88, 0x180
	s_addc_u32 s55, s89, 0
	s_add_i32 s45, s2, 0x1c000
	s_mov_b32 m0, s45
	v_lshl_add_u64 v[136:137], s[54:55], 0, v[206:207]
	global_load_lds_dwordx4 v[136:137], off
	v_lshl_add_u64 v[136:137], s[54:55], 0, v[204:205]
	s_add_i32 s54, s2, 0x1e000
	s_mov_b32 m0, s54
	s_nop 0
	global_load_lds_dwordx4 v[136:137], off
	s_waitcnt vmcnt(6)
	s_barrier
	v_mfma_f32_16x16x32_bf16 v[36:39], v[184:187], v[152:155], v[36:39]
	v_mfma_f32_16x16x32_bf16 v[32:35], v[192:195], v[152:155], v[32:35]
	v_mfma_f32_16x16x32_bf16 v[28:31], v[184:187], v[160:163], v[28:31]
	v_mfma_f32_16x16x32_bf16 v[24:27], v[192:195], v[160:163], v[24:27]
	v_mfma_f32_16x16x32_bf16 v[20:23], v[184:187], v[168:171], v[20:23]
	v_mfma_f32_16x16x32_bf16 v[16:19], v[192:195], v[168:171], v[16:19]
	v_mfma_f32_16x16x32_bf16 v[12:15], v[184:187], v[176:179], v[12:15]
	v_mfma_f32_16x16x32_bf16 v[8:11], v[192:195], v[176:179], v[8:11]
	v_mfma_f32_16x16x32_bf16 v[36:39], v[188:191], v[156:159], v[36:39]
	v_mfma_f32_16x16x32_bf16 v[32:35], v[196:199], v[156:159], v[32:35]
	v_mfma_f32_16x16x32_bf16 v[28:31], v[188:191], v[164:167], v[28:31]
	v_mfma_f32_16x16x32_bf16 v[24:27], v[196:199], v[164:167], v[24:27]
	v_mfma_f32_16x16x32_bf16 v[20:23], v[188:191], v[172:175], v[20:23]
	v_mfma_f32_16x16x32_bf16 v[16:19], v[196:199], v[172:175], v[16:19]
	v_mfma_f32_16x16x32_bf16 v[12:15], v[188:191], v[180:183], v[12:15]
	v_mfma_f32_16x16x32_bf16 v[8:11], v[196:199], v[180:183], v[8:11]
	s_add_u32 s12, s12, 0x100
	s_addc_u32 s13, s13, 0
	s_add_i32 s57, s57, 2
	s_cmp_lt_u32 s57, 12
	s_barrier
	s_cbranch_scc1 .LBB0_683
	s_add_u32 s12, s22, 0x780
	s_addc_u32 s13, s23, 0
	s_mov_b32 m0, s47
	ds_read_b128 v[164:167], v208
	ds_read_b128 v[168:171], v208 offset:1024
	ds_read_b128 v[172:175], v208 offset:2048
	ds_read_b128 v[176:179], v208 offset:3072
	ds_read_b128 v[136:139], v209
	ds_read_b128 v[140:143], v209 offset:1024
	ds_read_b128 v[144:147], v210
	ds_read_b128 v[148:151], v210 offset:1024
	ds_read_b128 v[152:155], v211
	ds_read_b128 v[156:159], v211 offset:1024
	ds_read_b128 v[160:163], v226
	ds_read_b128 v[180:183], v226 offset:1024
	s_nop 0
	v_lshl_add_u64 v[184:185], s[12:13], 0, v[206:207]
	global_load_lds_dwordx4 v[184:185], off
	v_lshl_add_u64 v[184:185], s[12:13], 0, v[204:205]
	s_mov_b32 m0, s46
	s_nop 0
	global_load_lds_dwordx4 v[184:185], off
	s_barrier
	s_waitcnt lgkmcnt(0)
	s_waitcnt lgkmcnt(0)
	v_mfma_f32_16x16x32_bf16 v[132:135], v[164:167], v[136:139], v[132:135]
	v_mfma_f32_16x16x32_bf16 v[128:131], v[172:175], v[136:139], v[128:131]
	v_mfma_f32_16x16x32_bf16 v[124:127], v[164:167], v[144:147], v[124:127]
	v_mfma_f32_16x16x32_bf16 v[120:123], v[172:175], v[144:147], v[120:123]
	v_mfma_f32_16x16x32_bf16 v[116:119], v[164:167], v[152:155], v[116:119]
	v_mfma_f32_16x16x32_bf16 v[112:115], v[172:175], v[152:155], v[112:115]
	v_mfma_f32_16x16x32_bf16 v[108:111], v[164:167], v[160:163], v[108:111]
	v_mfma_f32_16x16x32_bf16 v[104:107], v[172:175], v[160:163], v[104:107]
	v_mfma_f32_16x16x32_bf16 v[132:135], v[168:171], v[140:143], v[132:135]
	v_mfma_f32_16x16x32_bf16 v[184:187], v[176:179], v[140:143], v[128:131]
	v_mfma_f32_16x16x32_bf16 v[124:127], v[168:171], v[148:151], v[124:127]
	v_mfma_f32_16x16x32_bf16 v[188:191], v[176:179], v[148:151], v[120:123]
	v_mfma_f32_16x16x32_bf16 v[116:119], v[168:171], v[156:159], v[116:119]
	v_mfma_f32_16x16x32_bf16 v[192:195], v[176:179], v[156:159], v[112:115]
	v_mfma_f32_16x16x32_bf16 v[108:111], v[168:171], v[180:183], v[108:111]
	v_mfma_f32_16x16x32_bf16 v[196:199], v[176:179], v[180:183], v[104:107]
	s_barrier
	s_nop 0
	ds_read_b128 v[104:107], v227
	ds_read_b128 v[112:115], v227 offset:1024
	ds_read_b128 v[120:123], v227 offset:2048
	ds_read_b128 v[128:131], v227 offset:3072
	s_barrier
	s_waitcnt lgkmcnt(0)
	s_waitcnt lgkmcnt(0)
	v_mfma_f32_16x16x32_bf16 v[100:103], v[104:107], v[136:139], v[100:103]
	v_mfma_f32_16x16x32_bf16 v[96:99], v[120:123], v[136:139], v[96:99]
	v_mfma_f32_16x16x32_bf16 v[92:95], v[104:107], v[144:147], v[92:95]
	v_mfma_f32_16x16x32_bf16 v[88:91], v[120:123], v[144:147], v[88:91]
	v_mfma_f32_16x16x32_bf16 v[84:87], v[104:107], v[152:155], v[84:87]
	v_mfma_f32_16x16x32_bf16 v[80:83], v[120:123], v[152:155], v[80:83]
	v_mfma_f32_16x16x32_bf16 v[76:79], v[104:107], v[160:163], v[76:79]
	v_mfma_f32_16x16x32_bf16 v[72:75], v[120:123], v[160:163], v[72:75]
	v_mfma_f32_16x16x32_bf16 v[100:103], v[112:115], v[140:143], v[100:103]
	v_mfma_f32_16x16x32_bf16 v[136:139], v[128:131], v[140:143], v[96:99]
	v_mfma_f32_16x16x32_bf16 v[92:95], v[112:115], v[148:151], v[92:95]
	v_mfma_f32_16x16x32_bf16 v[140:143], v[128:131], v[148:151], v[88:91]
	v_mfma_f32_16x16x32_bf16 v[84:87], v[112:115], v[156:159], v[84:87]
	v_mfma_f32_16x16x32_bf16 v[144:147], v[128:131], v[156:159], v[80:83]
	v_mfma_f32_16x16x32_bf16 v[76:79], v[112:115], v[180:183], v[76:79]
	v_mfma_f32_16x16x32_bf16 v[148:151], v[128:131], v[180:183], v[72:75]
	s_barrier
; #define LDA(dst, b, h) for (int m = 0; m < 4; ++m) for (int k = 0; k < 2; ++k) \
;     dst[m][k] = *reinterpret_cast<const bf16x8*>((char*)SA(b, h) + lds_byte(wr * 64 + m * 16 + fr, k * 32 + fq * 8))
; #define LDB(dst, b, h) for (int n = 0; n < 2; ++n) for (int k = 0; k < 2; ++k) \
;     dst[n][k] = *reinterpret_cast<const bf16x8*>((char*)SB(b, h) + lds_byte(wc * 32 + n * 16 + fr, k * 32 + fq * 8))
; #define WAIT_V(n) asm volatile("s_waitcnt vmcnt(" #n ")" ::: "memory")
; #define WAIT_L(n) asm volatile("s_waitcnt lgkmcnt(" #n ")" ::: "memory")
; #define BAR __builtin_amdgcn_s_barrier()
; #define PRO_K0(brow_, bcol_) do { STAGE(SB(0, 0), Bt, bcol_, 0); STAGE(SA(0, 0), A, brow_, 0); STAGE(SB(0, 1), Bt, (bcol_) + HALF, 0); STAGE(SA(0, 1), A, (brow_) + HALF, 0); } while (0)
; template <class Epi>
; DEVI void gemm_phase(const Params& p, const u16* __restrict__ A, const u16* __restrict__ Bt, const int M, const int N, const int K, const int Msplit, const Epi& epi) {
;     ...
;       LDA(At, 0, 1); WAIT_V(4); BAR; WAIT_L(0); MMA(1, 0, At, B0); MMA(1, 1, At, B1); BAR; }
;     { LDB(B0, 1, 0); LDA(At, 1, 0); WAIT_V(2); BAR;
;       if (have2) { const u16* Asv = A; const u16* Bsv = Bt; A = An; Bt = Bn; PRO_K0(pm * BM, pn * BM); A = Asv; Bt = Bsv; }
;       WAIT_L(0); MMA(0, 0, At, B0); BAR;
;       LDB(B1, 1, 1); if (have2) { WAIT_V(8); } else { WAIT_V(0); } BAR; WAIT_L(0); MMA(0, 1, At, B1); BAR;
	s_nop 0
	ds_read_b128 v[72:75], v209 offset:16384
	ds_read_b128 v[80:83], v209 offset:17408
	ds_read_b128 v[88:91], v210 offset:16384
	ds_read_b128 v[96:99], v210 offset:17408
	ds_read_b128 v[180:183], v211 offset:16384
	ds_read_b128 v[200:203], v211 offset:17408
	ds_read_b128 v[246:249], v226 offset:16384
	ds_read_b128 v[214:217], v226 offset:17408
	s_waitcnt vmcnt(4)
	s_barrier
	s_waitcnt lgkmcnt(0)
	s_waitcnt lgkmcnt(0)
	v_mfma_f32_16x16x32_bf16 v[68:71], v[164:167], v[72:75], v[68:71]
	v_mfma_f32_16x16x32_bf16 v[64:67], v[172:175], v[72:75], v[64:67]
	v_mfma_f32_16x16x32_bf16 v[60:63], v[164:167], v[88:91], v[60:63]
	v_mfma_f32_16x16x32_bf16 v[56:59], v[172:175], v[88:91], v[56:59]
	v_mfma_f32_16x16x32_bf16 v[52:55], v[164:167], v[180:183], v[52:55]
	v_mfma_f32_16x16x32_bf16 v[48:51], v[172:175], v[180:183], v[48:51]
	v_mfma_f32_16x16x32_bf16 v[44:47], v[164:167], v[246:249], v[44:47]
	v_mfma_f32_16x16x32_bf16 v[40:43], v[172:175], v[246:249], v[40:43]
	v_mfma_f32_16x16x32_bf16 v[68:71], v[168:171], v[80:83], v[68:71]
	v_mfma_f32_16x16x32_bf16 v[152:155], v[176:179], v[80:83], v[64:67]
	v_mfma_f32_16x16x32_bf16 v[60:63], v[168:171], v[96:99], v[60:63]
	v_mfma_f32_16x16x32_bf16 v[156:159], v[176:179], v[96:99], v[56:59]
	v_mfma_f32_16x16x32_bf16 v[52:55], v[168:171], v[200:203], v[52:55]
	v_mfma_f32_16x16x32_bf16 v[160:163], v[176:179], v[200:203], v[48:51]
	v_mfma_f32_16x16x32_bf16 v[44:47], v[168:171], v[214:217], v[44:47]
	v_mfma_f32_16x16x32_bf16 v[164:167], v[176:179], v[214:217], v[40:43]
	v_mfma_f32_16x16x32_bf16 v[36:39], v[104:107], v[72:75], v[36:39]
	v_mfma_f32_16x16x32_bf16 v[32:35], v[120:123], v[72:75], v[32:35]
	v_mfma_f32_16x16x32_bf16 v[28:31], v[104:107], v[88:91], v[28:31]
	v_mfma_f32_16x16x32_bf16 v[24:27], v[120:123], v[88:91], v[24:27]
	v_mfma_f32_16x16x32_bf16 v[20:23], v[104:107], v[180:183], v[20:23]
	v_mfma_f32_16x16x32_bf16 v[16:19], v[120:123], v[180:183], v[16:19]
	v_mfma_f32_16x16x32_bf16 v[12:15], v[104:107], v[246:249], v[12:15]
	v_mfma_f32_16x16x32_bf16 v[8:11], v[120:123], v[246:249], v[8:11]
	v_mfma_f32_16x16x32_bf16 v[36:39], v[112:115], v[80:83], v[36:39]
	v_mfma_f32_16x16x32_bf16 v[168:171], v[128:131], v[80:83], v[32:35]
	v_mfma_f32_16x16x32_bf16 v[28:31], v[112:115], v[96:99], v[28:31]
	v_mfma_f32_16x16x32_bf16 v[172:175], v[128:131], v[96:99], v[24:27]
	v_mfma_f32_16x16x32_bf16 v[20:23], v[112:115], v[200:203], v[20:23]
	v_mfma_f32_16x16x32_bf16 v[176:179], v[128:131], v[200:203], v[16:19]
	v_mfma_f32_16x16x32_bf16 v[12:15], v[112:115], v[214:217], v[12:15]
	v_mfma_f32_16x16x32_bf16 v[180:183], v[128:131], v[214:217], v[8:11]
	s_barrier
	s_nop 0
	ds_read_b128 v[8:11], v228
	ds_read_b128 v[16:19], v228 offset:1024
	ds_read_b128 v[24:27], v228 offset:2048
	ds_read_b128 v[32:35], v228 offset:3072
	ds_read_b128 v[88:91], v209 offset:32768
	ds_read_b128 v[200:203], v209 offset:33792
	ds_read_b128 v[72:75], v210 offset:32768
	ds_read_b128 v[80:83], v210 offset:33792
	ds_read_b128 v[56:59], v211 offset:32768
	ds_read_b128 v[64:67], v211 offset:33792
	ds_read_b128 v[40:43], v226 offset:32768
	ds_read_b128 v[48:51], v226 offset:33792
	s_waitcnt vmcnt(2)
	v_cndmask_b32_e64 v96, 0, 1, s[10:11]
	v_cmp_ne_u32_e64 s[12:13], 1, v96
	s_andn2_b64 vcc, exec, s[10:11]
	s_barrier
	s_cbranch_vccnz .LBB0_686
	s_lshl_b32 s10, s36, 8
	s_mov_b32 s11, s91
	s_lshl_b64 s[22:23], s[10:11], 11
	s_add_u32 s22, s0, s22
	s_addc_u32 s23, s1, s23
	s_mov_b32 m0, s44
	s_nop 0
	v_lshl_add_u64 v[96:97], s[22:23], 0, v[206:207]
	global_load_lds_dwordx4 v[96:97], off
	v_lshl_add_u64 v[96:97], s[22:23], 0, v[204:205]
	s_lshl_b32 s22, s40, 8
	s_mov_b32 s23, s91
	s_lshl_b64 s[42:43], s[22:23], 11
	s_add_u32 s42, s68, s42
	s_addc_u32 s43, s69, s43
	s_bitset1_b32 s10, 7
	s_mov_b32 m0, s76
	s_lshl_b64 s[10:11], s[10:11], 11
	global_load_lds_dwordx4 v[96:97], off
	s_mov_b32 m0, s2
	v_lshl_add_u64 v[96:97], s[42:43], 0, v[206:207]
	s_add_u32 s10, s0, s10
	global_load_lds_dwordx4 v[96:97], off
	v_lshl_add_u64 v[96:97], s[42:43], 0, v[204:205]
	s_mov_b32 m0, s15
	s_addc_u32 s11, s1, s11
	global_load_lds_dwordx4 v[96:97], off
	s_mov_b32 m0, s38
	v_lshl_add_u64 v[96:97], s[10:11], 0, v[206:207]
	global_load_lds_dwordx4 v[96:97], off
	v_lshl_add_u64 v[96:97], s[10:11], 0, v[204:205]
	s_or_b32 s10, s22, 0x80
	s_mov_b32 s11, s91
	s_lshl_b64 s[10:11], s[10:11], 11
	s_add_u32 s10, s68, s10
	s_mov_b32 m0, s39
	s_addc_u32 s11, s69, s11
	global_load_lds_dwordx4 v[96:97], off
	s_mov_b32 m0, s24
	v_lshl_add_u64 v[96:97], s[10:11], 0, v[206:207]
	global_load_lds_dwordx4 v[96:97], off
	v_lshl_add_u64 v[96:97], s[10:11], 0, v[204:205]
	s_mov_b32 m0, s25
	s_nop 0
	global_load_lds_dwordx4 v[96:97], off
.LBB0_686:
	s_waitcnt lgkmcnt(0)
	s_waitcnt lgkmcnt(0)
	v_mfma_f32_16x16x32_bf16 v[96:99], v[8:11], v[88:91], v[132:135]
	v_mfma_f32_16x16x32_bf16 v[128:131], v[16:19], v[200:203], v[96:99]
	v_mfma_f32_16x16x32_bf16 v[96:99], v[24:27], v[88:91], v[184:187]
	v_mfma_f32_16x16x32_bf16 v[132:135], v[32:35], v[200:203], v[96:99]
	v_mfma_f32_16x16x32_bf16 v[96:99], v[8:11], v[72:75], v[124:127]
	v_mfma_f32_16x16x32_bf16 v[120:123], v[16:19], v[80:83], v[96:99]
	v_mfma_f32_16x16x32_bf16 v[96:99], v[24:27], v[72:75], v[188:191]
	v_mfma_f32_16x16x32_bf16 v[124:127], v[32:35], v[80:83], v[96:99]
	v_mfma_f32_16x16x32_bf16 v[96:99], v[8:11], v[56:59], v[116:119]
	v_mfma_f32_16x16x32_bf16 v[112:115], v[16:19], v[64:67], v[96:99]
	v_mfma_f32_16x16x32_bf16 v[96:99], v[24:27], v[56:59], v[192:195]
	v_mfma_f32_16x16x32_bf16 v[116:119], v[32:35], v[64:67], v[96:99]
	v_mfma_f32_16x16x32_bf16 v[96:99], v[8:11], v[40:43], v[108:111]
	v_mfma_f32_16x16x32_bf16 v[104:107], v[16:19], v[48:51], v[96:99]
	v_mfma_f32_16x16x32_bf16 v[96:99], v[24:27], v[40:43], v[196:199]
	v_mfma_f32_16x16x32_bf16 v[108:111], v[32:35], v[48:51], v[96:99]
	s_barrier
	ds_read_b128 v[184:187], v229
	ds_read_b128 v[188:191], v229 offset:1024
	ds_read_b128 v[192:195], v229 offset:2048
	ds_read_b128 v[196:199], v229 offset:3072
	s_mov_b64 s[10:11], -1
	s_and_b64 vcc, exec, s[8:9]
	s_cbranch_vccz .LBB0_688
	s_waitcnt vmcnt(0)
	s_mov_b64 s[10:11], 0

; #define LDA(dst, b, h) for (int m = 0; m < 4; ++m) for (int k = 0; k < 2; ++k) \
;     dst[m][k] = *reinterpret_cast<const bf16x8*>((char*)SA(b, h) + lds_byte(wr * 64 + m * 16 + fr, k * 32 + fq * 8))
; #define LDB(dst, b, h) for (int n = 0; n < 2; ++n) for (int k = 0; k < 2; ++k) \
;     dst[n][k] = *reinterpret_cast<const bf16x8*>((char*)SB(b, h) + lds_byte(wc * 32 + n * 16 + fr, k * 32 + fq * 8))
; #define WAIT_V(n) asm volatile("s_waitcnt vmcnt(" #n ")" ::: "memory")
; #define WAIT_L(n) asm volatile("s_waitcnt lgkmcnt(" #n ")" ::: "memory")
; #define BAR __builtin_amdgcn_s_barrier()
; template <class Epi>
; DEVI void gemm_phase(const Params& p, const u16* __restrict__ A, const u16* __restrict__ Bt, const int M, const int N, const int K, const int Msplit, const Epi& epi) {
;     ...
;       LDB(B1, 1, 1); if (have2) { WAIT_V(8); } else { WAIT_V(0); } BAR; WAIT_L(0); MMA(0, 1, At, B1); BAR;
;       LDA(At, 1, 1); BAR; WAIT_L(0); MMA(1, 0, At, B0); MMA(1, 1, At, B1); BAR; }
;     if (wr == 0) BAR;
.LBB0_690:
	s_barrier
	s_waitcnt lgkmcnt(0)
	s_waitcnt lgkmcnt(0)
	v_mfma_f32_16x16x32_bf16 v[96:99], v[184:187], v[88:91], v[100:103]
	v_mfma_f32_16x16x32_bf16 v[88:91], v[192:195], v[88:91], v[136:139]
	v_mfma_f32_16x16x32_bf16 v[100:103], v[196:199], v[200:203], v[88:91]
	v_mfma_f32_16x16x32_bf16 v[88:91], v[184:187], v[72:75], v[92:95]
	v_mfma_f32_16x16x32_bf16 v[72:75], v[192:195], v[72:75], v[140:143]
	v_mfma_f32_16x16x32_bf16 v[92:95], v[196:199], v[80:83], v[72:75]
	v_mfma_f32_16x16x32_bf16 v[72:75], v[184:187], v[56:59], v[84:87]
	v_mfma_f32_16x16x32_bf16 v[56:59], v[192:195], v[56:59], v[144:147]
	v_mfma_f32_16x16x32_bf16 v[84:87], v[196:199], v[64:67], v[56:59]
	v_mfma_f32_16x16x32_bf16 v[56:59], v[184:187], v[40:43], v[76:79]
	v_mfma_f32_16x16x32_bf16 v[40:43], v[192:195], v[40:43], v[148:151]
	v_mfma_f32_16x16x32_bf16 v[96:99], v[188:191], v[200:203], v[96:99]
	v_mfma_f32_16x16x32_bf16 v[88:91], v[188:191], v[80:83], v[88:91]
	v_mfma_f32_16x16x32_bf16 v[80:83], v[188:191], v[64:67], v[72:75]
	v_mfma_f32_16x16x32_bf16 v[72:75], v[188:191], v[48:51], v[56:59]
	v_mfma_f32_16x16x32_bf16 v[76:79], v[196:199], v[48:51], v[40:43]
	s_barrier
	ds_read_b128 v[136:139], v209 offset:49152
	ds_read_b128 v[140:143], v209 offset:50176
	ds_read_b128 v[144:147], v210 offset:49152
	ds_read_b128 v[148:151], v210 offset:50176
	ds_read_b128 v[200:203], v211 offset:49152
	ds_read_b128 v[214:217], v211 offset:50176
	ds_read_b128 v[246:249], v226 offset:49152
	ds_read_b128 v[220:223], v226 offset:50176
	s_barrier
	s_waitcnt lgkmcnt(0)
	s_waitcnt lgkmcnt(0)
	v_mfma_f32_16x16x32_bf16 v[40:43], v[8:11], v[136:139], v[68:71]
	v_mfma_f32_16x16x32_bf16 v[64:67], v[16:19], v[140:143], v[40:43]
	v_mfma_f32_16x16x32_bf16 v[40:43], v[24:27], v[136:139], v[152:155]
	v_mfma_f32_16x16x32_bf16 v[68:71], v[32:35], v[140:143], v[40:43]
	v_mfma_f32_16x16x32_bf16 v[40:43], v[8:11], v[144:147], v[60:63]
	v_mfma_f32_16x16x32_bf16 v[56:59], v[16:19], v[148:151], v[40:43]
	v_mfma_f32_16x16x32_bf16 v[40:43], v[24:27], v[144:147], v[156:159]
	v_mfma_f32_16x16x32_bf16 v[60:63], v[32:35], v[148:151], v[40:43]
	v_mfma_f32_16x16x32_bf16 v[40:43], v[8:11], v[200:203], v[52:55]
	v_mfma_f32_16x16x32_bf16 v[48:51], v[16:19], v[214:217], v[40:43]
	v_mfma_f32_16x16x32_bf16 v[40:43], v[24:27], v[200:203], v[160:163]
	v_mfma_f32_16x16x32_bf16 v[8:11], v[8:11], v[246:249], v[44:47]
	v_mfma_f32_16x16x32_bf16 v[52:55], v[32:35], v[214:217], v[40:43]
	v_mfma_f32_16x16x32_bf16 v[40:43], v[16:19], v[220:223], v[8:11]
	v_mfma_f32_16x16x32_bf16 v[8:11], v[24:27], v[246:249], v[164:167]
	v_mfma_f32_16x16x32_bf16 v[44:47], v[32:35], v[220:223], v[8:11]
	v_mfma_f32_16x16x32_bf16 v[8:11], v[184:187], v[136:139], v[36:39]
	v_mfma_f32_16x16x32_bf16 v[32:35], v[188:191], v[140:143], v[8:11]
	v_mfma_f32_16x16x32_bf16 v[8:11], v[192:195], v[136:139], v[168:171]
	v_mfma_f32_16x16x32_bf16 v[36:39], v[196:199], v[140:143], v[8:11]
	v_mfma_f32_16x16x32_bf16 v[8:11], v[184:187], v[144:147], v[28:31]
	v_mfma_f32_16x16x32_bf16 v[24:27], v[188:191], v[148:151], v[8:11]
	v_mfma_f32_16x16x32_bf16 v[8:11], v[192:195], v[144:147], v[172:175]
	v_mfma_f32_16x16x32_bf16 v[28:31], v[196:199], v[148:151], v[8:11]
	v_mfma_f32_16x16x32_bf16 v[8:11], v[184:187], v[200:203], v[20:23]
	v_mfma_f32_16x16x32_bf16 v[16:19], v[188:191], v[214:217], v[8:11]
	v_mfma_f32_16x16x32_bf16 v[8:11], v[192:195], v[200:203], v[176:179]
	v_mfma_f32_16x16x32_bf16 v[20:23], v[196:199], v[214:217], v[8:11]
	v_mfma_f32_16x16x32_bf16 v[8:11], v[184:187], v[246:249], v[12:15]
	v_mfma_f32_16x16x32_bf16 v[12:15], v[192:195], v[246:249], v[180:183]
	v_mfma_f32_16x16x32_bf16 v[8:11], v[188:191], v[220:223], v[8:11]
	v_mfma_f32_16x16x32_bf16 v[12:15], v[196:199], v[220:223], v[12:15]
	s_barrier
	s_and_saveexec_b64 s[10:11], s[6:7]
	s_mov_b32 s89, 0x8800000
	s_cbranch_execz .LBB0_692
	s_barrier

; #define LDA(dst, b, h) for (int m = 0; m < 4; ++m) for (int k = 0; k < 2; ++k) \
;     dst[m][k] = *reinterpret_cast<const bf16x8*>((char*)SA(b, h) + lds_byte(wr * 64 + m * 16 + fr, k * 32 + fq * 8))
; #define LDB(dst, b, h) for (int n = 0; n < 2; ++n) for (int k = 0; k < 2; ++k) \
;     dst[n][k] = *reinterpret_cast<const bf16x8*>((char*)SB(b, h) + lds_byte(wc * 32 + n * 16 + fr, k * 32 + fq * 8))
; #define WAIT_L(n) asm volatile("s_waitcnt lgkmcnt(" #n ")" ::: "memory")
; #define BAR __builtin_amdgcn_s_barrier()
; #define SCHED __builtin_amdgcn_sched_barrier(0)
; template <class Epi>
; DEVI void gemm_phase(const Params& p, const u16* __restrict__ A, const u16* __restrict__ Bt, const int M, const int N, const int K, const int Msplit, const Epi& epi) {
;     ...
;     for (int t = 0; t < nt - 2; t += 2) {
;       LDB(B0, 0, 0); SCHED; LDA(At, 0, 0); STAGE(SA(1, 1), A, brow + HALF, t + 1);
;       WAIT_L(8); BAR; WAIT_L(0); MMA(0, 0, At, B0); BAR; SCHED;
;       LDB(B1, 0, 1); STAGE(SB(0, 0), Bt, bcol, t + 2);
;       BAR; WAIT_L(0); MMA(0, 1, At, B1); BAR;
;       LDA(At, 0, 1); STAGE(SA(0, 0), A, brow, t + 2);
;       BAR; WAIT_L(0); MMA(1, 0, At, B0); BAR; SCHED;
.LBB0_813:
	ds_read_b128 v[144:147], v246
	ds_read_b128 v[148:151], v246 offset:1024
	ds_read_b128 v[152:155], v246 offset:2048
	ds_read_b128 v[156:159], v246 offset:3072
	s_add_u32 s46, s25, s12
	s_addc_u32 s55, s26, s13
	s_add_u32 s38, s46, 0x80
	s_addc_u32 s39, s55, 0
	s_add_i32 s56, s78, 0
	s_add_i32 s90, s56, 0xc000
	ds_read_b128 v[160:163], v247
	ds_read_b128 v[164:167], v247 offset:1024
	ds_read_b128 v[168:171], v248
	ds_read_b128 v[172:175], v248 offset:1024
	ds_read_b128 v[176:179], v249
	ds_read_b128 v[180:183], v249 offset:1024
	ds_read_b128 v[184:187], v250
	ds_read_b128 v[188:191], v250 offset:1024
	s_mov_b32 m0, s90
	v_lshl_add_u64 v[192:193], s[38:39], 0, v[226:227]
	s_add_i32 s47, s56, 0xe000
	global_load_lds_dwordx4 v[192:193], off
	v_lshl_add_u64 v[192:193], s[38:39], 0, v[228:229]
	s_mov_b32 m0, s47
	s_nop 0
	global_load_lds_dwordx4 v[192:193], off
	s_waitcnt lgkmcnt(8)
	s_barrier
	s_waitcnt lgkmcnt(0)
	s_waitcnt lgkmcnt(0)
	v_mfma_f32_16x16x32_bf16 v[140:143], v[144:147], v[160:163], v[140:143]
	v_mfma_f32_16x16x32_bf16 v[136:139], v[152:155], v[160:163], v[136:139]
	v_mfma_f32_16x16x32_bf16 v[132:135], v[144:147], v[168:171], v[132:135]
	v_mfma_f32_16x16x32_bf16 v[128:131], v[152:155], v[168:171], v[128:131]
	v_mfma_f32_16x16x32_bf16 v[124:127], v[144:147], v[176:179], v[124:127]
	v_mfma_f32_16x16x32_bf16 v[120:123], v[152:155], v[176:179], v[120:123]
	v_mfma_f32_16x16x32_bf16 v[116:119], v[144:147], v[184:187], v[116:119]
	v_mfma_f32_16x16x32_bf16 v[112:115], v[152:155], v[184:187], v[112:115]
	v_mfma_f32_16x16x32_bf16 v[140:143], v[148:151], v[164:167], v[140:143]
	v_mfma_f32_16x16x32_bf16 v[136:139], v[156:159], v[164:167], v[136:139]
	v_mfma_f32_16x16x32_bf16 v[132:135], v[148:151], v[172:175], v[132:135]
	v_mfma_f32_16x16x32_bf16 v[128:131], v[156:159], v[172:175], v[128:131]
	v_mfma_f32_16x16x32_bf16 v[124:127], v[148:151], v[180:183], v[124:127]
	v_mfma_f32_16x16x32_bf16 v[120:123], v[156:159], v[180:183], v[120:123]
	v_mfma_f32_16x16x32_bf16 v[116:119], v[148:151], v[188:191], v[116:119]
	v_mfma_f32_16x16x32_bf16 v[112:115], v[156:159], v[188:191], v[112:115]
	s_barrier
	s_add_i32 s53, s53, 2
	s_add_u32 s57, s43, s12
	s_addc_u32 s58, s52, s13
	s_add_u32 s38, s57, 0x100
	s_addc_u32 s39, s58, 0
	s_add_i32 s89, s56, 0x10000
	ds_read_b128 v[192:195], v251
	ds_read_b128 v[196:199], v251 offset:1024
	ds_read_b128 v[200:203], v251 offset:2048
	ds_read_b128 v[204:207], v251 offset:3072
	s_mov_b32 m0, s89
	v_lshl_add_u64 v[208:209], s[38:39], 0, v[226:227]
	s_add_i32 s63, s56, 0x12000
	global_load_lds_dwordx4 v[208:209], off
	v_lshl_add_u64 v[208:209], s[38:39], 0, v[228:229]
	s_mov_b32 m0, s63
	s_nop 0
	global_load_lds_dwordx4 v[208:209], off
	s_barrier
	s_waitcnt lgkmcnt(0)
	s_waitcnt lgkmcnt(0)
	v_mfma_f32_16x16x32_bf16 v[108:111], v[192:195], v[160:163], v[108:111]
	v_mfma_f32_16x16x32_bf16 v[104:107], v[200:203], v[160:163], v[104:107]
	v_mfma_f32_16x16x32_bf16 v[100:103], v[192:195], v[168:171], v[100:103]
	v_mfma_f32_16x16x32_bf16 v[96:99], v[200:203], v[168:171], v[96:99]
	v_mfma_f32_16x16x32_bf16 v[92:95], v[192:195], v[176:179], v[92:95]
	v_mfma_f32_16x16x32_bf16 v[88:91], v[200:203], v[176:179], v[88:91]
	v_mfma_f32_16x16x32_bf16 v[84:87], v[192:195], v[184:187], v[84:87]
	v_mfma_f32_16x16x32_bf16 v[80:83], v[200:203], v[184:187], v[80:83]
	v_mfma_f32_16x16x32_bf16 v[108:111], v[196:199], v[164:167], v[108:111]
	v_mfma_f32_16x16x32_bf16 v[104:107], v[204:207], v[164:167], v[104:107]
	v_mfma_f32_16x16x32_bf16 v[100:103], v[196:199], v[172:175], v[100:103]
	v_mfma_f32_16x16x32_bf16 v[96:99], v[204:207], v[172:175], v[96:99]
	v_mfma_f32_16x16x32_bf16 v[92:95], v[196:199], v[180:183], v[92:95]
	v_mfma_f32_16x16x32_bf16 v[88:91], v[204:207], v[180:183], v[88:91]
	v_mfma_f32_16x16x32_bf16 v[84:87], v[196:199], v[188:191], v[84:87]
	v_mfma_f32_16x16x32_bf16 v[80:83], v[204:207], v[188:191], v[80:83]
	s_add_u32 s59, s20, s12
	s_addc_u32 s77, s21, s13
	s_add_u32 s38, s59, 0x100
	s_addc_u32 s39, s77, 0
	s_mov_b32 m0, s56
	s_barrier
	ds_read_b128 v[160:163], v247 offset:16384
	ds_read_b128 v[164:167], v247 offset:17408
	ds_read_b128 v[168:171], v248 offset:16384
	ds_read_b128 v[172:175], v248 offset:17408
	ds_read_b128 v[176:179], v249 offset:16384
	ds_read_b128 v[180:183], v249 offset:17408
	ds_read_b128 v[184:187], v250 offset:16384
	ds_read_b128 v[188:191], v250 offset:17408
	s_add_i32 s44, s56, 0x2000
	v_lshl_add_u64 v[208:209], s[38:39], 0, v[226:227]
	global_load_lds_dwordx4 v[208:209], off
	v_lshl_add_u64 v[208:209], s[38:39], 0, v[228:229]
	s_mov_b32 m0, s44
	s_nop 0
	global_load_lds_dwordx4 v[208:209], off
	s_barrier
	s_waitcnt lgkmcnt(0)
	s_waitcnt lgkmcnt(0)
	v_mfma_f32_16x16x32_bf16 v[76:79], v[144:147], v[160:163], v[76:79]
	v_mfma_f32_16x16x32_bf16 v[72:75], v[152:155], v[160:163], v[72:75]
	v_mfma_f32_16x16x32_bf16 v[68:71], v[144:147], v[168:171], v[68:71]
	v_mfma_f32_16x16x32_bf16 v[64:67], v[152:155], v[168:171], v[64:67]
	v_mfma_f32_16x16x32_bf16 v[60:63], v[144:147], v[176:179], v[60:63]
	v_mfma_f32_16x16x32_bf16 v[56:59], v[152:155], v[176:179], v[56:59]
	v_mfma_f32_16x16x32_bf16 v[52:55], v[144:147], v[184:187], v[52:55]
	v_mfma_f32_16x16x32_bf16 v[48:51], v[152:155], v[184:187], v[48:51]
	v_mfma_f32_16x16x32_bf16 v[76:79], v[148:151], v[164:167], v[76:79]
	v_mfma_f32_16x16x32_bf16 v[72:75], v[156:159], v[164:167], v[72:75]
	v_mfma_f32_16x16x32_bf16 v[68:71], v[148:151], v[172:175], v[68:71]
	v_mfma_f32_16x16x32_bf16 v[64:67], v[156:159], v[172:175], v[64:67]
	v_mfma_f32_16x16x32_bf16 v[60:63], v[148:151], v[180:183], v[60:63]
	v_mfma_f32_16x16x32_bf16 v[56:59], v[156:159], v[180:183], v[56:59]
	v_mfma_f32_16x16x32_bf16 v[52:55], v[148:151], v[188:191], v[52:55]
	v_mfma_f32_16x16x32_bf16 v[48:51], v[156:159], v[188:191], v[48:51]
	s_barrier
; #define LDA(dst, b, h) for (int m = 0; m < 4; ++m) for (int k = 0; k < 2; ++k) \
;     dst[m][k] = *reinterpret_cast<const bf16x8*>((char*)SA(b, h) + lds_byte(wr * 64 + m * 16 + fr, k * 32 + fq * 8))
; #define LDB(dst, b, h) for (int n = 0; n < 2; ++n) for (int k = 0; k < 2; ++k) \
;     dst[n][k] = *reinterpret_cast<const bf16x8*>((char*)SB(b, h) + lds_byte(wc * 32 + n * 16 + fr, k * 32 + fq * 8))
; #define WAIT_V(n) asm volatile("s_waitcnt vmcnt(" #n ")" ::: "memory")
; #define WAIT_L(n) asm volatile("s_waitcnt lgkmcnt(" #n ")" ::: "memory")
; #define BAR __builtin_amdgcn_s_barrier()
; #define SCHED __builtin_amdgcn_sched_barrier(0)
; template <class Epi>
; DEVI void gemm_phase(const Params& p, const u16* __restrict__ A, const u16* __restrict__ Bt, const int M, const int N, const int K, const int Msplit, const Epi& epi) {
;     ...
;       STAGE(SB(0, 1), Bt, bcol + HALF, t + 2);
;       WAIT_V(6); BAR; MMA(1, 1, At, B1); BAR;
;       LDB(B0, 1, 0); SCHED; LDA(At, 1, 0); STAGE(SA(0, 1), A, brow + HALF, t + 2);
;       WAIT_L(8); BAR; WAIT_L(0); MMA(0, 0, At, B0); BAR; SCHED;
;       LDB(B1, 1, 1); STAGE(SB(1, 0), Bt, bcol, t + 3);
;       BAR; WAIT_L(0); MMA(0, 1, At, B1); BAR;
;       LDA(At, 1, 1); STAGE(SA(1, 0), A, brow, t + 3);
	s_add_u32 vcc_lo, s22, s12
	s_addc_u32 vcc_hi, s23, s13
	s_add_u32 s38, vcc_lo, 0x100
	s_addc_u32 s39, vcc_hi, 0
	s_add_i32 s45, s56, 0x14000
	s_mov_b32 m0, s45
	v_lshl_add_u64 v[144:145], s[38:39], 0, v[226:227]
	global_load_lds_dwordx4 v[144:145], off
	v_lshl_add_u64 v[144:145], s[38:39], 0, v[228:229]
	s_add_i32 s38, s56, 0x16000
	s_mov_b32 m0, s38
	s_nop 0
	global_load_lds_dwordx4 v[144:145], off
	s_waitcnt vmcnt(6)
	s_barrier
	v_mfma_f32_16x16x32_bf16 v[44:47], v[192:195], v[160:163], v[44:47]
	v_mfma_f32_16x16x32_bf16 v[40:43], v[200:203], v[160:163], v[40:43]
	v_mfma_f32_16x16x32_bf16 v[36:39], v[192:195], v[168:171], v[36:39]
	v_mfma_f32_16x16x32_bf16 v[32:35], v[200:203], v[168:171], v[32:35]
	v_mfma_f32_16x16x32_bf16 v[28:31], v[192:195], v[176:179], v[28:31]
	v_mfma_f32_16x16x32_bf16 v[24:27], v[200:203], v[176:179], v[24:27]
	v_mfma_f32_16x16x32_bf16 v[20:23], v[192:195], v[184:187], v[20:23]
	v_mfma_f32_16x16x32_bf16 v[16:19], v[200:203], v[184:187], v[16:19]
	v_mfma_f32_16x16x32_bf16 v[44:47], v[196:199], v[164:167], v[44:47]
	v_mfma_f32_16x16x32_bf16 v[40:43], v[204:207], v[164:167], v[40:43]
	v_mfma_f32_16x16x32_bf16 v[36:39], v[196:199], v[172:175], v[36:39]
	v_mfma_f32_16x16x32_bf16 v[32:35], v[204:207], v[172:175], v[32:35]
	v_mfma_f32_16x16x32_bf16 v[28:31], v[196:199], v[180:183], v[28:31]
	v_mfma_f32_16x16x32_bf16 v[24:27], v[204:207], v[180:183], v[24:27]
	v_mfma_f32_16x16x32_bf16 v[20:23], v[196:199], v[188:191], v[20:23]
	v_mfma_f32_16x16x32_bf16 v[16:19], v[204:207], v[188:191], v[16:19]
	s_barrier
	ds_read_b128 v[144:147], v245
	ds_read_b128 v[148:151], v245 offset:1024
	ds_read_b128 v[152:155], v245 offset:2048
	ds_read_b128 v[156:159], v245 offset:3072
	s_add_u32 s54, s46, 0x100
	s_addc_u32 s55, s55, 0
	s_add_i32 s39, s56, 0x4000
	ds_read_b128 v[160:163], v247 offset:32768
	ds_read_b128 v[164:167], v247 offset:33792
	ds_read_b128 v[168:171], v248 offset:32768
	ds_read_b128 v[172:175], v248 offset:33792
	ds_read_b128 v[176:179], v249 offset:32768
	ds_read_b128 v[180:183], v249 offset:33792
	ds_read_b128 v[184:187], v250 offset:32768
	ds_read_b128 v[188:191], v250 offset:33792
	s_mov_b32 m0, s39
	v_lshl_add_u64 v[192:193], s[54:55], 0, v[226:227]
	s_add_i32 s46, s56, 0x6000
	global_load_lds_dwordx4 v[192:193], off
	v_lshl_add_u64 v[192:193], s[54:55], 0, v[228:229]
	s_mov_b32 m0, s46
	s_nop 0
	global_load_lds_dwordx4 v[192:193], off
	s_waitcnt lgkmcnt(8)
	s_barrier
	s_waitcnt lgkmcnt(0)
	s_waitcnt lgkmcnt(0)
	v_mfma_f32_16x16x32_bf16 v[140:143], v[144:147], v[160:163], v[140:143]
	v_mfma_f32_16x16x32_bf16 v[136:139], v[152:155], v[160:163], v[136:139]
	v_mfma_f32_16x16x32_bf16 v[132:135], v[144:147], v[168:171], v[132:135]
	v_mfma_f32_16x16x32_bf16 v[128:131], v[152:155], v[168:171], v[128:131]
	v_mfma_f32_16x16x32_bf16 v[124:127], v[144:147], v[176:179], v[124:127]
	v_mfma_f32_16x16x32_bf16 v[120:123], v[152:155], v[176:179], v[120:123]
	v_mfma_f32_16x16x32_bf16 v[116:119], v[144:147], v[184:187], v[116:119]
	v_mfma_f32_16x16x32_bf16 v[112:115], v[152:155], v[184:187], v[112:115]
	v_mfma_f32_16x16x32_bf16 v[140:143], v[148:151], v[164:167], v[140:143]
	v_mfma_f32_16x16x32_bf16 v[136:139], v[156:159], v[164:167], v[136:139]
	v_mfma_f32_16x16x32_bf16 v[132:135], v[148:151], v[172:175], v[132:135]
	v_mfma_f32_16x16x32_bf16 v[128:131], v[156:159], v[172:175], v[128:131]
	v_mfma_f32_16x16x32_bf16 v[124:127], v[148:151], v[180:183], v[124:127]
	v_mfma_f32_16x16x32_bf16 v[120:123], v[156:159], v[180:183], v[120:123]
	v_mfma_f32_16x16x32_bf16 v[116:119], v[148:151], v[188:191], v[116:119]
	v_mfma_f32_16x16x32_bf16 v[112:115], v[156:159], v[188:191], v[112:115]
	s_barrier
	s_add_u32 s54, s57, 0x180
	s_addc_u32 s55, s58, 0
	s_add_i32 s62, s56, 0x18000
	ds_read_b128 v[192:195], v232
	ds_read_b128 v[196:199], v232 offset:1024
	ds_read_b128 v[200:203], v232 offset:2048
	ds_read_b128 v[204:207], v232 offset:3072
	s_mov_b32 m0, s62
	v_lshl_add_u64 v[208:209], s[54:55], 0, v[226:227]
	s_add_i32 s57, s56, 0x1a000
	global_load_lds_dwordx4 v[208:209], off
	v_lshl_add_u64 v[208:209], s[54:55], 0, v[228:229]
	s_mov_b32 m0, s57
	s_nop 0
	global_load_lds_dwordx4 v[208:209], off
	s_barrier
	s_waitcnt lgkmcnt(0)
	s_waitcnt lgkmcnt(0)
	v_mfma_f32_16x16x32_bf16 v[108:111], v[192:195], v[160:163], v[108:111]
	v_mfma_f32_16x16x32_bf16 v[104:107], v[200:203], v[160:163], v[104:107]
	v_mfma_f32_16x16x32_bf16 v[100:103], v[192:195], v[168:171], v[100:103]
	v_mfma_f32_16x16x32_bf16 v[96:99], v[200:203], v[168:171], v[96:99]
	v_mfma_f32_16x16x32_bf16 v[92:95], v[192:195], v[176:179], v[92:95]
	v_mfma_f32_16x16x32_bf16 v[88:91], v[200:203], v[176:179], v[88:91]
	v_mfma_f32_16x16x32_bf16 v[84:87], v[192:195], v[184:187], v[84:87]
	v_mfma_f32_16x16x32_bf16 v[80:83], v[200:203], v[184:187], v[80:83]
	v_mfma_f32_16x16x32_bf16 v[108:111], v[196:199], v[164:167], v[108:111]
	v_mfma_f32_16x16x32_bf16 v[104:107], v[204:207], v[164:167], v[104:107]
	v_mfma_f32_16x16x32_bf16 v[100:103], v[196:199], v[172:175], v[100:103]
	v_mfma_f32_16x16x32_bf16 v[96:99], v[204:207], v[172:175], v[96:99]
	v_mfma_f32_16x16x32_bf16 v[92:95], v[196:199], v[180:183], v[92:95]
	v_mfma_f32_16x16x32_bf16 v[88:91], v[204:207], v[180:183], v[88:91]
	v_mfma_f32_16x16x32_bf16 v[84:87], v[196:199], v[188:191], v[84:87]
	v_mfma_f32_16x16x32_bf16 v[80:83], v[204:207], v[188:191], v[80:83]
	s_add_u32 s54, s59, 0x180
	s_addc_u32 s55, s77, 0
	s_add_i32 s77, s56, 0x8000
	s_barrier
; #define LDA(dst, b, h) for (int m = 0; m < 4; ++m) for (int k = 0; k < 2; ++k) \
;     dst[m][k] = *reinterpret_cast<const bf16x8*>((char*)SA(b, h) + lds_byte(wr * 64 + m * 16 + fr, k * 32 + fq * 8))
; #define LDB(dst, b, h) for (int n = 0; n < 2; ++n) for (int k = 0; k < 2; ++k) \
;     dst[n][k] = *reinterpret_cast<const bf16x8*>((char*)SB(b, h) + lds_byte(wc * 32 + n * 16 + fr, k * 32 + fq * 8))
; #define WAIT_V(n) asm volatile("s_waitcnt vmcnt(" #n ")" ::: "memory")
; #define WAIT_L(n) asm volatile("s_waitcnt lgkmcnt(" #n ")" ::: "memory")
; #define BAR __builtin_amdgcn_s_barrier()
; #define SCHED __builtin_amdgcn_sched_barrier(0)
; template <class Epi>
; DEVI void gemm_phase(const Params& p, const u16* __restrict__ A, const u16* __restrict__ Bt, const int M, const int N, const int K, const int Msplit, const Epi& epi) {
;     ...
;       LDA(At, 1, 1); STAGE(SA(1, 0), A, brow, t + 3);
;       BAR; WAIT_L(0); MMA(1, 0, At, B0); BAR; SCHED;
;       STAGE(SB(1, 1), Bt, bcol + HALF, t + 3);
;       WAIT_V(6); BAR; MMA(1, 1, At, B1); BAR;
;     }
;     { LDB(B0, 0, 0); LDA(At, 0, 0); STAGE(SA(1, 1), A, brow + HALF, nt - 1);
;       BAR; WAIT_L(0); MMA(0, 0, At, B0); BAR;
;       LDB(B1, 0, 1); BAR; WAIT_L(0); MMA(0, 1, At, B1); BAR;
	ds_read_b128 v[160:163], v247 offset:49152
	ds_read_b128 v[164:167], v247 offset:50176
	ds_read_b128 v[168:171], v248 offset:49152
	ds_read_b128 v[172:175], v248 offset:50176
	ds_read_b128 v[176:179], v249 offset:49152
	ds_read_b128 v[180:183], v249 offset:50176
	ds_read_b128 v[184:187], v250 offset:49152
	ds_read_b128 v[188:191], v250 offset:50176
	s_mov_b32 m0, s77
	v_lshl_add_u64 v[208:209], s[54:55], 0, v[226:227]
	s_add_i32 s88, s56, 0xa000
	global_load_lds_dwordx4 v[208:209], off
	v_lshl_add_u64 v[208:209], s[54:55], 0, v[228:229]
	s_mov_b32 m0, s88
	s_nop 0
	global_load_lds_dwordx4 v[208:209], off
	s_barrier
	s_waitcnt lgkmcnt(0)
	s_waitcnt lgkmcnt(0)
	v_mfma_f32_16x16x32_bf16 v[76:79], v[144:147], v[160:163], v[76:79]
	v_mfma_f32_16x16x32_bf16 v[72:75], v[152:155], v[160:163], v[72:75]
	v_mfma_f32_16x16x32_bf16 v[68:71], v[144:147], v[168:171], v[68:71]
	v_mfma_f32_16x16x32_bf16 v[64:67], v[152:155], v[168:171], v[64:67]
	v_mfma_f32_16x16x32_bf16 v[60:63], v[144:147], v[176:179], v[60:63]
	v_mfma_f32_16x16x32_bf16 v[56:59], v[152:155], v[176:179], v[56:59]
	v_mfma_f32_16x16x32_bf16 v[52:55], v[144:147], v[184:187], v[52:55]
	v_mfma_f32_16x16x32_bf16 v[48:51], v[152:155], v[184:187], v[48:51]
	v_mfma_f32_16x16x32_bf16 v[76:79], v[148:151], v[164:167], v[76:79]
	v_mfma_f32_16x16x32_bf16 v[72:75], v[156:159], v[164:167], v[72:75]
	v_mfma_f32_16x16x32_bf16 v[68:71], v[148:151], v[172:175], v[68:71]
	v_mfma_f32_16x16x32_bf16 v[64:67], v[156:159], v[172:175], v[64:67]
	v_mfma_f32_16x16x32_bf16 v[60:63], v[148:151], v[180:183], v[60:63]
	v_mfma_f32_16x16x32_bf16 v[56:59], v[156:159], v[180:183], v[56:59]
	v_mfma_f32_16x16x32_bf16 v[52:55], v[148:151], v[188:191], v[52:55]
	v_mfma_f32_16x16x32_bf16 v[48:51], v[156:159], v[188:191], v[48:51]
	s_barrier
	s_add_u32 s58, vcc_lo, 0x180
	s_addc_u32 s59, vcc_hi, 0
	s_add_i32 s54, s56, 0x1c000
	s_mov_b32 m0, s54
	v_lshl_add_u64 v[144:145], s[58:59], 0, v[226:227]
	s_add_i32 s55, s56, 0x1e000
	global_load_lds_dwordx4 v[144:145], off
	v_lshl_add_u64 v[144:145], s[58:59], 0, v[228:229]
	s_mov_b32 m0, s55
	s_nop 0
	global_load_lds_dwordx4 v[144:145], off
	s_waitcnt vmcnt(6)
	s_barrier
	v_mfma_f32_16x16x32_bf16 v[44:47], v[192:195], v[160:163], v[44:47]
	v_mfma_f32_16x16x32_bf16 v[40:43], v[200:203], v[160:163], v[40:43]
	v_mfma_f32_16x16x32_bf16 v[36:39], v[192:195], v[168:171], v[36:39]
	v_mfma_f32_16x16x32_bf16 v[32:35], v[200:203], v[168:171], v[32:35]
	v_mfma_f32_16x16x32_bf16 v[28:31], v[192:195], v[176:179], v[28:31]
	v_mfma_f32_16x16x32_bf16 v[24:27], v[200:203], v[176:179], v[24:27]
	v_mfma_f32_16x16x32_bf16 v[20:23], v[192:195], v[184:187], v[20:23]
	v_mfma_f32_16x16x32_bf16 v[16:19], v[200:203], v[184:187], v[16:19]
	v_mfma_f32_16x16x32_bf16 v[44:47], v[196:199], v[164:167], v[44:47]
	v_mfma_f32_16x16x32_bf16 v[40:43], v[204:207], v[164:167], v[40:43]
	v_mfma_f32_16x16x32_bf16 v[36:39], v[196:199], v[172:175], v[36:39]
	v_mfma_f32_16x16x32_bf16 v[32:35], v[204:207], v[172:175], v[32:35]
	v_mfma_f32_16x16x32_bf16 v[28:31], v[196:199], v[180:183], v[28:31]
	v_mfma_f32_16x16x32_bf16 v[24:27], v[204:207], v[180:183], v[24:27]
	v_mfma_f32_16x16x32_bf16 v[20:23], v[196:199], v[188:191], v[20:23]
	v_mfma_f32_16x16x32_bf16 v[16:19], v[204:207], v[188:191], v[16:19]
	s_add_u32 s12, s12, 0x100
	s_addc_u32 s13, s13, 0
	s_cmp_ge_i32 s53, s27
	s_barrier
	s_cbranch_scc0 .LBB0_813
	s_lshl_b32 s12, s49, 7
	s_add_u32 s20, s60, s12
	s_addc_u32 s21, s61, 0
	s_add_u32 s22, s4, s12
	s_mov_b32 m0, s90
	s_addc_u32 s23, s5, 0
	s_add_i32 s90, s24, -1
	s_lshl_b64 s[12:13], s[90:91], 7
	s_add_u32 s12, s25, s12
	s_addc_u32 s13, s26, s13
	ds_read_b128 v[172:175], v246
	ds_read_b128 v[176:179], v246 offset:1024
	ds_read_b128 v[180:183], v246 offset:2048
	ds_read_b128 v[184:187], v246 offset:3072
	ds_read_b128 v[144:147], v247
	ds_read_b128 v[148:151], v247 offset:1024
	ds_read_b128 v[152:155], v248
	ds_read_b128 v[156:159], v248 offset:1024
	ds_read_b128 v[160:163], v249
	ds_read_b128 v[164:167], v249 offset:1024
	ds_read_b128 v[168:171], v250
	ds_read_b128 v[188:191], v250 offset:1024
	s_nop 0
	v_lshl_add_u64 v[192:193], s[12:13], 0, v[226:227]
	global_load_lds_dwordx4 v[192:193], off
	v_lshl_add_u64 v[192:193], s[12:13], 0, v[228:229]
	s_mov_b32 m0, s47
	s_nop 0
	global_load_lds_dwordx4 v[192:193], off
	s_barrier
	s_waitcnt lgkmcnt(0)
	s_waitcnt lgkmcnt(0)
	v_mfma_f32_16x16x32_bf16 v[140:143], v[172:175], v[144:147], v[140:143]
	v_mfma_f32_16x16x32_bf16 v[136:139], v[180:183], v[144:147], v[136:139]
	v_mfma_f32_16x16x32_bf16 v[132:135], v[172:175], v[152:155], v[132:135]
	v_mfma_f32_16x16x32_bf16 v[128:131], v[180:183], v[152:155], v[128:131]
	v_mfma_f32_16x16x32_bf16 v[124:127], v[172:175], v[160:163], v[124:127]
	v_mfma_f32_16x16x32_bf16 v[120:123], v[180:183], v[160:163], v[120:123]
	v_mfma_f32_16x16x32_bf16 v[116:119], v[172:175], v[168:171], v[116:119]
	v_mfma_f32_16x16x32_bf16 v[112:115], v[180:183], v[168:171], v[112:115]
	v_mfma_f32_16x16x32_bf16 v[140:143], v[176:179], v[148:151], v[140:143]
	v_mfma_f32_16x16x32_bf16 v[136:139], v[184:187], v[148:151], v[136:139]
	v_mfma_f32_16x16x32_bf16 v[132:135], v[176:179], v[156:159], v[132:135]
	v_mfma_f32_16x16x32_bf16 v[128:131], v[184:187], v[156:159], v[128:131]
	v_mfma_f32_16x16x32_bf16 v[124:127], v[176:179], v[164:167], v[124:127]
	v_mfma_f32_16x16x32_bf16 v[120:123], v[184:187], v[164:167], v[120:123]
	v_mfma_f32_16x16x32_bf16 v[116:119], v[176:179], v[188:191], v[116:119]
	v_mfma_f32_16x16x32_bf16 v[112:115], v[184:187], v[188:191], v[112:115]
	s_barrier
	ds_read_b128 v[192:195], v251
	ds_read_b128 v[196:199], v251 offset:1024
	ds_read_b128 v[200:203], v251 offset:2048
	ds_read_b128 v[204:207], v251 offset:3072
	s_barrier
; #define LDA(dst, b, h) for (int m = 0; m < 4; ++m) for (int k = 0; k < 2; ++k) \
;     dst[m][k] = *reinterpret_cast<const bf16x8*>((char*)SA(b, h) + lds_byte(wr * 64 + m * 16 + fr, k * 32 + fq * 8))
; #define LDB(dst, b, h) for (int n = 0; n < 2; ++n) for (int k = 0; k < 2; ++k) \
;     dst[n][k] = *reinterpret_cast<const bf16x8*>((char*)SB(b, h) + lds_byte(wc * 32 + n * 16 + fr, k * 32 + fq * 8))
; #define WAIT_V(n) asm volatile("s_waitcnt vmcnt(" #n ")" ::: "memory")
; #define WAIT_L(n) asm volatile("s_waitcnt lgkmcnt(" #n ")" ::: "memory")
; #define BAR __builtin_amdgcn_s_barrier()
; #define PRO_K0(brow_, bcol_) do { STAGE(SB(0, 0), Bt, bcol_, 0); STAGE(SA(0, 0), A, brow_, 0); STAGE(SB(0, 1), Bt, (bcol_) + HALF, 0); STAGE(SA(0, 1), A, (brow_) + HALF, 0); } while (0)
; template <class Epi>
; DEVI void gemm_phase(const Params& p, const u16* __restrict__ A, const u16* __restrict__ Bt, const int M, const int N, const int K, const int Msplit, const Epi& epi) {
;     ...
;       LDB(B1, 0, 1); BAR; WAIT_L(0); MMA(0, 1, At, B1); BAR;
;       LDA(At, 0, 1); WAIT_V(4); BAR; WAIT_L(0); MMA(1, 0, At, B0); MMA(1, 1, At, B1); BAR; }
;     { LDB(B0, 1, 0); LDA(At, 1, 0); WAIT_V(2); BAR;
;       if (have2) { const u16* Asv = A; const u16* Bsv = Bt; A = An; Bt = Bn; PRO_K0(pm * BM, pn * BM); A = Asv; Bt = Bsv; }
	s_waitcnt lgkmcnt(0)
	s_waitcnt lgkmcnt(0)
	v_mfma_f32_16x16x32_bf16 v[108:111], v[192:195], v[144:147], v[108:111]
	v_mfma_f32_16x16x32_bf16 v[104:107], v[200:203], v[144:147], v[104:107]
	v_mfma_f32_16x16x32_bf16 v[100:103], v[192:195], v[152:155], v[100:103]
	v_mfma_f32_16x16x32_bf16 v[96:99], v[200:203], v[152:155], v[96:99]
	v_mfma_f32_16x16x32_bf16 v[92:95], v[192:195], v[160:163], v[92:95]
	v_mfma_f32_16x16x32_bf16 v[88:91], v[200:203], v[160:163], v[88:91]
	v_mfma_f32_16x16x32_bf16 v[84:87], v[192:195], v[168:171], v[84:87]
	v_mfma_f32_16x16x32_bf16 v[80:83], v[200:203], v[168:171], v[80:83]
	v_mfma_f32_16x16x32_bf16 v[108:111], v[196:199], v[148:151], v[108:111]
	v_mfma_f32_16x16x32_bf16 v[144:147], v[204:207], v[148:151], v[104:107]
	v_mfma_f32_16x16x32_bf16 v[100:103], v[196:199], v[156:159], v[100:103]
	v_mfma_f32_16x16x32_bf16 v[148:151], v[204:207], v[156:159], v[96:99]
	v_mfma_f32_16x16x32_bf16 v[92:95], v[196:199], v[164:167], v[92:95]
	v_mfma_f32_16x16x32_bf16 v[152:155], v[204:207], v[164:167], v[88:91]
	v_mfma_f32_16x16x32_bf16 v[84:87], v[196:199], v[188:191], v[84:87]
	v_mfma_f32_16x16x32_bf16 v[156:159], v[204:207], v[188:191], v[80:83]
	s_barrier
	s_nop 0
	ds_read_b128 v[80:83], v247 offset:16384
	ds_read_b128 v[88:91], v247 offset:17408
	ds_read_b128 v[96:99], v248 offset:16384
	ds_read_b128 v[104:107], v248 offset:17408
	ds_read_b128 v[188:191], v249 offset:16384
	ds_read_b128 v[208:211], v249 offset:17408
	ds_read_b128 v[214:217], v250 offset:16384
	ds_read_b128 v[220:223], v250 offset:17408
	s_waitcnt vmcnt(4)
	s_barrier
	s_waitcnt lgkmcnt(0)
	s_waitcnt lgkmcnt(0)
	v_mfma_f32_16x16x32_bf16 v[76:79], v[172:175], v[80:83], v[76:79]
	v_mfma_f32_16x16x32_bf16 v[72:75], v[180:183], v[80:83], v[72:75]
	v_mfma_f32_16x16x32_bf16 v[68:71], v[172:175], v[96:99], v[68:71]
	v_mfma_f32_16x16x32_bf16 v[64:67], v[180:183], v[96:99], v[64:67]
	v_mfma_f32_16x16x32_bf16 v[60:63], v[172:175], v[188:191], v[60:63]
	v_mfma_f32_16x16x32_bf16 v[56:59], v[180:183], v[188:191], v[56:59]
	v_mfma_f32_16x16x32_bf16 v[52:55], v[172:175], v[214:217], v[52:55]
	v_mfma_f32_16x16x32_bf16 v[48:51], v[180:183], v[214:217], v[48:51]
	v_mfma_f32_16x16x32_bf16 v[76:79], v[176:179], v[88:91], v[76:79]
	v_mfma_f32_16x16x32_bf16 v[160:163], v[184:187], v[88:91], v[72:75]
	v_mfma_f32_16x16x32_bf16 v[68:71], v[176:179], v[104:107], v[68:71]
	v_mfma_f32_16x16x32_bf16 v[164:167], v[184:187], v[104:107], v[64:67]
	v_mfma_f32_16x16x32_bf16 v[60:63], v[176:179], v[208:211], v[60:63]
	v_mfma_f32_16x16x32_bf16 v[168:171], v[184:187], v[208:211], v[56:59]
	v_mfma_f32_16x16x32_bf16 v[52:55], v[176:179], v[220:223], v[52:55]
	v_mfma_f32_16x16x32_bf16 v[172:175], v[184:187], v[220:223], v[48:51]
	v_mfma_f32_16x16x32_bf16 v[44:47], v[192:195], v[80:83], v[44:47]
	v_mfma_f32_16x16x32_bf16 v[40:43], v[200:203], v[80:83], v[40:43]
	v_mfma_f32_16x16x32_bf16 v[36:39], v[192:195], v[96:99], v[36:39]
	v_mfma_f32_16x16x32_bf16 v[32:35], v[200:203], v[96:99], v[32:35]
	v_mfma_f32_16x16x32_bf16 v[28:31], v[192:195], v[188:191], v[28:31]
	v_mfma_f32_16x16x32_bf16 v[24:27], v[200:203], v[188:191], v[24:27]
	v_mfma_f32_16x16x32_bf16 v[20:23], v[192:195], v[214:217], v[20:23]
	v_mfma_f32_16x16x32_bf16 v[16:19], v[200:203], v[214:217], v[16:19]
	v_mfma_f32_16x16x32_bf16 v[44:47], v[196:199], v[88:91], v[44:47]
	v_mfma_f32_16x16x32_bf16 v[176:179], v[204:207], v[88:91], v[40:43]
	v_mfma_f32_16x16x32_bf16 v[36:39], v[196:199], v[104:107], v[36:39]
	v_mfma_f32_16x16x32_bf16 v[180:183], v[204:207], v[104:107], v[32:35]
	v_mfma_f32_16x16x32_bf16 v[28:31], v[196:199], v[208:211], v[28:31]
	v_mfma_f32_16x16x32_bf16 v[184:187], v[204:207], v[208:211], v[24:27]
	v_mfma_f32_16x16x32_bf16 v[20:23], v[196:199], v[220:223], v[20:23]
	v_mfma_f32_16x16x32_bf16 v[188:191], v[204:207], v[220:223], v[16:19]
	s_barrier
	s_nop 0
	ds_read_b128 v[16:19], v245
	ds_read_b128 v[24:27], v245 offset:1024
	ds_read_b128 v[32:35], v245 offset:2048
	ds_read_b128 v[40:43], v245 offset:3072
	ds_read_b128 v[96:99], v247 offset:32768
	ds_read_b128 v[192:195], v247 offset:33792
	ds_read_b128 v[80:83], v248 offset:32768
	ds_read_b128 v[88:91], v248 offset:33792
	ds_read_b128 v[64:67], v249 offset:32768
	ds_read_b128 v[72:75], v249 offset:33792
	ds_read_b128 v[48:51], v250 offset:32768
	ds_read_b128 v[56:59], v250 offset:33792
	s_waitcnt vmcnt(2)
	s_and_b64 vcc, exec, s[10:11]
	s_mul_i32 s25, s48, 0x160000
	s_mul_i32 s24, s41, 0x160000
	s_barrier
	s_cbranch_vccz .LBB0_816
	s_lshl_b32 s26, s48, 8
	s_mul_hi_i32 s13, s26, 0x1600
	s_add_u32 s12, s22, s25
	s_addc_u32 s13, s23, s13
	s_mov_b32 m0, s89
	s_lshl_b32 s27, s41, 8
	v_lshl_add_u64 v[104:105], s[12:13], 0, v[226:227]
	global_load_lds_dwordx4 v[104:105], off
	v_lshl_add_u64 v[104:105], s[12:13], 0, v[228:229]
	s_mul_hi_i32 s13, s27, 0x1600
	s_add_u32 s12, s20, s24
	s_mov_b32 m0, s63
	s_addc_u32 s13, s21, s13
	global_load_lds_dwordx4 v[104:105], off
	s_mov_b32 m0, s56
	v_lshl_add_u64 v[104:105], s[12:13], 0, v[226:227]
	global_load_lds_dwordx4 v[104:105], off
	v_lshl_add_u64 v[104:105], s[12:13], 0, v[228:229]
	s_or_b32 s12, s26, 0x80
	s_mul_hi_i32 s13, s12, 0x1600
	s_mulk_i32 s12, 0x1600
	s_add_u32 s12, s22, s12
	s_mov_b32 m0, s44
	s_addc_u32 s13, s23, s13
	global_load_lds_dwordx4 v[104:105], off
	s_mov_b32 m0, s45
	v_lshl_add_u64 v[104:105], s[12:13], 0, v[226:227]
	global_load_lds_dwordx4 v[104:105], off
	v_lshl_add_u64 v[104:105], s[12:13], 0, v[228:229]
	s_or_b32 s12, s27, 0x80
	s_mul_hi_i32 s13, s12, 0x1600
	s_mulk_i32 s12, 0x1600
	s_add_u32 s12, s20, s12
	s_mov_b32 m0, s38
	s_addc_u32 s13, s21, s13
	global_load_lds_dwordx4 v[104:105], off
	s_mov_b32 m0, s39
	v_lshl_add_u64 v[104:105], s[12:13], 0, v[226:227]
	global_load_lds_dwordx4 v[104:105], off
	v_lshl_add_u64 v[104:105], s[12:13], 0, v[228:229]
	s_mov_b32 m0, s46
	s_nop 0
	global_load_lds_dwordx4 v[104:105], off
; #define LDB(dst, b, h) for (int n = 0; n < 2; ++n) for (int k = 0; k < 2; ++k) \
;     dst[n][k] = *reinterpret_cast<const bf16x8*>((char*)SB(b, h) + lds_byte(wc * 32 + n * 16 + fr, k * 32 + fq * 8))
; #define WAIT_V(n) asm volatile("s_waitcnt vmcnt(" #n ")" ::: "memory")
; #define WAIT_L(n) asm volatile("s_waitcnt lgkmcnt(" #n ")" ::: "memory")
; #define BAR __builtin_amdgcn_s_barrier()
; template <class Epi>
; DEVI void gemm_phase(const Params& p, const u16* __restrict__ A, const u16* __restrict__ Bt, const int M, const int N, const int K, const int Msplit, const Epi& epi) {
;     ...
;       WAIT_L(0); MMA(0, 0, At, B0); BAR;
;       LDB(B1, 1, 1); if (have2) { WAIT_V(8); } else { WAIT_V(0); } BAR; WAIT_L(0); MMA(0, 1, At, B1); BAR;
.LBB0_816:
	s_waitcnt lgkmcnt(0)
	s_waitcnt lgkmcnt(0)
	v_mfma_f32_16x16x32_bf16 v[104:107], v[16:19], v[96:99], v[140:143]
	v_mfma_f32_16x16x32_bf16 v[140:143], v[24:27], v[192:195], v[104:107]
	v_mfma_f32_16x16x32_bf16 v[104:107], v[32:35], v[96:99], v[136:139]
	v_mfma_f32_16x16x32_bf16 v[136:139], v[40:43], v[192:195], v[104:107]
	v_mfma_f32_16x16x32_bf16 v[104:107], v[16:19], v[80:83], v[132:135]
	v_mfma_f32_16x16x32_bf16 v[132:135], v[24:27], v[88:91], v[104:107]
	v_mfma_f32_16x16x32_bf16 v[104:107], v[32:35], v[80:83], v[128:131]
	v_mfma_f32_16x16x32_bf16 v[128:131], v[40:43], v[88:91], v[104:107]
	v_mfma_f32_16x16x32_bf16 v[104:107], v[16:19], v[64:67], v[124:127]
	v_mfma_f32_16x16x32_bf16 v[124:127], v[24:27], v[72:75], v[104:107]
	v_mfma_f32_16x16x32_bf16 v[104:107], v[32:35], v[64:67], v[120:123]
	v_mfma_f32_16x16x32_bf16 v[120:123], v[40:43], v[72:75], v[104:107]
	v_mfma_f32_16x16x32_bf16 v[104:107], v[16:19], v[48:51], v[116:119]
	v_mfma_f32_16x16x32_bf16 v[116:119], v[24:27], v[56:59], v[104:107]
	v_mfma_f32_16x16x32_bf16 v[104:107], v[32:35], v[48:51], v[112:115]
	v_mfma_f32_16x16x32_bf16 v[112:115], v[40:43], v[56:59], v[104:107]
	s_barrier
	ds_read_b128 v[196:199], v232
	ds_read_b128 v[200:203], v232 offset:1024
	ds_read_b128 v[204:207], v232 offset:2048
	ds_read_b128 v[208:211], v232 offset:3072
	s_mov_b64 s[12:13], -1
	s_and_b64 vcc, exec, s[16:17]
	s_cbranch_vccz .LBB0_818
	s_waitcnt vmcnt(0)
	s_mov_b64 s[12:13], 0

; #define LDA(dst, b, h) for (int m = 0; m < 4; ++m) for (int k = 0; k < 2; ++k) \
;     dst[m][k] = *reinterpret_cast<const bf16x8*>((char*)SA(b, h) + lds_byte(wr * 64 + m * 16 + fr, k * 32 + fq * 8))
; #define LDB(dst, b, h) for (int n = 0; n < 2; ++n) for (int k = 0; k < 2; ++k) \
;     dst[n][k] = *reinterpret_cast<const bf16x8*>((char*)SB(b, h) + lds_byte(wc * 32 + n * 16 + fr, k * 32 + fq * 8))
; #define WAIT_V(n) asm volatile("s_waitcnt vmcnt(" #n ")" ::: "memory")
; #define WAIT_L(n) asm volatile("s_waitcnt lgkmcnt(" #n ")" ::: "memory")
; #define BAR __builtin_amdgcn_s_barrier()
; template <class Epi>
; DEVI void gemm_phase(const Params& p, const u16* __restrict__ A, const u16* __restrict__ Bt, const int M, const int N, const int K, const int Msplit, const Epi& epi) {
;     ...
;       LDB(B1, 1, 1); if (have2) { WAIT_V(8); } else { WAIT_V(0); } BAR; WAIT_L(0); MMA(0, 1, At, B1); BAR;
;       LDA(At, 1, 1); BAR; WAIT_L(0); MMA(1, 0, At, B0); MMA(1, 1, At, B1); BAR; }
;     if (wr == 0) BAR;
.LBB0_820:
	s_barrier
	s_waitcnt lgkmcnt(0)
	s_waitcnt lgkmcnt(0)
	v_mfma_f32_16x16x32_bf16 v[104:107], v[196:199], v[96:99], v[108:111]
	v_mfma_f32_16x16x32_bf16 v[96:99], v[204:207], v[96:99], v[144:147]
	v_mfma_f32_16x16x32_bf16 v[108:111], v[208:211], v[192:195], v[96:99]
	v_mfma_f32_16x16x32_bf16 v[96:99], v[196:199], v[80:83], v[100:103]
	v_mfma_f32_16x16x32_bf16 v[80:83], v[204:207], v[80:83], v[148:151]
	v_mfma_f32_16x16x32_bf16 v[100:103], v[208:211], v[88:91], v[80:83]
	v_mfma_f32_16x16x32_bf16 v[80:83], v[196:199], v[64:67], v[92:95]
	v_mfma_f32_16x16x32_bf16 v[64:67], v[204:207], v[64:67], v[152:155]
	v_mfma_f32_16x16x32_bf16 v[92:95], v[208:211], v[72:75], v[64:67]
	v_mfma_f32_16x16x32_bf16 v[64:67], v[196:199], v[48:51], v[84:87]
	v_mfma_f32_16x16x32_bf16 v[48:51], v[204:207], v[48:51], v[156:159]
	v_mfma_f32_16x16x32_bf16 v[104:107], v[200:203], v[192:195], v[104:107]
	v_mfma_f32_16x16x32_bf16 v[96:99], v[200:203], v[88:91], v[96:99]
	v_mfma_f32_16x16x32_bf16 v[88:91], v[200:203], v[72:75], v[80:83]
	v_mfma_f32_16x16x32_bf16 v[80:83], v[200:203], v[56:59], v[64:67]
	v_mfma_f32_16x16x32_bf16 v[84:87], v[208:211], v[56:59], v[48:51]
	s_barrier
	ds_read_b128 v[144:147], v247 offset:49152
	ds_read_b128 v[148:151], v247 offset:50176
	ds_read_b128 v[152:155], v248 offset:49152
	ds_read_b128 v[156:159], v248 offset:50176
	ds_read_b128 v[192:195], v249 offset:49152
	ds_read_b128 v[214:217], v249 offset:50176
	ds_read_b128 v[220:223], v250 offset:49152
	ds_read_b128 v[236:239], v250 offset:50176
	s_barrier
	s_waitcnt lgkmcnt(0)
	s_waitcnt lgkmcnt(0)
	v_mfma_f32_16x16x32_bf16 v[48:51], v[16:19], v[144:147], v[76:79]
	v_mfma_f32_16x16x32_bf16 v[72:75], v[24:27], v[148:151], v[48:51]
	v_mfma_f32_16x16x32_bf16 v[48:51], v[32:35], v[144:147], v[160:163]
	v_mfma_f32_16x16x32_bf16 v[76:79], v[40:43], v[148:151], v[48:51]
	v_mfma_f32_16x16x32_bf16 v[48:51], v[16:19], v[152:155], v[68:71]
	v_mfma_f32_16x16x32_bf16 v[64:67], v[24:27], v[156:159], v[48:51]
	v_mfma_f32_16x16x32_bf16 v[48:51], v[32:35], v[152:155], v[164:167]
	v_mfma_f32_16x16x32_bf16 v[68:71], v[40:43], v[156:159], v[48:51]
	v_mfma_f32_16x16x32_bf16 v[48:51], v[16:19], v[192:195], v[60:63]
	v_mfma_f32_16x16x32_bf16 v[56:59], v[24:27], v[214:217], v[48:51]
	v_mfma_f32_16x16x32_bf16 v[48:51], v[32:35], v[192:195], v[168:171]
	v_mfma_f32_16x16x32_bf16 v[16:19], v[16:19], v[220:223], v[52:55]
	v_mfma_f32_16x16x32_bf16 v[60:63], v[40:43], v[214:217], v[48:51]
	v_mfma_f32_16x16x32_bf16 v[48:51], v[24:27], v[236:239], v[16:19]
	v_mfma_f32_16x16x32_bf16 v[16:19], v[32:35], v[220:223], v[172:175]
	v_mfma_f32_16x16x32_bf16 v[52:55], v[40:43], v[236:239], v[16:19]
	v_mfma_f32_16x16x32_bf16 v[16:19], v[196:199], v[144:147], v[44:47]
	v_mfma_f32_16x16x32_bf16 v[40:43], v[200:203], v[148:151], v[16:19]
	v_mfma_f32_16x16x32_bf16 v[16:19], v[204:207], v[144:147], v[176:179]
	v_mfma_f32_16x16x32_bf16 v[44:47], v[208:211], v[148:151], v[16:19]
	v_mfma_f32_16x16x32_bf16 v[16:19], v[196:199], v[152:155], v[36:39]
	v_mfma_f32_16x16x32_bf16 v[32:35], v[200:203], v[156:159], v[16:19]
	v_mfma_f32_16x16x32_bf16 v[16:19], v[204:207], v[152:155], v[180:183]
	v_mfma_f32_16x16x32_bf16 v[36:39], v[208:211], v[156:159], v[16:19]
	v_mfma_f32_16x16x32_bf16 v[16:19], v[196:199], v[192:195], v[28:31]
	v_mfma_f32_16x16x32_bf16 v[24:27], v[200:203], v[214:217], v[16:19]
	v_mfma_f32_16x16x32_bf16 v[16:19], v[204:207], v[192:195], v[184:187]
	v_mfma_f32_16x16x32_bf16 v[28:31], v[208:211], v[214:217], v[16:19]
	v_mfma_f32_16x16x32_bf16 v[16:19], v[196:199], v[220:223], v[20:23]
	v_mfma_f32_16x16x32_bf16 v[20:23], v[204:207], v[220:223], v[188:191]
	v_mfma_f32_16x16x32_bf16 v[16:19], v[200:203], v[236:239], v[16:19]
	v_mfma_f32_16x16x32_bf16 v[20:23], v[208:211], v[236:239], v[20:23]
	s_barrier
	s_and_saveexec_b64 s[12:13], s[8:9]
	s_cbranch_execz .LBB0_822
	s_barrier

; #define LDA(dst, b, h) for (int m = 0; m < 4; ++m) for (int k = 0; k < 2; ++k) \
;     dst[m][k] = *reinterpret_cast<const bf16x8*>((char*)SA(b, h) + lds_byte(wr * 64 + m * 16 + fr, k * 32 + fq * 8))
; #define LDB(dst, b, h) for (int n = 0; n < 2; ++n) for (int k = 0; k < 2; ++k) \
;     dst[n][k] = *reinterpret_cast<const bf16x8*>((char*)SB(b, h) + lds_byte(wc * 32 + n * 16 + fr, k * 32 + fq * 8))
; #define WAIT_L(n) asm volatile("s_waitcnt lgkmcnt(" #n ")" ::: "memory")
; #define BAR __builtin_amdgcn_s_barrier()
; #define SCHED __builtin_amdgcn_sched_barrier(0)
; template <class Epi>
; DEVI void gemm_phase(const Params& p, const u16* __restrict__ A, const u16* __restrict__ Bt, const int M, const int N, const int K, const int Msplit, const Epi& epi) {
;     ...
;     for (int t = 0; t < nt - 2; t += 2) {
;       LDB(B0, 0, 0); SCHED; LDA(At, 0, 0); STAGE(SA(1, 1), A, brow + HALF, t + 1);
;       WAIT_L(8); BAR; WAIT_L(0); MMA(0, 0, At, B0); BAR; SCHED;
;       LDB(B1, 0, 1); STAGE(SB(0, 0), Bt, bcol, t + 2);
;       BAR; WAIT_L(0); MMA(0, 1, At, B1); BAR;
;       LDA(At, 0, 1); STAGE(SA(0, 0), A, brow, t + 2);
;       BAR; WAIT_L(0); MMA(1, 0, At, B0); BAR; SCHED;
.LBB0_1104:
	ds_read_b128 v[128:131], v200
	ds_read_b128 v[132:135], v200 offset:1024
	ds_read_b128 v[136:139], v200 offset:2048
	ds_read_b128 v[140:143], v200 offset:3072
	s_add_u32 s38, s27, s14
	s_addc_u32 s39, s41, s15
	s_add_u32 s38, s38, 0x80
	s_addc_u32 s39, s39, 0
	s_add_i32 s47, s88, 0xc000
	ds_read_b128 v[144:147], v201
	ds_read_b128 v[148:151], v201 offset:1024
	ds_read_b128 v[152:155], v202
	ds_read_b128 v[156:159], v202 offset:1024
	ds_read_b128 v[160:163], v203
	ds_read_b128 v[164:167], v203 offset:1024
	ds_read_b128 v[168:171], v204
	ds_read_b128 v[172:175], v204 offset:1024
	s_mov_b32 m0, s47
	v_lshl_add_u64 v[176:177], s[38:39], 0, v[196:197]
	s_add_i32 s46, s88, 0xe000
	global_load_lds_dwordx4 v[176:177], off
	v_lshl_add_u64 v[176:177], s[38:39], 0, v[198:199]
	s_mov_b32 m0, s46
	s_nop 0
	global_load_lds_dwordx4 v[176:177], off
	s_waitcnt lgkmcnt(8)
	s_barrier
	s_waitcnt lgkmcnt(0)
	s_waitcnt lgkmcnt(0)
	v_mfma_f32_16x16x32_bf16 v[124:127], v[144:147], v[128:131], v[124:127]
	v_mfma_f32_16x16x32_bf16 v[120:123], v[144:147], v[136:139], v[120:123]
	v_mfma_f32_16x16x32_bf16 v[116:119], v[152:155], v[128:131], v[116:119]
	v_mfma_f32_16x16x32_bf16 v[112:115], v[152:155], v[136:139], v[112:115]
	v_mfma_f32_16x16x32_bf16 v[108:111], v[160:163], v[128:131], v[108:111]
	v_mfma_f32_16x16x32_bf16 v[104:107], v[160:163], v[136:139], v[104:107]
	v_mfma_f32_16x16x32_bf16 v[100:103], v[168:171], v[128:131], v[100:103]
	v_mfma_f32_16x16x32_bf16 v[96:99], v[168:171], v[136:139], v[96:99]
	v_mfma_f32_16x16x32_bf16 v[124:127], v[148:151], v[132:135], v[124:127]
	v_mfma_f32_16x16x32_bf16 v[120:123], v[148:151], v[140:143], v[120:123]
	v_mfma_f32_16x16x32_bf16 v[116:119], v[156:159], v[132:135], v[116:119]
	v_mfma_f32_16x16x32_bf16 v[112:115], v[156:159], v[140:143], v[112:115]
	v_mfma_f32_16x16x32_bf16 v[108:111], v[164:167], v[132:135], v[108:111]
	v_mfma_f32_16x16x32_bf16 v[104:107], v[164:167], v[140:143], v[104:107]
	v_mfma_f32_16x16x32_bf16 v[100:103], v[172:175], v[132:135], v[100:103]
	v_mfma_f32_16x16x32_bf16 v[96:99], v[172:175], v[140:143], v[96:99]
	s_barrier
	s_add_u32 s43, s19, s14
	s_addc_u32 s44, s20, s15
	s_add_u32 s38, s43, 0x100
	s_addc_u32 s39, s44, 0
	s_add_i32 s45, s88, 0x10000
	ds_read_b128 v[176:179], v205
	ds_read_b128 v[180:183], v205 offset:1024
	ds_read_b128 v[184:187], v205 offset:2048
	ds_read_b128 v[188:191], v205 offset:3072
	s_mov_b32 m0, s45
	v_lshl_add_u64 v[192:193], s[38:39], 0, v[196:197]
	s_add_i32 s49, s88, 0x12000
	global_load_lds_dwordx4 v[192:193], off
	v_lshl_add_u64 v[192:193], s[38:39], 0, v[198:199]
	s_mov_b32 m0, s49
	s_nop 0
	global_load_lds_dwordx4 v[192:193], off
	s_barrier
	s_waitcnt lgkmcnt(0)
	s_waitcnt lgkmcnt(0)
	v_mfma_f32_16x16x32_bf16 v[92:95], v[144:147], v[176:179], v[92:95]
	v_mfma_f32_16x16x32_bf16 v[88:91], v[144:147], v[184:187], v[88:91]
	v_mfma_f32_16x16x32_bf16 v[84:87], v[152:155], v[176:179], v[84:87]
	v_mfma_f32_16x16x32_bf16 v[80:83], v[152:155], v[184:187], v[80:83]
	v_mfma_f32_16x16x32_bf16 v[76:79], v[160:163], v[176:179], v[76:79]
	v_mfma_f32_16x16x32_bf16 v[72:75], v[160:163], v[184:187], v[72:75]
	v_mfma_f32_16x16x32_bf16 v[68:71], v[168:171], v[176:179], v[68:71]
	v_mfma_f32_16x16x32_bf16 v[64:67], v[168:171], v[184:187], v[64:67]
	v_mfma_f32_16x16x32_bf16 v[92:95], v[148:151], v[180:183], v[92:95]
	v_mfma_f32_16x16x32_bf16 v[88:91], v[148:151], v[188:191], v[88:91]
	v_mfma_f32_16x16x32_bf16 v[84:87], v[156:159], v[180:183], v[84:87]
	v_mfma_f32_16x16x32_bf16 v[80:83], v[156:159], v[188:191], v[80:83]
	v_mfma_f32_16x16x32_bf16 v[76:79], v[164:167], v[180:183], v[76:79]
	v_mfma_f32_16x16x32_bf16 v[72:75], v[164:167], v[188:191], v[72:75]
	v_mfma_f32_16x16x32_bf16 v[68:71], v[172:175], v[180:183], v[68:71]
	v_mfma_f32_16x16x32_bf16 v[64:67], v[172:175], v[188:191], v[64:67]
	s_add_u32 s54, s21, s14
	s_addc_u32 s55, s22, s15
	s_add_u32 s38, s54, 0x100
	s_addc_u32 s39, s55, 0
	s_mov_b32 m0, s88
	s_barrier
	ds_read_b128 v[144:147], v201 offset:16384
	ds_read_b128 v[148:151], v201 offset:17408
	ds_read_b128 v[152:155], v202 offset:16384
	ds_read_b128 v[156:159], v202 offset:17408
	ds_read_b128 v[160:163], v203 offset:16384
	ds_read_b128 v[164:167], v203 offset:17408
	ds_read_b128 v[168:171], v204 offset:16384
	ds_read_b128 v[172:175], v204 offset:17408
	s_nop 0
	v_lshl_add_u64 v[192:193], s[38:39], 0, v[196:197]
	global_load_lds_dwordx4 v[192:193], off
	v_lshl_add_u64 v[192:193], s[38:39], 0, v[198:199]
	s_mov_b32 m0, s89
	s_nop 0
	global_load_lds_dwordx4 v[192:193], off
	s_barrier
	s_waitcnt lgkmcnt(0)
	s_waitcnt lgkmcnt(0)
	v_mfma_f32_16x16x32_bf16 v[60:63], v[144:147], v[128:131], v[60:63]
	v_mfma_f32_16x16x32_bf16 v[56:59], v[144:147], v[136:139], v[56:59]
	v_mfma_f32_16x16x32_bf16 v[52:55], v[152:155], v[128:131], v[52:55]
	v_mfma_f32_16x16x32_bf16 v[48:51], v[152:155], v[136:139], v[48:51]
	v_mfma_f32_16x16x32_bf16 v[44:47], v[160:163], v[128:131], v[44:47]
	v_mfma_f32_16x16x32_bf16 v[40:43], v[160:163], v[136:139], v[40:43]
	v_mfma_f32_16x16x32_bf16 v[36:39], v[168:171], v[128:131], v[36:39]
	v_mfma_f32_16x16x32_bf16 v[32:35], v[168:171], v[136:139], v[32:35]
	v_mfma_f32_16x16x32_bf16 v[60:63], v[148:151], v[132:135], v[60:63]
	v_mfma_f32_16x16x32_bf16 v[56:59], v[148:151], v[140:143], v[56:59]
	v_mfma_f32_16x16x32_bf16 v[52:55], v[156:159], v[132:135], v[52:55]
	v_mfma_f32_16x16x32_bf16 v[48:51], v[156:159], v[140:143], v[48:51]
	v_mfma_f32_16x16x32_bf16 v[44:47], v[164:167], v[132:135], v[44:47]
	v_mfma_f32_16x16x32_bf16 v[40:43], v[164:167], v[140:143], v[40:43]
	v_mfma_f32_16x16x32_bf16 v[36:39], v[172:175], v[132:135], v[36:39]
	v_mfma_f32_16x16x32_bf16 v[32:35], v[172:175], v[140:143], v[32:35]
	s_barrier
; #define LDA(dst, b, h) for (int m = 0; m < 4; ++m) for (int k = 0; k < 2; ++k) \
;     dst[m][k] = *reinterpret_cast<const bf16x8*>((char*)SA(b, h) + lds_byte(wr * 64 + m * 16 + fr, k * 32 + fq * 8))
; #define LDB(dst, b, h) for (int n = 0; n < 2; ++n) for (int k = 0; k < 2; ++k) \
;     dst[n][k] = *reinterpret_cast<const bf16x8*>((char*)SB(b, h) + lds_byte(wc * 32 + n * 16 + fr, k * 32 + fq * 8))
; #define WAIT_V(n) asm volatile("s_waitcnt vmcnt(" #n ")" ::: "memory")
; #define WAIT_L(n) asm volatile("s_waitcnt lgkmcnt(" #n ")" ::: "memory")
; #define BAR __builtin_amdgcn_s_barrier()
; #define SCHED __builtin_amdgcn_sched_barrier(0)
; template <class Epi>
; DEVI void gemm_phase(const Params& p, const u16* __restrict__ A, const u16* __restrict__ Bt, const int M, const int N, const int K, const int Msplit, const Epi& epi) {
;     ...
;       STAGE(SB(0, 1), Bt, bcol + HALF, t + 2);
;       WAIT_V(6); BAR; MMA(1, 1, At, B1); BAR;
;       LDB(B0, 1, 0); SCHED; LDA(At, 1, 0); STAGE(SA(0, 1), A, brow + HALF, t + 2);
;       WAIT_L(8); BAR; WAIT_L(0); MMA(0, 0, At, B0); BAR; SCHED;
;       LDB(B1, 1, 1); STAGE(SB(1, 0), Bt, bcol, t + 3);
;       BAR; WAIT_L(0); MMA(0, 1, At, B1); BAR;
;       LDA(At, 1, 1); STAGE(SA(1, 0), A, brow, t + 3);
	s_add_u32 s58, s23, s14
	s_addc_u32 s59, s24, s15
	s_add_u32 s52, s58, 0x100
	s_addc_u32 s53, s59, 0
	s_add_i32 s38, s88, 0x14000
	s_mov_b32 m0, s38
	v_lshl_add_u64 v[128:129], s[52:53], 0, v[196:197]
	s_add_i32 s39, s88, 0x16000
	global_load_lds_dwordx4 v[128:129], off
	v_lshl_add_u64 v[128:129], s[52:53], 0, v[198:199]
	s_mov_b32 m0, s39
	s_nop 0
	global_load_lds_dwordx4 v[128:129], off
	s_waitcnt vmcnt(6)
	s_barrier
	v_mfma_f32_16x16x32_bf16 v[28:31], v[144:147], v[176:179], v[28:31]
	v_mfma_f32_16x16x32_bf16 v[24:27], v[144:147], v[184:187], v[24:27]
	v_mfma_f32_16x16x32_bf16 v[20:23], v[152:155], v[176:179], v[20:23]
	v_mfma_f32_16x16x32_bf16 v[16:19], v[152:155], v[184:187], v[16:19]
	v_mfma_f32_16x16x32_bf16 v[12:15], v[160:163], v[176:179], v[12:15]
	v_mfma_f32_16x16x32_bf16 v[8:11], v[160:163], v[184:187], v[8:11]
	v_mfma_f32_16x16x32_bf16 v[4:7], v[168:171], v[176:179], v[4:7]
	v_mfma_f32_16x16x32_bf16 v[0:3], v[168:171], v[184:187], v[0:3]
	v_mfma_f32_16x16x32_bf16 v[28:31], v[148:151], v[180:183], v[28:31]
	v_mfma_f32_16x16x32_bf16 v[24:27], v[148:151], v[188:191], v[24:27]
	v_mfma_f32_16x16x32_bf16 v[20:23], v[156:159], v[180:183], v[20:23]
	v_mfma_f32_16x16x32_bf16 v[16:19], v[156:159], v[188:191], v[16:19]
	v_mfma_f32_16x16x32_bf16 v[12:15], v[164:167], v[180:183], v[12:15]
	v_mfma_f32_16x16x32_bf16 v[8:11], v[164:167], v[188:191], v[8:11]
	v_mfma_f32_16x16x32_bf16 v[4:7], v[172:175], v[180:183], v[4:7]
	v_mfma_f32_16x16x32_bf16 v[0:3], v[172:175], v[188:191], v[0:3]
	s_barrier
	ds_read_b128 v[128:131], v206
	ds_read_b128 v[132:135], v206 offset:1024
	ds_read_b128 v[136:139], v206 offset:2048
	ds_read_b128 v[140:143], v206 offset:3072
	s_add_u32 s52, s25, s14
	s_addc_u32 s53, s26, s15
	s_mov_b32 m0, s90
	ds_read_b128 v[144:147], v201 offset:32768
	ds_read_b128 v[148:151], v201 offset:33792
	ds_read_b128 v[152:155], v202 offset:32768
	ds_read_b128 v[156:159], v202 offset:33792
	ds_read_b128 v[160:163], v203 offset:32768
	ds_read_b128 v[164:167], v203 offset:33792
	ds_read_b128 v[168:171], v204 offset:32768
	ds_read_b128 v[172:175], v204 offset:33792
	s_nop 0
	v_lshl_add_u64 v[176:177], s[52:53], 0, v[196:197]
	global_load_lds_dwordx4 v[176:177], off
	v_lshl_add_u64 v[176:177], s[52:53], 0, v[198:199]
	s_mov_b32 m0, s77
	s_nop 0
	global_load_lds_dwordx4 v[176:177], off
	s_waitcnt lgkmcnt(8)
	s_barrier
	s_waitcnt lgkmcnt(0)
	s_waitcnt lgkmcnt(0)
	v_mfma_f32_16x16x32_bf16 v[124:127], v[144:147], v[128:131], v[124:127]
	v_mfma_f32_16x16x32_bf16 v[120:123], v[144:147], v[136:139], v[120:123]
	v_mfma_f32_16x16x32_bf16 v[116:119], v[152:155], v[128:131], v[116:119]
	v_mfma_f32_16x16x32_bf16 v[112:115], v[152:155], v[136:139], v[112:115]
	v_mfma_f32_16x16x32_bf16 v[108:111], v[160:163], v[128:131], v[108:111]
	v_mfma_f32_16x16x32_bf16 v[104:107], v[160:163], v[136:139], v[104:107]
	v_mfma_f32_16x16x32_bf16 v[100:103], v[168:171], v[128:131], v[100:103]
	v_mfma_f32_16x16x32_bf16 v[96:99], v[168:171], v[136:139], v[96:99]
	v_mfma_f32_16x16x32_bf16 v[124:127], v[148:151], v[132:135], v[124:127]
	v_mfma_f32_16x16x32_bf16 v[120:123], v[148:151], v[140:143], v[120:123]
	v_mfma_f32_16x16x32_bf16 v[116:119], v[156:159], v[132:135], v[116:119]
	v_mfma_f32_16x16x32_bf16 v[112:115], v[156:159], v[140:143], v[112:115]
	v_mfma_f32_16x16x32_bf16 v[108:111], v[164:167], v[132:135], v[108:111]
	v_mfma_f32_16x16x32_bf16 v[104:107], v[164:167], v[140:143], v[104:107]
	v_mfma_f32_16x16x32_bf16 v[100:103], v[172:175], v[132:135], v[100:103]
	v_mfma_f32_16x16x32_bf16 v[96:99], v[172:175], v[140:143], v[96:99]
	s_barrier
	s_add_u32 s52, s43, 0x180
	s_addc_u32 s53, s44, 0
	s_add_i32 s48, s88, 0x18000
	ds_read_b128 v[176:179], v207
	ds_read_b128 v[180:183], v207 offset:1024
	ds_read_b128 v[184:187], v207 offset:2048
	ds_read_b128 v[188:191], v207 offset:3072
	s_mov_b32 m0, s48
	v_lshl_add_u64 v[192:193], s[52:53], 0, v[196:197]
	s_add_i32 s43, s88, 0x1a000
	global_load_lds_dwordx4 v[192:193], off
	v_lshl_add_u64 v[192:193], s[52:53], 0, v[198:199]
	s_mov_b32 m0, s43
	s_nop 0
	global_load_lds_dwordx4 v[192:193], off
	s_barrier
	s_waitcnt lgkmcnt(0)
	s_waitcnt lgkmcnt(0)
	v_mfma_f32_16x16x32_bf16 v[92:95], v[144:147], v[176:179], v[92:95]
	v_mfma_f32_16x16x32_bf16 v[88:91], v[144:147], v[184:187], v[88:91]
	v_mfma_f32_16x16x32_bf16 v[84:87], v[152:155], v[176:179], v[84:87]
	v_mfma_f32_16x16x32_bf16 v[80:83], v[152:155], v[184:187], v[80:83]
	v_mfma_f32_16x16x32_bf16 v[76:79], v[160:163], v[176:179], v[76:79]
	v_mfma_f32_16x16x32_bf16 v[72:75], v[160:163], v[184:187], v[72:75]
	v_mfma_f32_16x16x32_bf16 v[68:71], v[168:171], v[176:179], v[68:71]
	v_mfma_f32_16x16x32_bf16 v[64:67], v[168:171], v[184:187], v[64:67]
	v_mfma_f32_16x16x32_bf16 v[92:95], v[148:151], v[180:183], v[92:95]
	v_mfma_f32_16x16x32_bf16 v[88:91], v[148:151], v[188:191], v[88:91]
	v_mfma_f32_16x16x32_bf16 v[84:87], v[156:159], v[180:183], v[84:87]
	v_mfma_f32_16x16x32_bf16 v[80:83], v[156:159], v[188:191], v[80:83]
	v_mfma_f32_16x16x32_bf16 v[76:79], v[164:167], v[180:183], v[76:79]
	v_mfma_f32_16x16x32_bf16 v[72:75], v[164:167], v[188:191], v[72:75]
	v_mfma_f32_16x16x32_bf16 v[68:71], v[172:175], v[180:183], v[68:71]
	v_mfma_f32_16x16x32_bf16 v[64:67], v[172:175], v[188:191], v[64:67]
	s_add_u32 s52, s54, 0x180
	s_addc_u32 s53, s55, 0
	s_mov_b32 m0, s0
	s_barrier
	ds_read_b128 v[144:147], v201 offset:49152
	ds_read_b128 v[148:151], v201 offset:50176
	ds_read_b128 v[152:155], v202 offset:49152
	ds_read_b128 v[156:159], v202 offset:50176
	ds_read_b128 v[160:163], v203 offset:49152
	ds_read_b128 v[164:167], v203 offset:50176
	ds_read_b128 v[168:171], v204 offset:49152
	ds_read_b128 v[172:175], v204 offset:50176
	s_nop 0
	v_lshl_add_u64 v[192:193], s[52:53], 0, v[196:197]
	global_load_lds_dwordx4 v[192:193], off
	v_lshl_add_u64 v[192:193], s[52:53], 0, v[198:199]
	s_mov_b32 m0, s1
	s_nop 0
	global_load_lds_dwordx4 v[192:193], off
	s_barrier
; #define LDA(dst, b, h) for (int m = 0; m < 4; ++m) for (int k = 0; k < 2; ++k) \
;     dst[m][k] = *reinterpret_cast<const bf16x8*>((char*)SA(b, h) + lds_byte(wr * 64 + m * 16 + fr, k * 32 + fq * 8))
; #define LDB(dst, b, h) for (int n = 0; n < 2; ++n) for (int k = 0; k < 2; ++k) \
;     dst[n][k] = *reinterpret_cast<const bf16x8*>((char*)SB(b, h) + lds_byte(wc * 32 + n * 16 + fr, k * 32 + fq * 8))
; #define WAIT_V(n) asm volatile("s_waitcnt vmcnt(" #n ")" ::: "memory")
; #define WAIT_L(n) asm volatile("s_waitcnt lgkmcnt(" #n ")" ::: "memory")
; #define BAR __builtin_amdgcn_s_barrier()
; #define SCHED __builtin_amdgcn_sched_barrier(0)
; template <class Epi>
; DEVI void gemm_phase(const Params& p, const u16* __restrict__ A, const u16* __restrict__ Bt, const int M, const int N, const int K, const int Msplit, const Epi& epi) {
;     ...
;       BAR; WAIT_L(0); MMA(1, 0, At, B0); BAR; SCHED;
;       STAGE(SB(1, 1), Bt, bcol + HALF, t + 3);
;       WAIT_V(6); BAR; MMA(1, 1, At, B1); BAR;
;     }
;     { LDB(B0, 0, 0); LDA(At, 0, 0); STAGE(SA(1, 1), A, brow + HALF, nt - 1);
;       BAR; WAIT_L(0); MMA(0, 0, At, B0); BAR;
;       LDB(B1, 0, 1); BAR; WAIT_L(0); MMA(0, 1, At, B1); BAR;
	s_waitcnt lgkmcnt(0)
	s_waitcnt lgkmcnt(0)
	v_mfma_f32_16x16x32_bf16 v[60:63], v[144:147], v[128:131], v[60:63]
	v_mfma_f32_16x16x32_bf16 v[56:59], v[144:147], v[136:139], v[56:59]
	v_mfma_f32_16x16x32_bf16 v[52:55], v[152:155], v[128:131], v[52:55]
	v_mfma_f32_16x16x32_bf16 v[48:51], v[152:155], v[136:139], v[48:51]
	v_mfma_f32_16x16x32_bf16 v[44:47], v[160:163], v[128:131], v[44:47]
	v_mfma_f32_16x16x32_bf16 v[40:43], v[160:163], v[136:139], v[40:43]
	v_mfma_f32_16x16x32_bf16 v[36:39], v[168:171], v[128:131], v[36:39]
	v_mfma_f32_16x16x32_bf16 v[32:35], v[168:171], v[136:139], v[32:35]
	v_mfma_f32_16x16x32_bf16 v[60:63], v[148:151], v[132:135], v[60:63]
	v_mfma_f32_16x16x32_bf16 v[56:59], v[148:151], v[140:143], v[56:59]
	v_mfma_f32_16x16x32_bf16 v[52:55], v[156:159], v[132:135], v[52:55]
	v_mfma_f32_16x16x32_bf16 v[48:51], v[156:159], v[140:143], v[48:51]
	v_mfma_f32_16x16x32_bf16 v[44:47], v[164:167], v[132:135], v[44:47]
	v_mfma_f32_16x16x32_bf16 v[40:43], v[164:167], v[140:143], v[40:43]
	v_mfma_f32_16x16x32_bf16 v[36:39], v[172:175], v[132:135], v[36:39]
	v_mfma_f32_16x16x32_bf16 v[32:35], v[172:175], v[140:143], v[32:35]
	s_barrier
	s_add_u32 s54, s58, 0x180
	s_addc_u32 s55, s59, 0
	s_add_i32 s52, s88, 0x1c000
	s_mov_b32 m0, s52
	v_lshl_add_u64 v[128:129], s[54:55], 0, v[196:197]
	s_add_i32 s44, s88, 0x1e000
	global_load_lds_dwordx4 v[128:129], off
	v_lshl_add_u64 v[128:129], s[54:55], 0, v[198:199]
	s_mov_b32 m0, s44
	s_nop 0
	global_load_lds_dwordx4 v[128:129], off
	s_waitcnt vmcnt(6)
	s_barrier
	v_mfma_f32_16x16x32_bf16 v[28:31], v[144:147], v[176:179], v[28:31]
	v_mfma_f32_16x16x32_bf16 v[24:27], v[144:147], v[184:187], v[24:27]
	v_mfma_f32_16x16x32_bf16 v[20:23], v[152:155], v[176:179], v[20:23]
	v_mfma_f32_16x16x32_bf16 v[16:19], v[152:155], v[184:187], v[16:19]
	v_mfma_f32_16x16x32_bf16 v[12:15], v[160:163], v[176:179], v[12:15]
	v_mfma_f32_16x16x32_bf16 v[8:11], v[160:163], v[184:187], v[8:11]
	v_mfma_f32_16x16x32_bf16 v[4:7], v[168:171], v[176:179], v[4:7]
	v_mfma_f32_16x16x32_bf16 v[0:3], v[168:171], v[184:187], v[0:3]
	v_mfma_f32_16x16x32_bf16 v[28:31], v[148:151], v[180:183], v[28:31]
	v_mfma_f32_16x16x32_bf16 v[24:27], v[148:151], v[188:191], v[24:27]
	v_mfma_f32_16x16x32_bf16 v[20:23], v[156:159], v[180:183], v[20:23]
	v_mfma_f32_16x16x32_bf16 v[16:19], v[156:159], v[188:191], v[16:19]
	v_mfma_f32_16x16x32_bf16 v[12:15], v[164:167], v[180:183], v[12:15]
	v_mfma_f32_16x16x32_bf16 v[8:11], v[164:167], v[188:191], v[8:11]
	v_mfma_f32_16x16x32_bf16 v[4:7], v[172:175], v[180:183], v[4:7]
	v_mfma_f32_16x16x32_bf16 v[0:3], v[172:175], v[188:191], v[0:3]
	s_add_u32 s14, s14, 0x100
	s_addc_u32 s15, s15, 0
	s_add_i32 s42, s42, 2
	s_cmp_lt_u32 s42, 12
	s_barrier
	s_cbranch_scc1 .LBB0_1104
	s_add_u32 s14, s17, 0x780
	s_addc_u32 s15, s18, 0
	s_mov_b32 m0, s47
	ds_read_b128 v[156:159], v200
	ds_read_b128 v[160:163], v200 offset:1024
	ds_read_b128 v[164:167], v200 offset:2048
	ds_read_b128 v[168:171], v200 offset:3072
	ds_read_b128 v[128:131], v201
	ds_read_b128 v[132:135], v201 offset:1024
	ds_read_b128 v[136:139], v202
	ds_read_b128 v[140:143], v202 offset:1024
	ds_read_b128 v[144:147], v203
	ds_read_b128 v[148:151], v203 offset:1024
	ds_read_b128 v[152:155], v204
	ds_read_b128 v[172:175], v204 offset:1024
	s_nop 0
	v_lshl_add_u64 v[176:177], s[14:15], 0, v[196:197]
	global_load_lds_dwordx4 v[176:177], off
	v_lshl_add_u64 v[176:177], s[14:15], 0, v[198:199]
	s_mov_b32 m0, s46
	s_nop 0
	global_load_lds_dwordx4 v[176:177], off
	s_barrier
	s_waitcnt lgkmcnt(0)
	s_waitcnt lgkmcnt(0)
	v_mfma_f32_16x16x32_bf16 v[124:127], v[128:131], v[156:159], v[124:127]
	v_mfma_f32_16x16x32_bf16 v[120:123], v[128:131], v[164:167], v[120:123]
	v_mfma_f32_16x16x32_bf16 v[116:119], v[136:139], v[156:159], v[116:119]
	v_mfma_f32_16x16x32_bf16 v[112:115], v[136:139], v[164:167], v[112:115]
	v_mfma_f32_16x16x32_bf16 v[108:111], v[144:147], v[156:159], v[108:111]
	v_mfma_f32_16x16x32_bf16 v[104:107], v[144:147], v[164:167], v[104:107]
	v_mfma_f32_16x16x32_bf16 v[100:103], v[152:155], v[156:159], v[100:103]
	v_mfma_f32_16x16x32_bf16 v[96:99], v[152:155], v[164:167], v[96:99]
	v_mfma_f32_16x16x32_bf16 v[124:127], v[132:135], v[160:163], v[124:127]
	v_mfma_f32_16x16x32_bf16 v[176:179], v[132:135], v[168:171], v[120:123]
	v_mfma_f32_16x16x32_bf16 v[116:119], v[140:143], v[160:163], v[116:119]
	v_mfma_f32_16x16x32_bf16 v[180:183], v[140:143], v[168:171], v[112:115]
	v_mfma_f32_16x16x32_bf16 v[108:111], v[148:151], v[160:163], v[108:111]
	v_mfma_f32_16x16x32_bf16 v[184:187], v[148:151], v[168:171], v[104:107]
	v_mfma_f32_16x16x32_bf16 v[100:103], v[172:175], v[160:163], v[100:103]
	v_mfma_f32_16x16x32_bf16 v[188:191], v[172:175], v[168:171], v[96:99]
	s_barrier
	s_nop 0
	ds_read_b128 v[96:99], v205
	ds_read_b128 v[104:107], v205 offset:1024
	ds_read_b128 v[112:115], v205 offset:2048
	ds_read_b128 v[120:123], v205 offset:3072
	s_barrier
	s_waitcnt lgkmcnt(0)
	s_waitcnt lgkmcnt(0)
	v_mfma_f32_16x16x32_bf16 v[92:95], v[128:131], v[96:99], v[92:95]
	v_mfma_f32_16x16x32_bf16 v[88:91], v[128:131], v[112:115], v[88:91]
	v_mfma_f32_16x16x32_bf16 v[84:87], v[136:139], v[96:99], v[84:87]
	v_mfma_f32_16x16x32_bf16 v[80:83], v[136:139], v[112:115], v[80:83]
	v_mfma_f32_16x16x32_bf16 v[76:79], v[144:147], v[96:99], v[76:79]
	v_mfma_f32_16x16x32_bf16 v[72:75], v[144:147], v[112:115], v[72:75]
	v_mfma_f32_16x16x32_bf16 v[68:71], v[152:155], v[96:99], v[68:71]
	v_mfma_f32_16x16x32_bf16 v[64:67], v[152:155], v[112:115], v[64:67]
	v_mfma_f32_16x16x32_bf16 v[92:95], v[132:135], v[104:107], v[92:95]
	v_mfma_f32_16x16x32_bf16 v[128:131], v[132:135], v[120:123], v[88:91]
	v_mfma_f32_16x16x32_bf16 v[84:87], v[140:143], v[104:107], v[84:87]
	v_mfma_f32_16x16x32_bf16 v[132:135], v[140:143], v[120:123], v[80:83]
	v_mfma_f32_16x16x32_bf16 v[76:79], v[148:151], v[104:107], v[76:79]
	v_mfma_f32_16x16x32_bf16 v[136:139], v[148:151], v[120:123], v[72:75]
	v_mfma_f32_16x16x32_bf16 v[68:71], v[172:175], v[104:107], v[68:71]
	v_mfma_f32_16x16x32_bf16 v[140:143], v[172:175], v[120:123], v[64:67]
	s_barrier
; #define LDA(dst, b, h) for (int m = 0; m < 4; ++m) for (int k = 0; k < 2; ++k) \
;     dst[m][k] = *reinterpret_cast<const bf16x8*>((char*)SA(b, h) + lds_byte(wr * 64 + m * 16 + fr, k * 32 + fq * 8))
; #define LDB(dst, b, h) for (int n = 0; n < 2; ++n) for (int k = 0; k < 2; ++k) \
;     dst[n][k] = *reinterpret_cast<const bf16x8*>((char*)SB(b, h) + lds_byte(wc * 32 + n * 16 + fr, k * 32 + fq * 8))
; #define WAIT_V(n) asm volatile("s_waitcnt vmcnt(" #n ")" ::: "memory")
; #define WAIT_L(n) asm volatile("s_waitcnt lgkmcnt(" #n ")" ::: "memory")
; #define BAR __builtin_amdgcn_s_barrier()
; #define PRO_K0(brow_, bcol_) do { STAGE(SB(0, 0), Bt, bcol_, 0); STAGE(SA(0, 0), A, brow_, 0); STAGE(SB(0, 1), Bt, (bcol_) + HALF, 0); STAGE(SA(0, 1), A, (brow_) + HALF, 0); } while (0)
; template <class Epi>
; DEVI void gemm_phase(const Params& p, const u16* __restrict__ A, const u16* __restrict__ Bt, const int M, const int N, const int K, const int Msplit, const Epi& epi) {
;     ...
;       LDA(At, 0, 1); WAIT_V(4); BAR; WAIT_L(0); MMA(1, 0, At, B0); MMA(1, 1, At, B1); BAR; }
;     { LDB(B0, 1, 0); LDA(At, 1, 0); WAIT_V(2); BAR;
;       if (have2) { const u16* Asv = A; const u16* Bsv = Bt; A = An; Bt = Bn; PRO_K0(pm * BM, pn * BM); A = Asv; Bt = Bsv; }
;       WAIT_L(0); MMA(0, 0, At, B0); BAR;
;       LDB(B1, 1, 1); if (have2) { WAIT_V(8); } else { WAIT_V(0); } BAR; WAIT_L(0); MMA(0, 1, At, B1); BAR;
	s_nop 0
	ds_read_b128 v[64:67], v201 offset:16384
	ds_read_b128 v[72:75], v201 offset:17408
	ds_read_b128 v[80:83], v202 offset:16384
	ds_read_b128 v[88:91], v202 offset:17408
	ds_read_b128 v[172:175], v203 offset:16384
	ds_read_b128 v[192:195], v203 offset:17408
	ds_read_b128 v[208:211], v204 offset:16384
	ds_read_b128 v[214:217], v204 offset:17408
	s_waitcnt vmcnt(4)
	s_barrier
	s_waitcnt lgkmcnt(0)
	s_waitcnt lgkmcnt(0)
	v_mfma_f32_16x16x32_bf16 v[60:63], v[64:67], v[156:159], v[60:63]
	v_mfma_f32_16x16x32_bf16 v[56:59], v[64:67], v[164:167], v[56:59]
	v_mfma_f32_16x16x32_bf16 v[52:55], v[80:83], v[156:159], v[52:55]
	v_mfma_f32_16x16x32_bf16 v[48:51], v[80:83], v[164:167], v[48:51]
	v_mfma_f32_16x16x32_bf16 v[44:47], v[172:175], v[156:159], v[44:47]
	v_mfma_f32_16x16x32_bf16 v[40:43], v[172:175], v[164:167], v[40:43]
	v_mfma_f32_16x16x32_bf16 v[36:39], v[208:211], v[156:159], v[36:39]
	v_mfma_f32_16x16x32_bf16 v[32:35], v[208:211], v[164:167], v[32:35]
	v_mfma_f32_16x16x32_bf16 v[60:63], v[72:75], v[160:163], v[60:63]
	v_mfma_f32_16x16x32_bf16 v[144:147], v[72:75], v[168:171], v[56:59]
	v_mfma_f32_16x16x32_bf16 v[52:55], v[88:91], v[160:163], v[52:55]
	v_mfma_f32_16x16x32_bf16 v[148:151], v[88:91], v[168:171], v[48:51]
	v_mfma_f32_16x16x32_bf16 v[44:47], v[192:195], v[160:163], v[44:47]
	v_mfma_f32_16x16x32_bf16 v[152:155], v[192:195], v[168:171], v[40:43]
	v_mfma_f32_16x16x32_bf16 v[36:39], v[214:217], v[160:163], v[36:39]
	v_mfma_f32_16x16x32_bf16 v[156:159], v[214:217], v[168:171], v[32:35]
	v_mfma_f32_16x16x32_bf16 v[28:31], v[64:67], v[96:99], v[28:31]
	v_mfma_f32_16x16x32_bf16 v[24:27], v[64:67], v[112:115], v[24:27]
	v_mfma_f32_16x16x32_bf16 v[20:23], v[80:83], v[96:99], v[20:23]
	v_mfma_f32_16x16x32_bf16 v[16:19], v[80:83], v[112:115], v[16:19]
	v_mfma_f32_16x16x32_bf16 v[12:15], v[172:175], v[96:99], v[12:15]
	v_mfma_f32_16x16x32_bf16 v[8:11], v[172:175], v[112:115], v[8:11]
	v_mfma_f32_16x16x32_bf16 v[4:7], v[208:211], v[96:99], v[4:7]
	v_mfma_f32_16x16x32_bf16 v[0:3], v[208:211], v[112:115], v[0:3]
	v_mfma_f32_16x16x32_bf16 v[28:31], v[72:75], v[104:107], v[28:31]
	v_mfma_f32_16x16x32_bf16 v[160:163], v[72:75], v[120:123], v[24:27]
	v_mfma_f32_16x16x32_bf16 v[20:23], v[88:91], v[104:107], v[20:23]
	v_mfma_f32_16x16x32_bf16 v[164:167], v[88:91], v[120:123], v[16:19]
	v_mfma_f32_16x16x32_bf16 v[12:15], v[192:195], v[104:107], v[12:15]
	v_mfma_f32_16x16x32_bf16 v[168:171], v[192:195], v[120:123], v[8:11]
	v_mfma_f32_16x16x32_bf16 v[4:7], v[214:217], v[104:107], v[4:7]
	v_mfma_f32_16x16x32_bf16 v[172:175], v[214:217], v[120:123], v[0:3]
	s_barrier
	s_nop 0
	ds_read_b128 v[0:3], v206
	ds_read_b128 v[8:11], v206 offset:1024
	ds_read_b128 v[16:19], v206 offset:2048
	ds_read_b128 v[24:27], v206 offset:3072
	ds_read_b128 v[80:83], v201 offset:32768
	ds_read_b128 v[192:195], v201 offset:33792
	ds_read_b128 v[64:67], v202 offset:32768
	ds_read_b128 v[72:75], v202 offset:33792
	ds_read_b128 v[48:51], v203 offset:32768
	ds_read_b128 v[56:59], v203 offset:33792
	ds_read_b128 v[32:35], v204 offset:32768
	ds_read_b128 v[40:43], v204 offset:33792
	s_waitcnt vmcnt(2)
	v_cndmask_b32_e64 v88, 0, 1, s[12:13]
	v_cmp_ne_u32_e64 s[14:15], 1, v88
	s_andn2_b64 vcc, exec, s[12:13]
	s_barrier
	s_cbranch_vccnz .LBB0_1107
	s_lshl_b32 s12, s57, 8
	s_ashr_i32 s13, s12, 31
	s_lshl_b64 s[18:19], s[12:13], 11
	s_add_u32 s18, s2, s18
	s_addc_u32 s19, s76, s19
	s_mov_b32 m0, s45
	s_nop 0
	v_lshl_add_u64 v[88:89], s[18:19], 0, v[196:197]
	global_load_lds_dwordx4 v[88:89], off
	v_lshl_add_u64 v[88:89], s[18:19], 0, v[198:199]
	s_lshl_b32 s18, s62, 8
	s_ashr_i32 s19, s18, 31
	s_lshl_b64 s[20:21], s[18:19], 11
	s_add_u32 s20, s68, s20
	s_addc_u32 s21, s69, s21
	s_bitset1_b32 s12, 7
	s_ashr_i32 s13, s12, 31
	s_mov_b32 m0, s49
	s_lshl_b64 s[12:13], s[12:13], 11
	global_load_lds_dwordx4 v[88:89], off
	s_mov_b32 m0, s88
	v_lshl_add_u64 v[88:89], s[20:21], 0, v[196:197]
	s_add_u32 s12, s2, s12
	global_load_lds_dwordx4 v[88:89], off
	v_lshl_add_u64 v[88:89], s[20:21], 0, v[198:199]
	s_mov_b32 m0, s89
	s_addc_u32 s13, s76, s13
	global_load_lds_dwordx4 v[88:89], off
	s_mov_b32 m0, s38
	v_lshl_add_u64 v[88:89], s[12:13], 0, v[196:197]
	global_load_lds_dwordx4 v[88:89], off
	v_lshl_add_u64 v[88:89], s[12:13], 0, v[198:199]
	s_or_b32 s12, s18, 0x80
	s_ashr_i32 s13, s12, 31
	s_lshl_b64 s[12:13], s[12:13], 11
	s_add_u32 s12, s68, s12
	s_mov_b32 m0, s39
	s_addc_u32 s13, s69, s13
	global_load_lds_dwordx4 v[88:89], off
	s_mov_b32 m0, s90
	v_lshl_add_u64 v[88:89], s[12:13], 0, v[196:197]
	global_load_lds_dwordx4 v[88:89], off
	v_lshl_add_u64 v[88:89], s[12:13], 0, v[198:199]
	s_mov_b32 m0, s77
	s_nop 0
	global_load_lds_dwordx4 v[88:89], off
.LBB0_1107:
	s_waitcnt lgkmcnt(0)
	s_waitcnt lgkmcnt(0)
	v_mfma_f32_16x16x32_bf16 v[88:91], v[80:83], v[0:3], v[124:127]
	v_mfma_f32_16x16x32_bf16 v[120:123], v[192:195], v[8:11], v[88:91]
	v_mfma_f32_16x16x32_bf16 v[88:91], v[80:83], v[16:19], v[176:179]
	v_mfma_f32_16x16x32_bf16 v[124:127], v[192:195], v[24:27], v[88:91]
	v_mfma_f32_16x16x32_bf16 v[88:91], v[64:67], v[0:3], v[116:119]
	v_mfma_f32_16x16x32_bf16 v[112:115], v[72:75], v[8:11], v[88:91]
	v_mfma_f32_16x16x32_bf16 v[88:91], v[64:67], v[16:19], v[180:183]
	v_mfma_f32_16x16x32_bf16 v[116:119], v[72:75], v[24:27], v[88:91]
	v_mfma_f32_16x16x32_bf16 v[88:91], v[48:51], v[0:3], v[108:111]
	v_mfma_f32_16x16x32_bf16 v[104:107], v[56:59], v[8:11], v[88:91]
	v_mfma_f32_16x16x32_bf16 v[88:91], v[48:51], v[16:19], v[184:187]
	v_mfma_f32_16x16x32_bf16 v[108:111], v[56:59], v[24:27], v[88:91]
	v_mfma_f32_16x16x32_bf16 v[88:91], v[32:35], v[0:3], v[100:103]
	v_mfma_f32_16x16x32_bf16 v[96:99], v[40:43], v[8:11], v[88:91]
	v_mfma_f32_16x16x32_bf16 v[88:91], v[32:35], v[16:19], v[188:191]
	v_mfma_f32_16x16x32_bf16 v[100:103], v[40:43], v[24:27], v[88:91]
	s_barrier
	ds_read_b128 v[176:179], v207
	ds_read_b128 v[180:183], v207 offset:1024
	ds_read_b128 v[184:187], v207 offset:2048
	ds_read_b128 v[188:191], v207 offset:3072
	s_mov_b64 s[12:13], -1
	s_and_b64 vcc, exec, s[10:11]
	s_cbranch_vccz .LBB0_1109
	s_waitcnt vmcnt(0)
	s_mov_b64 s[12:13], 0

; #define LDA(dst, b, h) for (int m = 0; m < 4; ++m) for (int k = 0; k < 2; ++k) \
;     dst[m][k] = *reinterpret_cast<const bf16x8*>((char*)SA(b, h) + lds_byte(wr * 64 + m * 16 + fr, k * 32 + fq * 8))
; #define LDB(dst, b, h) for (int n = 0; n < 2; ++n) for (int k = 0; k < 2; ++k) \
;     dst[n][k] = *reinterpret_cast<const bf16x8*>((char*)SB(b, h) + lds_byte(wc * 32 + n * 16 + fr, k * 32 + fq * 8))
; #define WAIT_V(n) asm volatile("s_waitcnt vmcnt(" #n ")" ::: "memory")
; #define WAIT_L(n) asm volatile("s_waitcnt lgkmcnt(" #n ")" ::: "memory")
; #define BAR __builtin_amdgcn_s_barrier()
; template <class Epi>
; DEVI void gemm_phase(const Params& p, const u16* __restrict__ A, const u16* __restrict__ Bt, const int M, const int N, const int K, const int Msplit, const Epi& epi) {
;     ...
;       LDB(B1, 1, 1); if (have2) { WAIT_V(8); } else { WAIT_V(0); } BAR; WAIT_L(0); MMA(0, 1, At, B1); BAR;
;       LDA(At, 1, 1); BAR; WAIT_L(0); MMA(1, 0, At, B0); MMA(1, 1, At, B1); BAR; }
;     if (wr == 0) BAR;
.LBB0_1111:
	s_barrier
	s_waitcnt lgkmcnt(0)
	s_waitcnt lgkmcnt(0)
	v_mfma_f32_16x16x32_bf16 v[88:91], v[80:83], v[176:179], v[92:95]
	v_mfma_f32_16x16x32_bf16 v[80:83], v[80:83], v[184:187], v[128:131]
	v_mfma_f32_16x16x32_bf16 v[92:95], v[192:195], v[188:191], v[80:83]
	v_mfma_f32_16x16x32_bf16 v[80:83], v[64:67], v[176:179], v[84:87]
	v_mfma_f32_16x16x32_bf16 v[64:67], v[64:67], v[184:187], v[132:135]
	v_mfma_f32_16x16x32_bf16 v[84:87], v[72:75], v[188:191], v[64:67]
	v_mfma_f32_16x16x32_bf16 v[64:67], v[48:51], v[176:179], v[76:79]
	v_mfma_f32_16x16x32_bf16 v[48:51], v[48:51], v[184:187], v[136:139]
	v_mfma_f32_16x16x32_bf16 v[76:79], v[56:59], v[188:191], v[48:51]
	v_mfma_f32_16x16x32_bf16 v[48:51], v[32:35], v[176:179], v[68:71]
	v_mfma_f32_16x16x32_bf16 v[32:35], v[32:35], v[184:187], v[140:143]
	v_mfma_f32_16x16x32_bf16 v[88:91], v[192:195], v[180:183], v[88:91]
	v_mfma_f32_16x16x32_bf16 v[80:83], v[72:75], v[180:183], v[80:83]
	v_mfma_f32_16x16x32_bf16 v[72:75], v[56:59], v[180:183], v[64:67]
	v_mfma_f32_16x16x32_bf16 v[64:67], v[40:43], v[180:183], v[48:51]
	v_mfma_f32_16x16x32_bf16 v[68:71], v[40:43], v[188:191], v[32:35]
	s_barrier
	ds_read_b128 v[128:131], v201 offset:49152
	ds_read_b128 v[132:135], v201 offset:50176
	ds_read_b128 v[136:139], v202 offset:49152
	ds_read_b128 v[140:143], v202 offset:50176
	ds_read_b128 v[192:195], v203 offset:49152
	ds_read_b128 v[208:211], v203 offset:50176
	ds_read_b128 v[214:217], v204 offset:49152
	ds_read_b128 v[220:223], v204 offset:50176
	s_barrier
	s_waitcnt lgkmcnt(0)
	s_waitcnt lgkmcnt(0)
	v_mfma_f32_16x16x32_bf16 v[32:35], v[128:131], v[0:3], v[60:63]
	v_mfma_f32_16x16x32_bf16 v[56:59], v[132:135], v[8:11], v[32:35]
	v_mfma_f32_16x16x32_bf16 v[32:35], v[128:131], v[16:19], v[144:147]
	v_mfma_f32_16x16x32_bf16 v[60:63], v[132:135], v[24:27], v[32:35]
	v_mfma_f32_16x16x32_bf16 v[32:35], v[136:139], v[0:3], v[52:55]
	v_mfma_f32_16x16x32_bf16 v[48:51], v[140:143], v[8:11], v[32:35]
	v_mfma_f32_16x16x32_bf16 v[32:35], v[136:139], v[16:19], v[148:151]
	v_mfma_f32_16x16x32_bf16 v[52:55], v[140:143], v[24:27], v[32:35]
	v_mfma_f32_16x16x32_bf16 v[32:35], v[192:195], v[0:3], v[44:47]
	v_mfma_f32_16x16x32_bf16 v[40:43], v[208:211], v[8:11], v[32:35]
	v_mfma_f32_16x16x32_bf16 v[32:35], v[192:195], v[16:19], v[152:155]
	v_mfma_f32_16x16x32_bf16 v[0:3], v[214:217], v[0:3], v[36:39]
	v_mfma_f32_16x16x32_bf16 v[44:47], v[208:211], v[24:27], v[32:35]
	v_mfma_f32_16x16x32_bf16 v[32:35], v[220:223], v[8:11], v[0:3]
	v_mfma_f32_16x16x32_bf16 v[0:3], v[214:217], v[16:19], v[156:159]
	v_mfma_f32_16x16x32_bf16 v[36:39], v[220:223], v[24:27], v[0:3]
	v_mfma_f32_16x16x32_bf16 v[0:3], v[128:131], v[176:179], v[28:31]
	v_mfma_f32_16x16x32_bf16 v[24:27], v[132:135], v[180:183], v[0:3]
	v_mfma_f32_16x16x32_bf16 v[0:3], v[128:131], v[184:187], v[160:163]
	v_mfma_f32_16x16x32_bf16 v[28:31], v[132:135], v[188:191], v[0:3]
	v_mfma_f32_16x16x32_bf16 v[0:3], v[136:139], v[176:179], v[20:23]
	v_mfma_f32_16x16x32_bf16 v[16:19], v[140:143], v[180:183], v[0:3]
	v_mfma_f32_16x16x32_bf16 v[0:3], v[136:139], v[184:187], v[164:167]
	v_mfma_f32_16x16x32_bf16 v[20:23], v[140:143], v[188:191], v[0:3]
	v_mfma_f32_16x16x32_bf16 v[0:3], v[192:195], v[176:179], v[12:15]
	v_mfma_f32_16x16x32_bf16 v[8:11], v[208:211], v[180:183], v[0:3]
	v_mfma_f32_16x16x32_bf16 v[0:3], v[192:195], v[184:187], v[168:171]
	v_mfma_f32_16x16x32_bf16 v[12:15], v[208:211], v[188:191], v[0:3]
	v_mfma_f32_16x16x32_bf16 v[0:3], v[214:217], v[176:179], v[4:7]
	v_mfma_f32_16x16x32_bf16 v[4:7], v[214:217], v[184:187], v[172:175]
	v_mfma_f32_16x16x32_bf16 v[0:3], v[220:223], v[180:183], v[0:3]
	v_mfma_f32_16x16x32_bf16 v[4:7], v[220:223], v[188:191], v[4:7]
	s_barrier
	s_and_saveexec_b64 s[12:13], s[8:9]
	s_cbranch_execz .LBB0_1113
	s_barrier

; #define LDA(dst, b, h) for (int m = 0; m < 4; ++m) for (int k = 0; k < 2; ++k) \
;     dst[m][k] = *reinterpret_cast<const bf16x8*>((char*)SA(b, h) + lds_byte(wr * 64 + m * 16 + fr, k * 32 + fq * 8))
; #define LDB(dst, b, h) for (int n = 0; n < 2; ++n) for (int k = 0; k < 2; ++k) \
;     dst[n][k] = *reinterpret_cast<const bf16x8*>((char*)SB(b, h) + lds_byte(wc * 32 + n * 16 + fr, k * 32 + fq * 8))
; #define WAIT_L(n) asm volatile("s_waitcnt lgkmcnt(" #n ")" ::: "memory")
; #define BAR __builtin_amdgcn_s_barrier()
; #define SCHED __builtin_amdgcn_sched_barrier(0)
; template <class Epi>
; DEVI void gemm_phase(const Params& p, const u16* __restrict__ A, const u16* __restrict__ Bt, const int M, const int N, const int K, const int Msplit, const Epi& epi) {
;     ...
;     for (int t = 0; t < nt - 2; t += 2) {
;       LDB(B0, 0, 0); SCHED; LDA(At, 0, 0); STAGE(SA(1, 1), A, brow + HALF, t + 1);
;       WAIT_L(8); BAR; WAIT_L(0); MMA(0, 0, At, B0); BAR; SCHED;
;       LDB(B1, 0, 1); STAGE(SB(0, 0), Bt, bcol, t + 2);
;       BAR; WAIT_L(0); MMA(0, 1, At, B1); BAR;
;       LDA(At, 0, 1); STAGE(SA(0, 0), A, brow, t + 2);
;       BAR; WAIT_L(0); MMA(1, 0, At, B0); BAR; SCHED;
.LBB0_1717:
	v_add_u32_e32 v148, v226, v232
	ds_read_b128 v[136:139], v148
	ds_read_b128 v[140:143], v148 offset:1024
	ds_read_b128 v[144:147], v148 offset:2048
	ds_read_b128 v[148:151], v148 offset:3072
	s_add_u32 s17, s20, s18
	s_addc_u32 s44, s21, s19
	s_add_u32 s38, s17, 0x80
	v_add_u32_e32 v202, v249, v245
	v_add_u32_e32 v203, v250, v246
	v_add_u32_e32 v204, v250, v247
	v_add_u32_e32 v205, v250, v248
	s_addc_u32 s39, s44, 0
	s_add_i32 s16, s78, 0
	ds_read_b128 v[152:155], v202
	ds_read_b128 v[156:159], v202 offset:1024
	ds_read_b128 v[160:163], v203
	ds_read_b128 v[164:167], v203 offset:1024
	ds_read_b128 v[168:171], v204
	ds_read_b128 v[172:175], v204 offset:1024
	ds_read_b128 v[176:179], v205
	ds_read_b128 v[180:183], v205 offset:1024
	s_add_i32 m0, s16, 0xc000
	v_lshl_add_u64 v[184:185], s[38:39], 0, v[208:209]
	global_load_lds_dwordx4 v[184:185], off
	v_lshl_add_u64 v[184:185], s[38:39], 0, v[210:211]
	s_add_i32 m0, s16, 0xe000
	s_nop 0
	global_load_lds_dwordx4 v[184:185], off
	s_waitcnt lgkmcnt(8)
	s_barrier
	s_waitcnt lgkmcnt(0)
	s_waitcnt lgkmcnt(0)
	v_mfma_f32_16x16x32_bf16 v[132:135], v[136:139], v[152:155], v[132:135]
	v_mfma_f32_16x16x32_bf16 v[128:131], v[144:147], v[152:155], v[128:131]
	v_mfma_f32_16x16x32_bf16 v[124:127], v[136:139], v[160:163], v[124:127]
	v_mfma_f32_16x16x32_bf16 v[120:123], v[144:147], v[160:163], v[120:123]
	v_mfma_f32_16x16x32_bf16 v[116:119], v[136:139], v[168:171], v[116:119]
	v_mfma_f32_16x16x32_bf16 v[112:115], v[144:147], v[168:171], v[112:115]
	v_mfma_f32_16x16x32_bf16 v[108:111], v[136:139], v[176:179], v[108:111]
	v_mfma_f32_16x16x32_bf16 v[104:107], v[144:147], v[176:179], v[104:107]
	v_mfma_f32_16x16x32_bf16 v[132:135], v[140:143], v[156:159], v[132:135]
	v_mfma_f32_16x16x32_bf16 v[128:131], v[148:151], v[156:159], v[128:131]
	v_mfma_f32_16x16x32_bf16 v[124:127], v[140:143], v[164:167], v[124:127]
	v_mfma_f32_16x16x32_bf16 v[120:123], v[148:151], v[164:167], v[120:123]
	v_mfma_f32_16x16x32_bf16 v[116:119], v[140:143], v[172:175], v[116:119]
	v_mfma_f32_16x16x32_bf16 v[112:115], v[148:151], v[172:175], v[112:115]
	v_mfma_f32_16x16x32_bf16 v[108:111], v[140:143], v[180:183], v[108:111]
	v_mfma_f32_16x16x32_bf16 v[104:107], v[148:151], v[180:183], v[104:107]
	s_barrier
	s_add_i32 s53, s53, 2
	s_add_u32 s45, s22, s18
	s_addc_u32 s46, s23, s19
	s_add_u32 s38, s45, 0x100
	v_add_u32_e32 v196, v227, v232
	s_addc_u32 s39, s46, 0
	ds_read_b128 v[184:187], v196
	ds_read_b128 v[188:191], v196 offset:1024
	ds_read_b128 v[192:195], v196 offset:2048
	ds_read_b128 v[196:199], v196 offset:3072
	s_add_i32 m0, s16, 0x10000
	v_lshl_add_u64 v[200:201], s[38:39], 0, v[208:209]
	global_load_lds_dwordx4 v[200:201], off
	v_lshl_add_u64 v[200:201], s[38:39], 0, v[210:211]
	s_add_i32 m0, s16, 0x12000
	s_nop 0
	global_load_lds_dwordx4 v[200:201], off
	s_barrier
	s_waitcnt lgkmcnt(0)
	s_waitcnt lgkmcnt(0)
	v_mfma_f32_16x16x32_bf16 v[100:103], v[184:187], v[152:155], v[100:103]
	v_mfma_f32_16x16x32_bf16 v[96:99], v[192:195], v[152:155], v[96:99]
	v_mfma_f32_16x16x32_bf16 v[92:95], v[184:187], v[160:163], v[92:95]
	v_mfma_f32_16x16x32_bf16 v[88:91], v[192:195], v[160:163], v[88:91]
	v_mfma_f32_16x16x32_bf16 v[84:87], v[184:187], v[168:171], v[84:87]
	v_mfma_f32_16x16x32_bf16 v[80:83], v[192:195], v[168:171], v[80:83]
	v_mfma_f32_16x16x32_bf16 v[76:79], v[184:187], v[176:179], v[76:79]
	v_mfma_f32_16x16x32_bf16 v[72:75], v[192:195], v[176:179], v[72:75]
	v_mfma_f32_16x16x32_bf16 v[100:103], v[188:191], v[156:159], v[100:103]
	v_mfma_f32_16x16x32_bf16 v[96:99], v[196:199], v[156:159], v[96:99]
	v_mfma_f32_16x16x32_bf16 v[92:95], v[188:191], v[164:167], v[92:95]
	v_mfma_f32_16x16x32_bf16 v[88:91], v[196:199], v[164:167], v[88:91]
	v_mfma_f32_16x16x32_bf16 v[84:87], v[188:191], v[172:175], v[84:87]
	v_mfma_f32_16x16x32_bf16 v[80:83], v[196:199], v[172:175], v[80:83]
	v_mfma_f32_16x16x32_bf16 v[76:79], v[188:191], v[180:183], v[76:79]
	v_mfma_f32_16x16x32_bf16 v[72:75], v[196:199], v[180:183], v[72:75]
	s_add_u32 s47, s11, s18
	s_addc_u32 s54, s25, s19
	s_add_u32 s38, s47, 0x100
	s_addc_u32 s39, s54, 0
	s_mov_b32 m0, s16
	s_barrier
	ds_read_b128 v[152:155], v202 offset:16384
	ds_read_b128 v[156:159], v202 offset:17408
	ds_read_b128 v[160:163], v203 offset:16384
	ds_read_b128 v[164:167], v203 offset:17408
	ds_read_b128 v[168:171], v204 offset:16384
	ds_read_b128 v[172:175], v204 offset:17408
	ds_read_b128 v[176:179], v205 offset:16384
	ds_read_b128 v[180:183], v205 offset:17408
	s_nop 0
	v_lshl_add_u64 v[200:201], s[38:39], 0, v[208:209]
	global_load_lds_dwordx4 v[200:201], off
	v_lshl_add_u64 v[200:201], s[38:39], 0, v[210:211]
	s_add_i32 m0, s16, 0x2000
	s_nop 0
	global_load_lds_dwordx4 v[200:201], off
	s_barrier
	s_waitcnt lgkmcnt(0)
	s_waitcnt lgkmcnt(0)
	v_mfma_f32_16x16x32_bf16 v[68:71], v[136:139], v[152:155], v[68:71]
	v_mfma_f32_16x16x32_bf16 v[64:67], v[144:147], v[152:155], v[64:67]
	v_mfma_f32_16x16x32_bf16 v[60:63], v[136:139], v[160:163], v[60:63]
	v_mfma_f32_16x16x32_bf16 v[56:59], v[144:147], v[160:163], v[56:59]
	v_mfma_f32_16x16x32_bf16 v[52:55], v[136:139], v[168:171], v[52:55]
	v_mfma_f32_16x16x32_bf16 v[48:51], v[144:147], v[168:171], v[48:51]
	v_mfma_f32_16x16x32_bf16 v[44:47], v[136:139], v[176:179], v[44:47]
	v_mfma_f32_16x16x32_bf16 v[40:43], v[144:147], v[176:179], v[40:43]
	v_mfma_f32_16x16x32_bf16 v[68:71], v[140:143], v[156:159], v[68:71]
	v_mfma_f32_16x16x32_bf16 v[64:67], v[148:151], v[156:159], v[64:67]
	v_mfma_f32_16x16x32_bf16 v[60:63], v[140:143], v[164:167], v[60:63]
	v_mfma_f32_16x16x32_bf16 v[56:59], v[148:151], v[164:167], v[56:59]
	v_mfma_f32_16x16x32_bf16 v[52:55], v[140:143], v[172:175], v[52:55]
	v_mfma_f32_16x16x32_bf16 v[48:51], v[148:151], v[172:175], v[48:51]
	v_mfma_f32_16x16x32_bf16 v[44:47], v[140:143], v[180:183], v[44:47]
	v_mfma_f32_16x16x32_bf16 v[40:43], v[148:151], v[180:183], v[40:43]
	s_barrier
; #define LDA(dst, b, h) for (int m = 0; m < 4; ++m) for (int k = 0; k < 2; ++k) \
;     dst[m][k] = *reinterpret_cast<const bf16x8*>((char*)SA(b, h) + lds_byte(wr * 64 + m * 16 + fr, k * 32 + fq * 8))
; #define LDB(dst, b, h) for (int n = 0; n < 2; ++n) for (int k = 0; k < 2; ++k) \
;     dst[n][k] = *reinterpret_cast<const bf16x8*>((char*)SB(b, h) + lds_byte(wc * 32 + n * 16 + fr, k * 32 + fq * 8))
; #define WAIT_V(n) asm volatile("s_waitcnt vmcnt(" #n ")" ::: "memory")
; #define WAIT_L(n) asm volatile("s_waitcnt lgkmcnt(" #n ")" ::: "memory")
; #define BAR __builtin_amdgcn_s_barrier()
; #define SCHED __builtin_amdgcn_sched_barrier(0)
; template <class Epi>
; DEVI void gemm_phase(const Params& p, const u16* __restrict__ A, const u16* __restrict__ Bt, const int M, const int N, const int K, const int Msplit, const Epi& epi) {
;     ...
;       STAGE(SB(0, 1), Bt, bcol + HALF, t + 2);
;       WAIT_V(6); BAR; MMA(1, 1, At, B1); BAR;
;       LDB(B0, 1, 0); SCHED; LDA(At, 1, 0); STAGE(SA(0, 1), A, brow + HALF, t + 2);
;       WAIT_L(8); BAR; WAIT_L(0); MMA(0, 0, At, B0); BAR; SCHED;
;       LDB(B1, 1, 1); STAGE(SB(1, 0), Bt, bcol, t + 3);
;       BAR; WAIT_L(0); MMA(0, 1, At, B1); BAR;
;       LDA(At, 1, 1); STAGE(SA(1, 0), A, brow, t + 3);
	s_add_u32 s55, s41, s18
	s_addc_u32 s56, s52, s19
	s_add_u32 s38, s55, 0x100
	s_addc_u32 s39, s56, 0
	s_add_i32 m0, s16, 0x14000
	v_lshl_add_u64 v[136:137], s[38:39], 0, v[208:209]
	global_load_lds_dwordx4 v[136:137], off
	v_lshl_add_u64 v[136:137], s[38:39], 0, v[210:211]
	s_add_i32 m0, s16, 0x16000
	s_nop 0
	global_load_lds_dwordx4 v[136:137], off
	s_waitcnt vmcnt(6)
	s_barrier
	v_mfma_f32_16x16x32_bf16 v[36:39], v[184:187], v[152:155], v[36:39]
	v_mfma_f32_16x16x32_bf16 v[32:35], v[192:195], v[152:155], v[32:35]
	v_mfma_f32_16x16x32_bf16 v[28:31], v[184:187], v[160:163], v[28:31]
	v_mfma_f32_16x16x32_bf16 v[24:27], v[192:195], v[160:163], v[24:27]
	v_mfma_f32_16x16x32_bf16 v[20:23], v[184:187], v[168:171], v[20:23]
	v_mfma_f32_16x16x32_bf16 v[16:19], v[192:195], v[168:171], v[16:19]
	v_mfma_f32_16x16x32_bf16 v[12:15], v[184:187], v[176:179], v[12:15]
	v_mfma_f32_16x16x32_bf16 v[8:11], v[192:195], v[176:179], v[8:11]
	v_mfma_f32_16x16x32_bf16 v[36:39], v[188:191], v[156:159], v[36:39]
	v_mfma_f32_16x16x32_bf16 v[32:35], v[196:199], v[156:159], v[32:35]
	v_mfma_f32_16x16x32_bf16 v[28:31], v[188:191], v[164:167], v[28:31]
	v_mfma_f32_16x16x32_bf16 v[24:27], v[196:199], v[164:167], v[24:27]
	v_mfma_f32_16x16x32_bf16 v[20:23], v[188:191], v[172:175], v[20:23]
	v_mfma_f32_16x16x32_bf16 v[16:19], v[196:199], v[172:175], v[16:19]
	v_mfma_f32_16x16x32_bf16 v[12:15], v[188:191], v[180:183], v[12:15]
	v_mfma_f32_16x16x32_bf16 v[8:11], v[196:199], v[180:183], v[8:11]
	v_add_u32_e32 v148, v228, v232
	s_barrier
	ds_read_b128 v[136:139], v148
	ds_read_b128 v[140:143], v148 offset:1024
	ds_read_b128 v[144:147], v148 offset:2048
	ds_read_b128 v[148:151], v148 offset:3072
	s_add_u32 s38, s17, 0x100
	s_addc_u32 s39, s44, 0
	ds_read_b128 v[152:155], v202 offset:32768
	ds_read_b128 v[156:159], v202 offset:33792
	ds_read_b128 v[160:163], v203 offset:32768
	ds_read_b128 v[164:167], v203 offset:33792
	ds_read_b128 v[168:171], v204 offset:32768
	ds_read_b128 v[172:175], v204 offset:33792
	ds_read_b128 v[176:179], v205 offset:32768
	ds_read_b128 v[180:183], v205 offset:33792
	s_add_i32 m0, s16, 0x4000
	v_lshl_add_u64 v[184:185], s[38:39], 0, v[208:209]
	global_load_lds_dwordx4 v[184:185], off
	v_lshl_add_u64 v[184:185], s[38:39], 0, v[210:211]
	s_add_i32 m0, s16, 0x6000
	s_nop 0
	global_load_lds_dwordx4 v[184:185], off
	s_waitcnt lgkmcnt(8)
	s_barrier
	s_waitcnt lgkmcnt(0)
	s_waitcnt lgkmcnt(0)
	v_mfma_f32_16x16x32_bf16 v[132:135], v[136:139], v[152:155], v[132:135]
	v_mfma_f32_16x16x32_bf16 v[128:131], v[144:147], v[152:155], v[128:131]
	v_mfma_f32_16x16x32_bf16 v[124:127], v[136:139], v[160:163], v[124:127]
	v_mfma_f32_16x16x32_bf16 v[120:123], v[144:147], v[160:163], v[120:123]
	v_mfma_f32_16x16x32_bf16 v[116:119], v[136:139], v[168:171], v[116:119]
	v_mfma_f32_16x16x32_bf16 v[112:115], v[144:147], v[168:171], v[112:115]
	v_mfma_f32_16x16x32_bf16 v[108:111], v[136:139], v[176:179], v[108:111]
	v_mfma_f32_16x16x32_bf16 v[104:107], v[144:147], v[176:179], v[104:107]
	v_mfma_f32_16x16x32_bf16 v[132:135], v[140:143], v[156:159], v[132:135]
	v_mfma_f32_16x16x32_bf16 v[128:131], v[148:151], v[156:159], v[128:131]
	v_mfma_f32_16x16x32_bf16 v[124:127], v[140:143], v[164:167], v[124:127]
	v_mfma_f32_16x16x32_bf16 v[120:123], v[148:151], v[164:167], v[120:123]
	v_mfma_f32_16x16x32_bf16 v[116:119], v[140:143], v[172:175], v[116:119]
	v_mfma_f32_16x16x32_bf16 v[112:115], v[148:151], v[172:175], v[112:115]
	v_mfma_f32_16x16x32_bf16 v[108:111], v[140:143], v[180:183], v[108:111]
	v_mfma_f32_16x16x32_bf16 v[104:107], v[148:151], v[180:183], v[104:107]
	s_barrier
	s_add_u32 s38, s45, 0x180
	v_add_u32_e32 v196, v229, v232
	s_addc_u32 s39, s46, 0
	ds_read_b128 v[184:187], v196
	ds_read_b128 v[188:191], v196 offset:1024
	ds_read_b128 v[192:195], v196 offset:2048
	ds_read_b128 v[196:199], v196 offset:3072
	s_add_i32 m0, s16, 0x18000
	v_lshl_add_u64 v[200:201], s[38:39], 0, v[208:209]
	global_load_lds_dwordx4 v[200:201], off
	v_lshl_add_u64 v[200:201], s[38:39], 0, v[210:211]
	s_add_i32 m0, s16, 0x1a000
	s_nop 0
	global_load_lds_dwordx4 v[200:201], off
	s_barrier
	s_waitcnt lgkmcnt(0)
	s_waitcnt lgkmcnt(0)
	v_mfma_f32_16x16x32_bf16 v[100:103], v[184:187], v[152:155], v[100:103]
	v_mfma_f32_16x16x32_bf16 v[96:99], v[192:195], v[152:155], v[96:99]
	v_mfma_f32_16x16x32_bf16 v[92:95], v[184:187], v[160:163], v[92:95]
	v_mfma_f32_16x16x32_bf16 v[88:91], v[192:195], v[160:163], v[88:91]
	v_mfma_f32_16x16x32_bf16 v[84:87], v[184:187], v[168:171], v[84:87]
	v_mfma_f32_16x16x32_bf16 v[80:83], v[192:195], v[168:171], v[80:83]
	v_mfma_f32_16x16x32_bf16 v[76:79], v[184:187], v[176:179], v[76:79]
	v_mfma_f32_16x16x32_bf16 v[72:75], v[192:195], v[176:179], v[72:75]
	v_mfma_f32_16x16x32_bf16 v[100:103], v[188:191], v[156:159], v[100:103]
	v_mfma_f32_16x16x32_bf16 v[96:99], v[196:199], v[156:159], v[96:99]
	v_mfma_f32_16x16x32_bf16 v[92:95], v[188:191], v[164:167], v[92:95]
	v_mfma_f32_16x16x32_bf16 v[88:91], v[196:199], v[164:167], v[88:91]
	v_mfma_f32_16x16x32_bf16 v[84:87], v[188:191], v[172:175], v[84:87]
	v_mfma_f32_16x16x32_bf16 v[80:83], v[196:199], v[172:175], v[80:83]
	v_mfma_f32_16x16x32_bf16 v[76:79], v[188:191], v[180:183], v[76:79]
	v_mfma_f32_16x16x32_bf16 v[72:75], v[196:199], v[180:183], v[72:75]
	s_add_u32 s38, s47, 0x180
	s_addc_u32 s39, s54, 0
	s_barrier
	ds_read_b128 v[152:155], v202 offset:49152
	ds_read_b128 v[156:159], v202 offset:50176
	ds_read_b128 v[160:163], v203 offset:49152
	ds_read_b128 v[164:167], v203 offset:50176
	ds_read_b128 v[168:171], v204 offset:49152
	ds_read_b128 v[172:175], v204 offset:50176
	ds_read_b128 v[176:179], v205 offset:49152
	ds_read_b128 v[180:183], v205 offset:50176
	s_add_i32 m0, s16, 0x8000
	v_lshl_add_u64 v[200:201], s[38:39], 0, v[208:209]
	global_load_lds_dwordx4 v[200:201], off
	v_lshl_add_u64 v[200:201], s[38:39], 0, v[210:211]
	s_add_i32 m0, s16, 0xa000
	s_nop 0
	global_load_lds_dwordx4 v[200:201], off
	s_barrier
; #define LDA(dst, b, h) for (int m = 0; m < 4; ++m) for (int k = 0; k < 2; ++k) \
;     dst[m][k] = *reinterpret_cast<const bf16x8*>((char*)SA(b, h) + lds_byte(wr * 64 + m * 16 + fr, k * 32 + fq * 8))
; #define LDB(dst, b, h) for (int n = 0; n < 2; ++n) for (int k = 0; k < 2; ++k) \
;     dst[n][k] = *reinterpret_cast<const bf16x8*>((char*)SB(b, h) + lds_byte(wc * 32 + n * 16 + fr, k * 32 + fq * 8))
; #define WAIT_V(n) asm volatile("s_waitcnt vmcnt(" #n ")" ::: "memory")
; #define WAIT_L(n) asm volatile("s_waitcnt lgkmcnt(" #n ")" ::: "memory")
; #define BAR __builtin_amdgcn_s_barrier()
; #define SCHED __builtin_amdgcn_sched_barrier(0)
; template <class Epi>
; DEVI void gemm_phase(const Params& p, const u16* __restrict__ A, const u16* __restrict__ Bt, const int M, const int N, const int K, const int Msplit, const Epi& epi) {
;     ...
;       BAR; WAIT_L(0); MMA(1, 0, At, B0); BAR; SCHED;
;       STAGE(SB(1, 1), Bt, bcol + HALF, t + 3);
;       WAIT_V(6); BAR; MMA(1, 1, At, B1); BAR;
;     }
;     { LDB(B0, 0, 0); LDA(At, 0, 0); STAGE(SA(1, 1), A, brow + HALF, nt - 1);
;       BAR; WAIT_L(0); MMA(0, 0, At, B0); BAR;
;       LDB(B1, 0, 1); BAR; WAIT_L(0); MMA(0, 1, At, B1); BAR;
	s_waitcnt lgkmcnt(0)
	s_waitcnt lgkmcnt(0)
	v_mfma_f32_16x16x32_bf16 v[68:71], v[136:139], v[152:155], v[68:71]
	v_mfma_f32_16x16x32_bf16 v[64:67], v[144:147], v[152:155], v[64:67]
	v_mfma_f32_16x16x32_bf16 v[60:63], v[136:139], v[160:163], v[60:63]
	v_mfma_f32_16x16x32_bf16 v[56:59], v[144:147], v[160:163], v[56:59]
	v_mfma_f32_16x16x32_bf16 v[52:55], v[136:139], v[168:171], v[52:55]
	v_mfma_f32_16x16x32_bf16 v[48:51], v[144:147], v[168:171], v[48:51]
	v_mfma_f32_16x16x32_bf16 v[44:47], v[136:139], v[176:179], v[44:47]
	v_mfma_f32_16x16x32_bf16 v[40:43], v[144:147], v[176:179], v[40:43]
	v_mfma_f32_16x16x32_bf16 v[68:71], v[140:143], v[156:159], v[68:71]
	v_mfma_f32_16x16x32_bf16 v[64:67], v[148:151], v[156:159], v[64:67]
	v_mfma_f32_16x16x32_bf16 v[60:63], v[140:143], v[164:167], v[60:63]
	v_mfma_f32_16x16x32_bf16 v[56:59], v[148:151], v[164:167], v[56:59]
	v_mfma_f32_16x16x32_bf16 v[52:55], v[140:143], v[172:175], v[52:55]
	v_mfma_f32_16x16x32_bf16 v[48:51], v[148:151], v[172:175], v[48:51]
	v_mfma_f32_16x16x32_bf16 v[44:47], v[140:143], v[180:183], v[44:47]
	v_mfma_f32_16x16x32_bf16 v[40:43], v[148:151], v[180:183], v[40:43]
	s_barrier
	s_add_u32 s38, s55, 0x180
	s_addc_u32 s39, s56, 0
	s_add_i32 m0, s16, 0x1c000
	v_lshl_add_u64 v[136:137], s[38:39], 0, v[208:209]
	global_load_lds_dwordx4 v[136:137], off
	v_lshl_add_u64 v[136:137], s[38:39], 0, v[210:211]
	s_add_i32 m0, s16, 0x1e000
	s_nop 0
	global_load_lds_dwordx4 v[136:137], off
	s_waitcnt vmcnt(6)
	s_barrier
	v_mfma_f32_16x16x32_bf16 v[36:39], v[184:187], v[152:155], v[36:39]
	v_mfma_f32_16x16x32_bf16 v[32:35], v[192:195], v[152:155], v[32:35]
	v_mfma_f32_16x16x32_bf16 v[28:31], v[184:187], v[160:163], v[28:31]
	v_mfma_f32_16x16x32_bf16 v[24:27], v[192:195], v[160:163], v[24:27]
	v_mfma_f32_16x16x32_bf16 v[20:23], v[184:187], v[168:171], v[20:23]
	v_mfma_f32_16x16x32_bf16 v[16:19], v[192:195], v[168:171], v[16:19]
	v_mfma_f32_16x16x32_bf16 v[12:15], v[184:187], v[176:179], v[12:15]
	v_mfma_f32_16x16x32_bf16 v[8:11], v[192:195], v[176:179], v[8:11]
	v_mfma_f32_16x16x32_bf16 v[36:39], v[188:191], v[156:159], v[36:39]
	v_mfma_f32_16x16x32_bf16 v[32:35], v[196:199], v[156:159], v[32:35]
	v_mfma_f32_16x16x32_bf16 v[28:31], v[188:191], v[164:167], v[28:31]
	v_mfma_f32_16x16x32_bf16 v[24:27], v[196:199], v[164:167], v[24:27]
	v_mfma_f32_16x16x32_bf16 v[20:23], v[188:191], v[172:175], v[20:23]
	v_mfma_f32_16x16x32_bf16 v[16:19], v[196:199], v[172:175], v[16:19]
	v_mfma_f32_16x16x32_bf16 v[12:15], v[188:191], v[180:183], v[12:15]
	v_mfma_f32_16x16x32_bf16 v[8:11], v[196:199], v[180:183], v[8:11]
	s_add_u32 s18, s18, 0x100
	s_addc_u32 s19, s19, 0
	s_cmp_ge_i32 s53, s15
	s_barrier
	s_cbranch_scc0 .LBB0_1717
.LBB0_1718:
	s_mov_b32 s15, s91
	s_xor_b64 s[20:21], s[12:13], -1
	s_lshl_b64 s[16:17], s[14:15], 7
	s_add_u32 s22, s68, s16
	s_addc_u32 s23, s69, s17
	s_add_u32 s18, s4, s16
	s_addc_u32 s19, s5, s17
	s_lshl_b64 s[16:17], s[36:37], 1
	s_add_u32 s11, s26, s16
	s_addc_u32 s15, s27, s17
	s_add_i32 s90, s40, -1
	s_lshl_b64 s[16:17], s[90:91], 7
	s_add_u32 s16, s11, s16
	v_add_u32_e32 v144, v226, v232
	v_add_u32_e32 v212, v249, v245
	v_add_u32_e32 v251, v250, v246
	v_add_u32_e32 v220, v250, v247
	v_add_u32_e32 v221, v250, v248
	s_addc_u32 s17, s15, s17
	s_add_i32 s11, s78, 0
	ds_read_b128 v[136:139], v144
	ds_read_b128 v[140:143], v144 offset:1024
	ds_read_b128 v[152:155], v144 offset:2048
	ds_read_b128 v[156:159], v144 offset:3072
	ds_read_b128 v[160:163], v212
	ds_read_b128 v[164:167], v212 offset:1024
	ds_read_b128 v[168:171], v251
	ds_read_b128 v[172:175], v251 offset:1024
	ds_read_b128 v[176:179], v220
	ds_read_b128 v[180:183], v220 offset:1024
	ds_read_b128 v[184:187], v221
	ds_read_b128 v[188:191], v221 offset:1024
	s_add_i32 m0, s11, 0xc000
	v_lshl_add_u64 v[144:145], s[16:17], 0, v[208:209]
	global_load_lds_dwordx4 v[144:145], off
	v_lshl_add_u64 v[144:145], s[16:17], 0, v[210:211]
	s_add_i32 m0, s11, 0xe000
	s_nop 0
	global_load_lds_dwordx4 v[144:145], off
	s_barrier
	s_waitcnt lgkmcnt(0)
	s_waitcnt lgkmcnt(0)
	v_mfma_f32_16x16x32_bf16 v[132:135], v[136:139], v[160:163], v[132:135]
	v_mfma_f32_16x16x32_bf16 v[128:131], v[152:155], v[160:163], v[128:131]
	v_mfma_f32_16x16x32_bf16 v[124:127], v[136:139], v[168:171], v[124:127]
	v_mfma_f32_16x16x32_bf16 v[120:123], v[152:155], v[168:171], v[120:123]
	v_mfma_f32_16x16x32_bf16 v[116:119], v[136:139], v[176:179], v[116:119]
	v_mfma_f32_16x16x32_bf16 v[112:115], v[152:155], v[176:179], v[112:115]
	v_mfma_f32_16x16x32_bf16 v[108:111], v[136:139], v[184:187], v[108:111]
	v_mfma_f32_16x16x32_bf16 v[104:107], v[152:155], v[184:187], v[104:107]
	v_mfma_f32_16x16x32_bf16 v[132:135], v[140:143], v[164:167], v[132:135]
	v_mfma_f32_16x16x32_bf16 v[128:131], v[156:159], v[164:167], v[128:131]
	v_mfma_f32_16x16x32_bf16 v[124:127], v[140:143], v[172:175], v[124:127]
	v_mfma_f32_16x16x32_bf16 v[120:123], v[156:159], v[172:175], v[120:123]
	v_mfma_f32_16x16x32_bf16 v[144:147], v[140:143], v[180:183], v[116:119]
	v_mfma_f32_16x16x32_bf16 v[148:151], v[156:159], v[180:183], v[112:115]
	v_mfma_f32_16x16x32_bf16 v[108:111], v[140:143], v[188:191], v[108:111]
	v_mfma_f32_16x16x32_bf16 v[104:107], v[156:159], v[188:191], v[104:107]
	v_add_u32_e32 v112, v227, v232
	s_barrier
	ds_read_b128 v[192:195], v112
	ds_read_b128 v[196:199], v112 offset:1024
	ds_read_b128 v[200:203], v112 offset:2048
	ds_read_b128 v[204:207], v112 offset:3072
	s_barrier
; #define LDA(dst, b, h) for (int m = 0; m < 4; ++m) for (int k = 0; k < 2; ++k) \
;     dst[m][k] = *reinterpret_cast<const bf16x8*>((char*)SA(b, h) + lds_byte(wr * 64 + m * 16 + fr, k * 32 + fq * 8))
; #define LDB(dst, b, h) for (int n = 0; n < 2; ++n) for (int k = 0; k < 2; ++k) \
;     dst[n][k] = *reinterpret_cast<const bf16x8*>((char*)SB(b, h) + lds_byte(wc * 32 + n * 16 + fr, k * 32 + fq * 8))
; #define WAIT_V(n) asm volatile("s_waitcnt vmcnt(" #n ")" ::: "memory")
; #define WAIT_L(n) asm volatile("s_waitcnt lgkmcnt(" #n ")" ::: "memory")
; #define BAR __builtin_amdgcn_s_barrier()
; #define PRO_K0(brow_, bcol_) do { STAGE(SB(0, 0), Bt, bcol_, 0); STAGE(SA(0, 0), A, brow_, 0); STAGE(SB(0, 1), Bt, (bcol_) + HALF, 0); STAGE(SA(0, 1), A, (brow_) + HALF, 0); } while (0)
; template <class Epi>
; DEVI void gemm_phase(const Params& p, const u16* __restrict__ A, const u16* __restrict__ Bt, const int M, const int N, const int K, const int Msplit, const Epi& epi) {
;     ...
;       LDB(B1, 0, 1); BAR; WAIT_L(0); MMA(0, 1, At, B1); BAR;
;       LDA(At, 0, 1); WAIT_V(4); BAR; WAIT_L(0); MMA(1, 0, At, B0); MMA(1, 1, At, B1); BAR; }
;     { LDB(B0, 1, 0); LDA(At, 1, 0); WAIT_V(2); BAR;
;       if (have2) { const u16* Asv = A; const u16* Bsv = Bt; A = An; Bt = Bn; PRO_K0(pm * BM, pn * BM); A = Asv; Bt = Bsv; }
	s_waitcnt lgkmcnt(0)
	s_waitcnt lgkmcnt(0)
	v_mfma_f32_16x16x32_bf16 v[100:103], v[192:195], v[160:163], v[100:103]
	v_mfma_f32_16x16x32_bf16 v[96:99], v[200:203], v[160:163], v[96:99]
	v_mfma_f32_16x16x32_bf16 v[92:95], v[192:195], v[168:171], v[92:95]
	v_mfma_f32_16x16x32_bf16 v[88:91], v[200:203], v[168:171], v[88:91]
	v_mfma_f32_16x16x32_bf16 v[84:87], v[192:195], v[176:179], v[84:87]
	v_mfma_f32_16x16x32_bf16 v[80:83], v[200:203], v[176:179], v[80:83]
	v_mfma_f32_16x16x32_bf16 v[76:79], v[192:195], v[184:187], v[76:79]
	v_mfma_f32_16x16x32_bf16 v[72:75], v[200:203], v[184:187], v[72:75]
	v_mfma_f32_16x16x32_bf16 v[100:103], v[196:199], v[164:167], v[100:103]
	v_mfma_f32_16x16x32_bf16 v[96:99], v[204:207], v[164:167], v[96:99]
	v_mfma_f32_16x16x32_bf16 v[92:95], v[196:199], v[172:175], v[92:95]
	v_mfma_f32_16x16x32_bf16 v[88:91], v[204:207], v[172:175], v[88:91]
	v_mfma_f32_16x16x32_bf16 v[84:87], v[196:199], v[180:183], v[84:87]
	v_mfma_f32_16x16x32_bf16 v[80:83], v[204:207], v[180:183], v[80:83]
	v_mfma_f32_16x16x32_bf16 v[76:79], v[196:199], v[188:191], v[76:79]
	v_mfma_f32_16x16x32_bf16 v[72:75], v[204:207], v[188:191], v[72:75]
	s_barrier
	ds_read_b128 v[160:163], v212 offset:16384
	ds_read_b128 v[164:167], v212 offset:17408
	ds_read_b128 v[168:171], v251 offset:16384
	ds_read_b128 v[172:175], v251 offset:17408
	ds_read_b128 v[176:179], v220 offset:16384
	ds_read_b128 v[180:183], v220 offset:17408
	ds_read_b128 v[184:187], v221 offset:16384
	ds_read_b128 v[188:191], v221 offset:17408
	s_waitcnt vmcnt(4)
	s_barrier
	s_waitcnt lgkmcnt(0)
	s_waitcnt lgkmcnt(0)
	v_mfma_f32_16x16x32_bf16 v[68:71], v[136:139], v[160:163], v[68:71]
	v_mfma_f32_16x16x32_bf16 v[64:67], v[152:155], v[160:163], v[64:67]
	v_mfma_f32_16x16x32_bf16 v[60:63], v[136:139], v[168:171], v[60:63]
	v_mfma_f32_16x16x32_bf16 v[56:59], v[152:155], v[168:171], v[56:59]
	v_mfma_f32_16x16x32_bf16 v[52:55], v[136:139], v[176:179], v[52:55]
	v_mfma_f32_16x16x32_bf16 v[48:51], v[152:155], v[176:179], v[48:51]
	v_mfma_f32_16x16x32_bf16 v[44:47], v[136:139], v[184:187], v[44:47]
	v_mfma_f32_16x16x32_bf16 v[40:43], v[152:155], v[184:187], v[40:43]
	v_mfma_f32_16x16x32_bf16 v[112:115], v[140:143], v[164:167], v[68:71]
	v_mfma_f32_16x16x32_bf16 v[116:119], v[156:159], v[164:167], v[64:67]
	v_mfma_f32_16x16x32_bf16 v[60:63], v[140:143], v[172:175], v[60:63]
	v_mfma_f32_16x16x32_bf16 v[56:59], v[156:159], v[172:175], v[56:59]
	v_mfma_f32_16x16x32_bf16 v[52:55], v[140:143], v[180:183], v[52:55]
	v_mfma_f32_16x16x32_bf16 v[48:51], v[156:159], v[180:183], v[48:51]
	v_mfma_f32_16x16x32_bf16 v[44:47], v[140:143], v[188:191], v[44:47]
	v_mfma_f32_16x16x32_bf16 v[40:43], v[156:159], v[188:191], v[40:43]
	v_mfma_f32_16x16x32_bf16 v[36:39], v[192:195], v[160:163], v[36:39]
	v_mfma_f32_16x16x32_bf16 v[32:35], v[200:203], v[160:163], v[32:35]
	v_mfma_f32_16x16x32_bf16 v[28:31], v[192:195], v[168:171], v[28:31]
	v_mfma_f32_16x16x32_bf16 v[24:27], v[200:203], v[168:171], v[24:27]
	v_mfma_f32_16x16x32_bf16 v[20:23], v[192:195], v[176:179], v[20:23]
	v_mfma_f32_16x16x32_bf16 v[16:19], v[200:203], v[176:179], v[16:19]
	v_mfma_f32_16x16x32_bf16 v[12:15], v[192:195], v[184:187], v[12:15]
	v_mfma_f32_16x16x32_bf16 v[8:11], v[200:203], v[184:187], v[8:11]
	v_mfma_f32_16x16x32_bf16 v[36:39], v[196:199], v[164:167], v[36:39]
	v_mfma_f32_16x16x32_bf16 v[32:35], v[204:207], v[164:167], v[32:35]
	v_mfma_f32_16x16x32_bf16 v[28:31], v[196:199], v[172:175], v[28:31]
	v_mfma_f32_16x16x32_bf16 v[24:27], v[204:207], v[172:175], v[24:27]
	v_mfma_f32_16x16x32_bf16 v[20:23], v[196:199], v[180:183], v[20:23]
	v_mfma_f32_16x16x32_bf16 v[16:19], v[204:207], v[180:183], v[16:19]
	v_mfma_f32_16x16x32_bf16 v[12:15], v[196:199], v[188:191], v[12:15]
	v_mfma_f32_16x16x32_bf16 v[8:11], v[204:207], v[188:191], v[8:11]
	v_add_u32_e32 v64, v228, v232
	s_barrier
	ds_read_b128 v[152:155], v64
	ds_read_b128 v[156:159], v64 offset:1024
	ds_read_b128 v[160:163], v64 offset:2048
	ds_read_b128 v[164:167], v64 offset:3072
	ds_read_b128 v[192:195], v212 offset:32768
	ds_read_b128 v[196:199], v212 offset:33792
	ds_read_b128 v[184:187], v251 offset:32768
	ds_read_b128 v[188:191], v251 offset:33792
	ds_read_b128 v[176:179], v220 offset:32768
	ds_read_b128 v[180:183], v220 offset:33792
	ds_read_b128 v[168:171], v221 offset:32768
	ds_read_b128 v[172:175], v221 offset:33792
	s_waitcnt vmcnt(2)
	s_and_b64 vcc, exec, s[12:13]
	s_barrier
	s_cbranch_vccz .LBB0_1720
	s_lshl_b32 s16, s48, 8
	s_ashr_i32 s17, s16, 31
	s_lshl_b64 s[26:27], s[16:17], 11
	s_add_u32 s26, s18, s26
	s_addc_u32 s27, s19, s27
	s_add_i32 m0, s11, 0x10000
	v_lshl_add_u64 v[64:65], s[26:27], 0, v[208:209]
	global_load_lds_dwordx4 v[64:65], off
	v_lshl_add_u64 v[64:65], s[26:27], 0, v[210:211]
	s_lshl_b32 s26, s43, 8
	s_ashr_i32 s27, s26, 31
	s_add_i32 m0, s11, 0x12000
	s_lshl_b64 s[36:37], s[26:27], 11
	s_add_u32 s36, s22, s36
	s_addc_u32 s37, s23, s37
	s_bitset1_b32 s16, 7
	global_load_lds_dwordx4 v[64:65], off
	s_mov_b32 m0, s11
	v_lshl_add_u64 v[64:65], s[36:37], 0, v[208:209]
	s_ashr_i32 s17, s16, 31
	global_load_lds_dwordx4 v[64:65], off
	s_add_i32 m0, s11, 0x2000
	s_lshl_b64 s[16:17], s[16:17], 11
	s_add_u32 s16, s18, s16
	v_lshl_add_u64 v[64:65], s[36:37], 0, v[210:211]
	s_addc_u32 s17, s19, s17
	global_load_lds_dwordx4 v[64:65], off
	s_add_i32 m0, s11, 0x14000
	v_lshl_add_u64 v[64:65], s[16:17], 0, v[208:209]
	global_load_lds_dwordx4 v[64:65], off
	v_lshl_add_u64 v[64:65], s[16:17], 0, v[210:211]
	s_or_b32 s16, s26, 0x80
	s_ashr_i32 s17, s16, 31
	s_add_i32 m0, s11, 0x16000
	s_lshl_b64 s[16:17], s[16:17], 11
	s_add_u32 s16, s22, s16
	s_addc_u32 s17, s23, s17
	global_load_lds_dwordx4 v[64:65], off
	s_add_i32 m0, s11, 0x4000
	v_lshl_add_u64 v[64:65], s[16:17], 0, v[208:209]
	global_load_lds_dwordx4 v[64:65], off
	v_lshl_add_u64 v[64:65], s[16:17], 0, v[210:211]
	s_add_i32 m0, s11, 0x6000
	s_nop 0
	global_load_lds_dwordx4 v[64:65], off
; #define LDB(dst, b, h) for (int n = 0; n < 2; ++n) for (int k = 0; k < 2; ++k) \
;     dst[n][k] = *reinterpret_cast<const bf16x8*>((char*)SB(b, h) + lds_byte(wc * 32 + n * 16 + fr, k * 32 + fq * 8))
; #define WAIT_V(n) asm volatile("s_waitcnt vmcnt(" #n ")" ::: "memory")
; #define WAIT_L(n) asm volatile("s_waitcnt lgkmcnt(" #n ")" ::: "memory")
; #define BAR __builtin_amdgcn_s_barrier()
; template <class Epi>
; DEVI void gemm_phase(const Params& p, const u16* __restrict__ A, const u16* __restrict__ Bt, const int M, const int N, const int K, const int Msplit, const Epi& epi) {
;     ...
;       WAIT_L(0); MMA(0, 0, At, B0); BAR;
;       LDB(B1, 1, 1); if (have2) { WAIT_V(8); } else { WAIT_V(0); } BAR; WAIT_L(0); MMA(0, 1, At, B1); BAR;
.LBB0_1720:
	s_waitcnt lgkmcnt(0)
	s_waitcnt lgkmcnt(0)
	v_mfma_f32_16x16x32_bf16 v[64:67], v[152:155], v[192:195], v[132:135]
	v_mfma_f32_16x16x32_bf16 v[140:143], v[156:159], v[196:199], v[64:67]
	v_mfma_f32_16x16x32_bf16 v[64:67], v[160:163], v[192:195], v[128:131]
	v_mfma_f32_16x16x32_bf16 v[136:139], v[164:167], v[196:199], v[64:67]
	v_mfma_f32_16x16x32_bf16 v[64:67], v[152:155], v[184:187], v[124:127]
	v_mfma_f32_16x16x32_bf16 v[132:135], v[156:159], v[188:191], v[64:67]
	v_mfma_f32_16x16x32_bf16 v[64:67], v[160:163], v[184:187], v[120:123]
	v_mfma_f32_16x16x32_bf16 v[128:131], v[164:167], v[188:191], v[64:67]
	v_mfma_f32_16x16x32_bf16 v[64:67], v[152:155], v[176:179], v[144:147]
	v_mfma_f32_16x16x32_bf16 v[124:127], v[156:159], v[180:183], v[64:67]
	v_mfma_f32_16x16x32_bf16 v[64:67], v[160:163], v[176:179], v[148:151]
	v_mfma_f32_16x16x32_bf16 v[120:123], v[164:167], v[180:183], v[64:67]
	v_mfma_f32_16x16x32_bf16 v[64:67], v[152:155], v[168:171], v[108:111]
	v_mfma_f32_16x16x32_bf16 v[68:71], v[156:159], v[172:175], v[64:67]
	v_mfma_f32_16x16x32_bf16 v[64:67], v[160:163], v[168:171], v[104:107]
	v_mfma_f32_16x16x32_bf16 v[64:67], v[164:167], v[172:175], v[64:67]
	s_nop 0
	v_add_u32_e32 v104, v229, v232
	s_barrier
	ds_read_b128 v[144:147], v104
	ds_read_b128 v[148:151], v104 offset:1024
	ds_read_b128 v[200:203], v104 offset:2048
	ds_read_b128 v[204:207], v104 offset:3072
	s_mov_b64 s[26:27], -1
	s_and_b64 vcc, exec, s[20:21]
	s_cbranch_vccz .LBB0_1722
	s_waitcnt vmcnt(0)
	s_mov_b64 s[26:27], 0

; #define LDA(dst, b, h) for (int m = 0; m < 4; ++m) for (int k = 0; k < 2; ++k) \
;     dst[m][k] = *reinterpret_cast<const bf16x8*>((char*)SA(b, h) + lds_byte(wr * 64 + m * 16 + fr, k * 32 + fq * 8))
; #define LDB(dst, b, h) for (int n = 0; n < 2; ++n) for (int k = 0; k < 2; ++k) \
;     dst[n][k] = *reinterpret_cast<const bf16x8*>((char*)SB(b, h) + lds_byte(wc * 32 + n * 16 + fr, k * 32 + fq * 8))
; #define WAIT_V(n) asm volatile("s_waitcnt vmcnt(" #n ")" ::: "memory")
; #define WAIT_L(n) asm volatile("s_waitcnt lgkmcnt(" #n ")" ::: "memory")
; #define BAR __builtin_amdgcn_s_barrier()
; template <class Epi>
; DEVI void gemm_phase(const Params& p, const u16* __restrict__ A, const u16* __restrict__ Bt, const int M, const int N, const int K, const int Msplit, const Epi& epi) {
;     ...
;       LDB(B1, 1, 1); if (have2) { WAIT_V(8); } else { WAIT_V(0); } BAR; WAIT_L(0); MMA(0, 1, At, B1); BAR;
;       LDA(At, 1, 1); BAR; WAIT_L(0); MMA(1, 0, At, B0); MMA(1, 1, At, B1); BAR; }
;     if (wr == 0) BAR;
.LBB0_1724:
	s_barrier
	s_waitcnt lgkmcnt(0)
	s_waitcnt lgkmcnt(0)
	v_mfma_f32_16x16x32_bf16 v[100:103], v[144:147], v[192:195], v[100:103]
	v_mfma_f32_16x16x32_bf16 v[96:99], v[200:203], v[192:195], v[96:99]
	v_mfma_f32_16x16x32_bf16 v[92:95], v[144:147], v[184:187], v[92:95]
	v_mfma_f32_16x16x32_bf16 v[88:91], v[200:203], v[184:187], v[88:91]
	v_mfma_f32_16x16x32_bf16 v[84:87], v[144:147], v[176:179], v[84:87]
	v_mfma_f32_16x16x32_bf16 v[80:83], v[200:203], v[176:179], v[80:83]
	v_mfma_f32_16x16x32_bf16 v[76:79], v[144:147], v[168:171], v[76:79]
	v_mfma_f32_16x16x32_bf16 v[72:75], v[200:203], v[168:171], v[72:75]
	v_mfma_f32_16x16x32_bf16 v[108:111], v[148:151], v[196:199], v[100:103]
	v_mfma_f32_16x16x32_bf16 v[104:107], v[204:207], v[196:199], v[96:99]
	v_mfma_f32_16x16x32_bf16 v[100:103], v[148:151], v[188:191], v[92:95]
	v_mfma_f32_16x16x32_bf16 v[96:99], v[204:207], v[188:191], v[88:91]
	v_mfma_f32_16x16x32_bf16 v[92:95], v[148:151], v[180:183], v[84:87]
	v_mfma_f32_16x16x32_bf16 v[88:91], v[204:207], v[180:183], v[80:83]
	v_mfma_f32_16x16x32_bf16 v[84:87], v[148:151], v[172:175], v[76:79]
	v_mfma_f32_16x16x32_bf16 v[80:83], v[204:207], v[172:175], v[72:75]
	s_barrier
	ds_read_b128 v[168:171], v212 offset:49152
	ds_read_b128 v[172:175], v212 offset:50176
	ds_read_b128 v[176:179], v251 offset:49152
	ds_read_b128 v[180:183], v251 offset:50176
	ds_read_b128 v[184:187], v220 offset:49152
	ds_read_b128 v[188:191], v220 offset:50176
	ds_read_b128 v[192:195], v221 offset:49152
	ds_read_b128 v[196:199], v221 offset:50176
	s_barrier
	s_waitcnt lgkmcnt(0)
	s_waitcnt lgkmcnt(0)
	v_mfma_f32_16x16x32_bf16 v[72:75], v[152:155], v[168:171], v[112:115]
	v_mfma_f32_16x16x32_bf16 v[76:79], v[156:159], v[172:175], v[72:75]
	v_mfma_f32_16x16x32_bf16 v[72:75], v[160:163], v[168:171], v[116:119]
	v_mfma_f32_16x16x32_bf16 v[60:63], v[152:155], v[176:179], v[60:63]
	v_mfma_f32_16x16x32_bf16 v[56:59], v[160:163], v[176:179], v[56:59]
	v_mfma_f32_16x16x32_bf16 v[52:55], v[152:155], v[184:187], v[52:55]
	v_mfma_f32_16x16x32_bf16 v[48:51], v[160:163], v[184:187], v[48:51]
	v_mfma_f32_16x16x32_bf16 v[44:47], v[152:155], v[192:195], v[44:47]
	v_mfma_f32_16x16x32_bf16 v[40:43], v[160:163], v[192:195], v[40:43]
	v_mfma_f32_16x16x32_bf16 v[72:75], v[164:167], v[172:175], v[72:75]
	v_mfma_f32_16x16x32_bf16 v[60:63], v[156:159], v[180:183], v[60:63]
	v_mfma_f32_16x16x32_bf16 v[56:59], v[164:167], v[180:183], v[56:59]
	v_mfma_f32_16x16x32_bf16 v[52:55], v[156:159], v[188:191], v[52:55]
	v_mfma_f32_16x16x32_bf16 v[48:51], v[164:167], v[188:191], v[48:51]
	v_mfma_f32_16x16x32_bf16 v[44:47], v[156:159], v[196:199], v[44:47]
	v_mfma_f32_16x16x32_bf16 v[40:43], v[164:167], v[196:199], v[40:43]
	v_mfma_f32_16x16x32_bf16 v[36:39], v[144:147], v[168:171], v[36:39]
	v_mfma_f32_16x16x32_bf16 v[32:35], v[200:203], v[168:171], v[32:35]
	v_mfma_f32_16x16x32_bf16 v[28:31], v[144:147], v[176:179], v[28:31]
	v_mfma_f32_16x16x32_bf16 v[24:27], v[200:203], v[176:179], v[24:27]
	v_mfma_f32_16x16x32_bf16 v[20:23], v[144:147], v[184:187], v[20:23]
	v_mfma_f32_16x16x32_bf16 v[16:19], v[200:203], v[184:187], v[16:19]
	v_mfma_f32_16x16x32_bf16 v[12:15], v[144:147], v[192:195], v[12:15]
	v_mfma_f32_16x16x32_bf16 v[8:11], v[200:203], v[192:195], v[8:11]
	v_mfma_f32_16x16x32_bf16 v[36:39], v[148:151], v[172:175], v[36:39]
	v_mfma_f32_16x16x32_bf16 v[32:35], v[204:207], v[172:175], v[32:35]
	v_mfma_f32_16x16x32_bf16 v[28:31], v[148:151], v[180:183], v[28:31]
	v_mfma_f32_16x16x32_bf16 v[24:27], v[204:207], v[180:183], v[24:27]
	v_mfma_f32_16x16x32_bf16 v[20:23], v[148:151], v[188:191], v[20:23]
	v_mfma_f32_16x16x32_bf16 v[16:19], v[204:207], v[188:191], v[16:19]
	v_mfma_f32_16x16x32_bf16 v[12:15], v[148:151], v[196:199], v[12:15]
	v_mfma_f32_16x16x32_bf16 v[8:11], v[204:207], v[196:199], v[8:11]
	s_barrier
	s_and_saveexec_b64 s[26:27], s[8:9]
	s_cbranch_execz .LBB0_1726
	s_barrier

; #define LDA(dst, b, h) for (int m = 0; m < 4; ++m) for (int k = 0; k < 2; ++k) \
;     dst[m][k] = *reinterpret_cast<const bf16x8*>((char*)SA(b, h) + lds_byte(wr * 64 + m * 16 + fr, k * 32 + fq * 8))
; #define LDB(dst, b, h) for (int n = 0; n < 2; ++n) for (int k = 0; k < 2; ++k) \
;     dst[n][k] = *reinterpret_cast<const bf16x8*>((char*)SB(b, h) + lds_byte(wc * 32 + n * 16 + fr, k * 32 + fq * 8))
; #define WAIT_L(n) asm volatile("s_waitcnt lgkmcnt(" #n ")" ::: "memory")
; #define BAR __builtin_amdgcn_s_barrier()
; #define SCHED __builtin_amdgcn_sched_barrier(0)
; template <class Epi>
; DEVI void gemm_phase(const Params& p, const u16* __restrict__ A, const u16* __restrict__ Bt, const int M, const int N, const int K, const int Msplit, const Epi& epi) {
;     ...
;     for (int t = 0; t < nt - 2; t += 2) {
;       LDB(B0, 0, 0); SCHED; LDA(At, 0, 0); STAGE(SA(1, 1), A, brow + HALF, t + 1);
;       WAIT_L(8); BAR; WAIT_L(0); MMA(0, 0, At, B0); BAR; SCHED;
;       LDB(B1, 0, 1); STAGE(SB(0, 0), Bt, bcol, t + 2);
;       BAR; WAIT_L(0); MMA(0, 1, At, B1); BAR;
;       LDA(At, 0, 1); STAGE(SA(0, 0), A, brow, t + 2);
;       BAR; WAIT_L(0); MMA(1, 0, At, B0); BAR; SCHED;
.LBB0_1994:
	ds_read_b128 v[128:131], v198
	ds_read_b128 v[132:135], v198 offset:1024
	ds_read_b128 v[136:139], v198 offset:2048
	ds_read_b128 v[140:143], v198 offset:3072
	s_add_u32 s16, s62, s14
	s_addc_u32 s39, s63, s15
	s_add_u32 s38, s16, 0x80
	s_addc_u32 s39, s39, 0
	s_add_i32 s47, s19, 0xc000
	ds_read_b128 v[144:147], v199
	ds_read_b128 v[148:151], v199 offset:1024
	ds_read_b128 v[152:155], v200
	ds_read_b128 v[156:159], v200 offset:1024
	ds_read_b128 v[160:163], v201
	ds_read_b128 v[164:167], v201 offset:1024
	ds_read_b128 v[168:171], v202
	ds_read_b128 v[172:175], v202 offset:1024
	s_mov_b32 m0, s47
	v_lshl_add_u64 v[176:177], s[38:39], 0, v[212:213]
	s_add_i32 s46, s19, 0xe000
	global_load_lds_dwordx4 v[176:177], off
	v_lshl_add_u64 v[176:177], s[38:39], 0, v[196:197]
	s_mov_b32 m0, s46
	s_nop 0
	global_load_lds_dwordx4 v[176:177], off
	s_waitcnt lgkmcnt(8)
	s_barrier
	s_waitcnt lgkmcnt(0)
	s_waitcnt lgkmcnt(0)
	v_mfma_f32_16x16x32_bf16 v[124:127], v[128:131], v[144:147], v[124:127]
	v_mfma_f32_16x16x32_bf16 v[120:123], v[136:139], v[144:147], v[120:123]
	v_mfma_f32_16x16x32_bf16 v[116:119], v[128:131], v[152:155], v[116:119]
	v_mfma_f32_16x16x32_bf16 v[112:115], v[136:139], v[152:155], v[112:115]
	v_mfma_f32_16x16x32_bf16 v[108:111], v[128:131], v[160:163], v[108:111]
	v_mfma_f32_16x16x32_bf16 v[104:107], v[136:139], v[160:163], v[104:107]
	v_mfma_f32_16x16x32_bf16 v[100:103], v[128:131], v[168:171], v[100:103]
	v_mfma_f32_16x16x32_bf16 v[96:99], v[136:139], v[168:171], v[96:99]
	v_mfma_f32_16x16x32_bf16 v[124:127], v[132:135], v[148:151], v[124:127]
	v_mfma_f32_16x16x32_bf16 v[120:123], v[140:143], v[148:151], v[120:123]
	v_mfma_f32_16x16x32_bf16 v[116:119], v[132:135], v[156:159], v[116:119]
	v_mfma_f32_16x16x32_bf16 v[112:115], v[140:143], v[156:159], v[112:115]
	v_mfma_f32_16x16x32_bf16 v[108:111], v[132:135], v[164:167], v[108:111]
	v_mfma_f32_16x16x32_bf16 v[104:107], v[140:143], v[164:167], v[104:107]
	v_mfma_f32_16x16x32_bf16 v[100:103], v[132:135], v[172:175], v[100:103]
	v_mfma_f32_16x16x32_bf16 v[96:99], v[140:143], v[172:175], v[96:99]
	s_barrier
	s_add_u32 s54, s23, s14
	s_addc_u32 s55, s48, s15
	s_add_u32 s38, s54, 0x100
	s_addc_u32 s39, s55, 0
	s_add_i32 s16, s19, 0x10000
	ds_read_b128 v[176:179], v203
	ds_read_b128 v[180:183], v203 offset:1024
	ds_read_b128 v[184:187], v203 offset:2048
	ds_read_b128 v[188:191], v203 offset:3072
	s_mov_b32 m0, s16
	v_lshl_add_u64 v[192:193], s[38:39], 0, v[212:213]
	s_add_i32 s89, s19, 0x12000
	global_load_lds_dwordx4 v[192:193], off
	v_lshl_add_u64 v[192:193], s[38:39], 0, v[196:197]
	s_mov_b32 m0, s89
	s_nop 0
	global_load_lds_dwordx4 v[192:193], off
	s_barrier
	s_waitcnt lgkmcnt(0)
	s_waitcnt lgkmcnt(0)
	v_mfma_f32_16x16x32_bf16 v[92:95], v[176:179], v[144:147], v[92:95]
	v_mfma_f32_16x16x32_bf16 v[88:91], v[184:187], v[144:147], v[88:91]
	v_mfma_f32_16x16x32_bf16 v[84:87], v[176:179], v[152:155], v[84:87]
	v_mfma_f32_16x16x32_bf16 v[80:83], v[184:187], v[152:155], v[80:83]
	v_mfma_f32_16x16x32_bf16 v[76:79], v[176:179], v[160:163], v[76:79]
	v_mfma_f32_16x16x32_bf16 v[72:75], v[184:187], v[160:163], v[72:75]
	v_mfma_f32_16x16x32_bf16 v[68:71], v[176:179], v[168:171], v[68:71]
	v_mfma_f32_16x16x32_bf16 v[64:67], v[184:187], v[168:171], v[64:67]
	v_mfma_f32_16x16x32_bf16 v[92:95], v[180:183], v[148:151], v[92:95]
	v_mfma_f32_16x16x32_bf16 v[88:91], v[188:191], v[148:151], v[88:91]
	v_mfma_f32_16x16x32_bf16 v[84:87], v[180:183], v[156:159], v[84:87]
	v_mfma_f32_16x16x32_bf16 v[80:83], v[188:191], v[156:159], v[80:83]
	v_mfma_f32_16x16x32_bf16 v[76:79], v[180:183], v[164:167], v[76:79]
	v_mfma_f32_16x16x32_bf16 v[72:75], v[188:191], v[164:167], v[72:75]
	v_mfma_f32_16x16x32_bf16 v[68:71], v[180:183], v[172:175], v[68:71]
	v_mfma_f32_16x16x32_bf16 v[64:67], v[188:191], v[172:175], v[64:67]
	s_add_u32 s58, s21, s14
	s_addc_u32 s59, s49, s15
	s_add_u32 s38, s58, 0x100
	s_addc_u32 s39, s59, 0
	s_mov_b32 m0, s19
	s_barrier
	ds_read_b128 v[144:147], v199 offset:16384
	ds_read_b128 v[148:151], v199 offset:17408
	ds_read_b128 v[152:155], v200 offset:16384
	ds_read_b128 v[156:159], v200 offset:17408
	ds_read_b128 v[160:163], v201 offset:16384
	ds_read_b128 v[164:167], v201 offset:17408
	ds_read_b128 v[168:171], v202 offset:16384
	ds_read_b128 v[172:175], v202 offset:17408
	s_nop 0
	v_lshl_add_u64 v[192:193], s[38:39], 0, v[212:213]
	global_load_lds_dwordx4 v[192:193], off
	v_lshl_add_u64 v[192:193], s[38:39], 0, v[196:197]
	s_mov_b32 m0, s24
	s_nop 0
	global_load_lds_dwordx4 v[192:193], off
	s_barrier
	s_waitcnt lgkmcnt(0)
	s_waitcnt lgkmcnt(0)
	v_mfma_f32_16x16x32_bf16 v[60:63], v[128:131], v[144:147], v[60:63]
	v_mfma_f32_16x16x32_bf16 v[56:59], v[136:139], v[144:147], v[56:59]
	v_mfma_f32_16x16x32_bf16 v[52:55], v[128:131], v[152:155], v[52:55]
	v_mfma_f32_16x16x32_bf16 v[48:51], v[136:139], v[152:155], v[48:51]
	v_mfma_f32_16x16x32_bf16 v[44:47], v[128:131], v[160:163], v[44:47]
	v_mfma_f32_16x16x32_bf16 v[40:43], v[136:139], v[160:163], v[40:43]
	v_mfma_f32_16x16x32_bf16 v[36:39], v[128:131], v[168:171], v[36:39]
	v_mfma_f32_16x16x32_bf16 v[32:35], v[136:139], v[168:171], v[32:35]
	v_mfma_f32_16x16x32_bf16 v[60:63], v[132:135], v[148:151], v[60:63]
	v_mfma_f32_16x16x32_bf16 v[56:59], v[140:143], v[148:151], v[56:59]
	v_mfma_f32_16x16x32_bf16 v[52:55], v[132:135], v[156:159], v[52:55]
	v_mfma_f32_16x16x32_bf16 v[48:51], v[140:143], v[156:159], v[48:51]
	v_mfma_f32_16x16x32_bf16 v[44:47], v[132:135], v[164:167], v[44:47]
	v_mfma_f32_16x16x32_bf16 v[40:43], v[140:143], v[164:167], v[40:43]
	v_mfma_f32_16x16x32_bf16 v[36:39], v[132:135], v[172:175], v[36:39]
	v_mfma_f32_16x16x32_bf16 v[32:35], v[140:143], v[172:175], v[32:35]
	s_barrier
; #define LDA(dst, b, h) for (int m = 0; m < 4; ++m) for (int k = 0; k < 2; ++k) \
;     dst[m][k] = *reinterpret_cast<const bf16x8*>((char*)SA(b, h) + lds_byte(wr * 64 + m * 16 + fr, k * 32 + fq * 8))
; #define LDB(dst, b, h) for (int n = 0; n < 2; ++n) for (int k = 0; k < 2; ++k) \
;     dst[n][k] = *reinterpret_cast<const bf16x8*>((char*)SB(b, h) + lds_byte(wc * 32 + n * 16 + fr, k * 32 + fq * 8))
; #define WAIT_V(n) asm volatile("s_waitcnt vmcnt(" #n ")" ::: "memory")
; #define WAIT_L(n) asm volatile("s_waitcnt lgkmcnt(" #n ")" ::: "memory")
; #define BAR __builtin_amdgcn_s_barrier()
; #define SCHED __builtin_amdgcn_sched_barrier(0)
; template <class Epi>
; DEVI void gemm_phase(const Params& p, const u16* __restrict__ A, const u16* __restrict__ Bt, const int M, const int N, const int K, const int Msplit, const Epi& epi) {
;     ...
;       STAGE(SB(0, 1), Bt, bcol + HALF, t + 2);
;       WAIT_V(6); BAR; MMA(1, 1, At, B1); BAR;
;       LDB(B0, 1, 0); SCHED; LDA(At, 1, 0); STAGE(SA(0, 1), A, brow + HALF, t + 2);
;       WAIT_L(8); BAR; WAIT_L(0); MMA(0, 0, At, B0); BAR; SCHED;
;       LDB(B1, 1, 1); STAGE(SB(1, 0), Bt, bcol, t + 3);
;       BAR; WAIT_L(0); MMA(0, 1, At, B1); BAR;
;       LDA(At, 1, 1); STAGE(SA(1, 0), A, brow, t + 3);
	s_add_u32 s90, s52, s14
	s_addc_u32 vcc_lo, s53, s15
	s_add_u32 s44, s90, 0x100
	s_addc_u32 s45, vcc_lo, 0
	s_add_i32 s38, s19, 0x14000
	s_mov_b32 m0, s38
	v_lshl_add_u64 v[128:129], s[44:45], 0, v[212:213]
	s_add_i32 s39, s19, 0x16000
	global_load_lds_dwordx4 v[128:129], off
	v_lshl_add_u64 v[128:129], s[44:45], 0, v[196:197]
	s_mov_b32 m0, s39
	s_nop 0
	global_load_lds_dwordx4 v[128:129], off
	s_waitcnt vmcnt(6)
	s_barrier
	v_mfma_f32_16x16x32_bf16 v[28:31], v[176:179], v[144:147], v[28:31]
	v_mfma_f32_16x16x32_bf16 v[24:27], v[184:187], v[144:147], v[24:27]
	v_mfma_f32_16x16x32_bf16 v[20:23], v[176:179], v[152:155], v[20:23]
	v_mfma_f32_16x16x32_bf16 v[16:19], v[184:187], v[152:155], v[16:19]
	v_mfma_f32_16x16x32_bf16 v[12:15], v[176:179], v[160:163], v[12:15]
	v_mfma_f32_16x16x32_bf16 v[8:11], v[184:187], v[160:163], v[8:11]
	v_mfma_f32_16x16x32_bf16 v[4:7], v[176:179], v[168:171], v[4:7]
	v_mfma_f32_16x16x32_bf16 v[0:3], v[184:187], v[168:171], v[0:3]
	v_mfma_f32_16x16x32_bf16 v[28:31], v[180:183], v[148:151], v[28:31]
	v_mfma_f32_16x16x32_bf16 v[24:27], v[188:191], v[148:151], v[24:27]
	v_mfma_f32_16x16x32_bf16 v[20:23], v[180:183], v[156:159], v[20:23]
	v_mfma_f32_16x16x32_bf16 v[16:19], v[188:191], v[156:159], v[16:19]
	v_mfma_f32_16x16x32_bf16 v[12:15], v[180:183], v[164:167], v[12:15]
	v_mfma_f32_16x16x32_bf16 v[8:11], v[188:191], v[164:167], v[8:11]
	v_mfma_f32_16x16x32_bf16 v[4:7], v[180:183], v[172:175], v[4:7]
	v_mfma_f32_16x16x32_bf16 v[0:3], v[188:191], v[172:175], v[0:3]
	s_barrier
	ds_read_b128 v[128:131], v204
	ds_read_b128 v[132:135], v204 offset:1024
	ds_read_b128 v[136:139], v204 offset:2048
	ds_read_b128 v[140:143], v204 offset:3072
	s_add_u32 s44, s56, s14
	s_addc_u32 s45, s57, s15
	s_mov_b32 m0, s25
	ds_read_b128 v[144:147], v199 offset:32768
	ds_read_b128 v[148:151], v199 offset:33792
	ds_read_b128 v[152:155], v200 offset:32768
	ds_read_b128 v[156:159], v200 offset:33792
	ds_read_b128 v[160:163], v201 offset:32768
	ds_read_b128 v[164:167], v201 offset:33792
	ds_read_b128 v[168:171], v202 offset:32768
	ds_read_b128 v[172:175], v202 offset:33792
	s_nop 0
	v_lshl_add_u64 v[176:177], s[44:45], 0, v[212:213]
	global_load_lds_dwordx4 v[176:177], off
	v_lshl_add_u64 v[176:177], s[44:45], 0, v[196:197]
	s_mov_b32 m0, s26
	s_nop 0
	global_load_lds_dwordx4 v[176:177], off
	s_waitcnt lgkmcnt(8)
	s_barrier
	s_waitcnt lgkmcnt(0)
	s_waitcnt lgkmcnt(0)
	v_mfma_f32_16x16x32_bf16 v[124:127], v[128:131], v[144:147], v[124:127]
	v_mfma_f32_16x16x32_bf16 v[120:123], v[136:139], v[144:147], v[120:123]
	v_mfma_f32_16x16x32_bf16 v[116:119], v[128:131], v[152:155], v[116:119]
	v_mfma_f32_16x16x32_bf16 v[112:115], v[136:139], v[152:155], v[112:115]
	v_mfma_f32_16x16x32_bf16 v[108:111], v[128:131], v[160:163], v[108:111]
	v_mfma_f32_16x16x32_bf16 v[104:107], v[136:139], v[160:163], v[104:107]
	v_mfma_f32_16x16x32_bf16 v[100:103], v[128:131], v[168:171], v[100:103]
	v_mfma_f32_16x16x32_bf16 v[96:99], v[136:139], v[168:171], v[96:99]
	v_mfma_f32_16x16x32_bf16 v[124:127], v[132:135], v[148:151], v[124:127]
	v_mfma_f32_16x16x32_bf16 v[120:123], v[140:143], v[148:151], v[120:123]
	v_mfma_f32_16x16x32_bf16 v[116:119], v[132:135], v[156:159], v[116:119]
	v_mfma_f32_16x16x32_bf16 v[112:115], v[140:143], v[156:159], v[112:115]
	v_mfma_f32_16x16x32_bf16 v[108:111], v[132:135], v[164:167], v[108:111]
	v_mfma_f32_16x16x32_bf16 v[104:107], v[140:143], v[164:167], v[104:107]
	v_mfma_f32_16x16x32_bf16 v[100:103], v[132:135], v[172:175], v[100:103]
	v_mfma_f32_16x16x32_bf16 v[96:99], v[140:143], v[172:175], v[96:99]
	s_barrier
	s_add_u32 s44, s54, 0x180
	s_addc_u32 s45, s55, 0
	s_add_i32 s88, s19, 0x18000
	ds_read_b128 v[176:179], v205
	ds_read_b128 v[180:183], v205 offset:1024
	ds_read_b128 v[184:187], v205 offset:2048
	ds_read_b128 v[188:191], v205 offset:3072
	s_mov_b32 m0, s88
	v_lshl_add_u64 v[192:193], s[44:45], 0, v[212:213]
	s_add_i32 s77, s19, 0x1a000
	global_load_lds_dwordx4 v[192:193], off
	v_lshl_add_u64 v[192:193], s[44:45], 0, v[196:197]
	s_mov_b32 m0, s77
	s_nop 0
	global_load_lds_dwordx4 v[192:193], off
	s_barrier
	s_waitcnt lgkmcnt(0)
	s_waitcnt lgkmcnt(0)
	v_mfma_f32_16x16x32_bf16 v[92:95], v[176:179], v[144:147], v[92:95]
	v_mfma_f32_16x16x32_bf16 v[88:91], v[184:187], v[144:147], v[88:91]
	v_mfma_f32_16x16x32_bf16 v[84:87], v[176:179], v[152:155], v[84:87]
	v_mfma_f32_16x16x32_bf16 v[80:83], v[184:187], v[152:155], v[80:83]
	v_mfma_f32_16x16x32_bf16 v[76:79], v[176:179], v[160:163], v[76:79]
	v_mfma_f32_16x16x32_bf16 v[72:75], v[184:187], v[160:163], v[72:75]
	v_mfma_f32_16x16x32_bf16 v[68:71], v[176:179], v[168:171], v[68:71]
	v_mfma_f32_16x16x32_bf16 v[64:67], v[184:187], v[168:171], v[64:67]
	v_mfma_f32_16x16x32_bf16 v[92:95], v[180:183], v[148:151], v[92:95]
	v_mfma_f32_16x16x32_bf16 v[88:91], v[188:191], v[148:151], v[88:91]
	v_mfma_f32_16x16x32_bf16 v[84:87], v[180:183], v[156:159], v[84:87]
	v_mfma_f32_16x16x32_bf16 v[80:83], v[188:191], v[156:159], v[80:83]
	v_mfma_f32_16x16x32_bf16 v[76:79], v[180:183], v[164:167], v[76:79]
	v_mfma_f32_16x16x32_bf16 v[72:75], v[188:191], v[164:167], v[72:75]
	v_mfma_f32_16x16x32_bf16 v[68:71], v[180:183], v[172:175], v[68:71]
	v_mfma_f32_16x16x32_bf16 v[64:67], v[188:191], v[172:175], v[64:67]
	s_add_u32 s44, s58, 0x180
	s_addc_u32 s45, s59, 0
	s_mov_b32 m0, s27
	s_barrier
	ds_read_b128 v[144:147], v199 offset:49152
	ds_read_b128 v[148:151], v199 offset:50176
	ds_read_b128 v[152:155], v200 offset:49152
	ds_read_b128 v[156:159], v200 offset:50176
	ds_read_b128 v[160:163], v201 offset:49152
	ds_read_b128 v[164:167], v201 offset:50176
	ds_read_b128 v[168:171], v202 offset:49152
	ds_read_b128 v[172:175], v202 offset:50176
	s_nop 0
	v_lshl_add_u64 v[192:193], s[44:45], 0, v[212:213]
	global_load_lds_dwordx4 v[192:193], off
	v_lshl_add_u64 v[192:193], s[44:45], 0, v[196:197]
	s_mov_b32 m0, s36
	s_nop 0
	global_load_lds_dwordx4 v[192:193], off
	s_barrier
; #define LDA(dst, b, h) for (int m = 0; m < 4; ++m) for (int k = 0; k < 2; ++k) \
;     dst[m][k] = *reinterpret_cast<const bf16x8*>((char*)SA(b, h) + lds_byte(wr * 64 + m * 16 + fr, k * 32 + fq * 8))
; #define LDB(dst, b, h) for (int n = 0; n < 2; ++n) for (int k = 0; k < 2; ++k) \
;     dst[n][k] = *reinterpret_cast<const bf16x8*>((char*)SB(b, h) + lds_byte(wc * 32 + n * 16 + fr, k * 32 + fq * 8))
; #define WAIT_V(n) asm volatile("s_waitcnt vmcnt(" #n ")" ::: "memory")
; #define WAIT_L(n) asm volatile("s_waitcnt lgkmcnt(" #n ")" ::: "memory")
; #define BAR __builtin_amdgcn_s_barrier()
; #define SCHED __builtin_amdgcn_sched_barrier(0)
; template <class Epi>
; DEVI void gemm_phase(const Params& p, const u16* __restrict__ A, const u16* __restrict__ Bt, const int M, const int N, const int K, const int Msplit, const Epi& epi) {
;     ...
;       BAR; WAIT_L(0); MMA(1, 0, At, B0); BAR; SCHED;
;       STAGE(SB(1, 1), Bt, bcol + HALF, t + 3);
;       WAIT_V(6); BAR; MMA(1, 1, At, B1); BAR;
;     }
;     { LDB(B0, 0, 0); LDA(At, 0, 0); STAGE(SA(1, 1), A, brow + HALF, nt - 1);
;       BAR; WAIT_L(0); MMA(0, 0, At, B0); BAR;
;       LDB(B1, 0, 1); BAR; WAIT_L(0); MMA(0, 1, At, B1); BAR;
	s_waitcnt lgkmcnt(0)
	s_waitcnt lgkmcnt(0)
	v_mfma_f32_16x16x32_bf16 v[60:63], v[128:131], v[144:147], v[60:63]
	v_mfma_f32_16x16x32_bf16 v[56:59], v[136:139], v[144:147], v[56:59]
	v_mfma_f32_16x16x32_bf16 v[52:55], v[128:131], v[152:155], v[52:55]
	v_mfma_f32_16x16x32_bf16 v[48:51], v[136:139], v[152:155], v[48:51]
	v_mfma_f32_16x16x32_bf16 v[44:47], v[128:131], v[160:163], v[44:47]
	v_mfma_f32_16x16x32_bf16 v[40:43], v[136:139], v[160:163], v[40:43]
	v_mfma_f32_16x16x32_bf16 v[36:39], v[128:131], v[168:171], v[36:39]
	v_mfma_f32_16x16x32_bf16 v[32:35], v[136:139], v[168:171], v[32:35]
	v_mfma_f32_16x16x32_bf16 v[60:63], v[132:135], v[148:151], v[60:63]
	v_mfma_f32_16x16x32_bf16 v[56:59], v[140:143], v[148:151], v[56:59]
	v_mfma_f32_16x16x32_bf16 v[52:55], v[132:135], v[156:159], v[52:55]
	v_mfma_f32_16x16x32_bf16 v[48:51], v[140:143], v[156:159], v[48:51]
	v_mfma_f32_16x16x32_bf16 v[44:47], v[132:135], v[164:167], v[44:47]
	v_mfma_f32_16x16x32_bf16 v[40:43], v[140:143], v[164:167], v[40:43]
	v_mfma_f32_16x16x32_bf16 v[36:39], v[132:135], v[172:175], v[36:39]
	v_mfma_f32_16x16x32_bf16 v[32:35], v[140:143], v[172:175], v[32:35]
	s_barrier
	s_add_u32 s54, s90, 0x180
	s_addc_u32 s55, vcc_lo, 0
	s_add_i32 s44, s19, 0x1c000
	s_mov_b32 m0, s44
	v_lshl_add_u64 v[128:129], s[54:55], 0, v[212:213]
	s_add_i32 s45, s19, 0x1e000
	global_load_lds_dwordx4 v[128:129], off
	v_lshl_add_u64 v[128:129], s[54:55], 0, v[196:197]
	s_mov_b32 m0, s45
	s_nop 0
	global_load_lds_dwordx4 v[128:129], off
	s_waitcnt vmcnt(6)
	s_barrier
	v_mfma_f32_16x16x32_bf16 v[28:31], v[176:179], v[144:147], v[28:31]
	v_mfma_f32_16x16x32_bf16 v[24:27], v[184:187], v[144:147], v[24:27]
	v_mfma_f32_16x16x32_bf16 v[20:23], v[176:179], v[152:155], v[20:23]
	v_mfma_f32_16x16x32_bf16 v[16:19], v[184:187], v[152:155], v[16:19]
	v_mfma_f32_16x16x32_bf16 v[12:15], v[176:179], v[160:163], v[12:15]
	v_mfma_f32_16x16x32_bf16 v[8:11], v[184:187], v[160:163], v[8:11]
	v_mfma_f32_16x16x32_bf16 v[4:7], v[176:179], v[168:171], v[4:7]
	v_mfma_f32_16x16x32_bf16 v[0:3], v[184:187], v[168:171], v[0:3]
	v_mfma_f32_16x16x32_bf16 v[28:31], v[180:183], v[148:151], v[28:31]
	v_mfma_f32_16x16x32_bf16 v[24:27], v[188:191], v[148:151], v[24:27]
	v_mfma_f32_16x16x32_bf16 v[20:23], v[180:183], v[156:159], v[20:23]
	v_mfma_f32_16x16x32_bf16 v[16:19], v[188:191], v[156:159], v[16:19]
	v_mfma_f32_16x16x32_bf16 v[12:15], v[180:183], v[164:167], v[12:15]
	v_mfma_f32_16x16x32_bf16 v[8:11], v[188:191], v[164:167], v[8:11]
	v_mfma_f32_16x16x32_bf16 v[4:7], v[180:183], v[172:175], v[4:7]
	v_mfma_f32_16x16x32_bf16 v[0:3], v[188:191], v[172:175], v[0:3]
	s_add_u32 s14, s14, 0x100
	s_addc_u32 s15, s15, 0
	s_add_i32 s76, s76, 2
	s_cmp_lt_u32 s76, 12
	s_barrier
	s_cbranch_scc1 .LBB0_1994
	s_add_u32 s14, s42, 0x780
	s_addc_u32 s15, s43, 0
	s_mov_b32 m0, s47
	ds_read_b128 v[156:159], v198
	ds_read_b128 v[160:163], v198 offset:1024
	ds_read_b128 v[164:167], v198 offset:2048
	ds_read_b128 v[168:171], v198 offset:3072
	ds_read_b128 v[128:131], v199
	ds_read_b128 v[132:135], v199 offset:1024
	ds_read_b128 v[136:139], v200
	ds_read_b128 v[140:143], v200 offset:1024
	ds_read_b128 v[144:147], v201
	ds_read_b128 v[148:151], v201 offset:1024
	ds_read_b128 v[152:155], v202
	ds_read_b128 v[172:175], v202 offset:1024
	s_nop 0
	v_lshl_add_u64 v[176:177], s[14:15], 0, v[212:213]
	global_load_lds_dwordx4 v[176:177], off
	v_lshl_add_u64 v[176:177], s[14:15], 0, v[196:197]
	s_mov_b32 m0, s46
	s_nop 0
	global_load_lds_dwordx4 v[176:177], off
	s_barrier
	s_waitcnt lgkmcnt(0)
	s_waitcnt lgkmcnt(0)
	v_mfma_f32_16x16x32_bf16 v[124:127], v[156:159], v[128:131], v[124:127]
	v_mfma_f32_16x16x32_bf16 v[120:123], v[164:167], v[128:131], v[120:123]
	v_mfma_f32_16x16x32_bf16 v[116:119], v[156:159], v[136:139], v[116:119]
	v_mfma_f32_16x16x32_bf16 v[112:115], v[164:167], v[136:139], v[112:115]
	v_mfma_f32_16x16x32_bf16 v[108:111], v[156:159], v[144:147], v[108:111]
	v_mfma_f32_16x16x32_bf16 v[104:107], v[164:167], v[144:147], v[104:107]
	v_mfma_f32_16x16x32_bf16 v[100:103], v[156:159], v[152:155], v[100:103]
	v_mfma_f32_16x16x32_bf16 v[96:99], v[164:167], v[152:155], v[96:99]
	v_mfma_f32_16x16x32_bf16 v[124:127], v[160:163], v[132:135], v[124:127]
	v_mfma_f32_16x16x32_bf16 v[176:179], v[168:171], v[132:135], v[120:123]
	v_mfma_f32_16x16x32_bf16 v[116:119], v[160:163], v[140:143], v[116:119]
	v_mfma_f32_16x16x32_bf16 v[180:183], v[168:171], v[140:143], v[112:115]
	v_mfma_f32_16x16x32_bf16 v[108:111], v[160:163], v[148:151], v[108:111]
	v_mfma_f32_16x16x32_bf16 v[184:187], v[168:171], v[148:151], v[104:107]
	v_mfma_f32_16x16x32_bf16 v[100:103], v[160:163], v[172:175], v[100:103]
	v_mfma_f32_16x16x32_bf16 v[188:191], v[168:171], v[172:175], v[96:99]
	s_barrier
	s_nop 0
	ds_read_b128 v[96:99], v203
	ds_read_b128 v[104:107], v203 offset:1024
	ds_read_b128 v[112:115], v203 offset:2048
	ds_read_b128 v[120:123], v203 offset:3072
	s_barrier
	s_waitcnt lgkmcnt(0)
	s_waitcnt lgkmcnt(0)
	v_mfma_f32_16x16x32_bf16 v[92:95], v[96:99], v[128:131], v[92:95]
	v_mfma_f32_16x16x32_bf16 v[88:91], v[112:115], v[128:131], v[88:91]
	v_mfma_f32_16x16x32_bf16 v[84:87], v[96:99], v[136:139], v[84:87]
	v_mfma_f32_16x16x32_bf16 v[80:83], v[112:115], v[136:139], v[80:83]
	v_mfma_f32_16x16x32_bf16 v[76:79], v[96:99], v[144:147], v[76:79]
	v_mfma_f32_16x16x32_bf16 v[72:75], v[112:115], v[144:147], v[72:75]
	v_mfma_f32_16x16x32_bf16 v[68:71], v[96:99], v[152:155], v[68:71]
	v_mfma_f32_16x16x32_bf16 v[64:67], v[112:115], v[152:155], v[64:67]
	v_mfma_f32_16x16x32_bf16 v[92:95], v[104:107], v[132:135], v[92:95]
	v_mfma_f32_16x16x32_bf16 v[128:131], v[120:123], v[132:135], v[88:91]
	v_mfma_f32_16x16x32_bf16 v[84:87], v[104:107], v[140:143], v[84:87]
	v_mfma_f32_16x16x32_bf16 v[132:135], v[120:123], v[140:143], v[80:83]
	v_mfma_f32_16x16x32_bf16 v[76:79], v[104:107], v[148:151], v[76:79]
	v_mfma_f32_16x16x32_bf16 v[136:139], v[120:123], v[148:151], v[72:75]
	v_mfma_f32_16x16x32_bf16 v[68:71], v[104:107], v[172:175], v[68:71]
	v_mfma_f32_16x16x32_bf16 v[140:143], v[120:123], v[172:175], v[64:67]
	s_barrier
; #define LDA(dst, b, h) for (int m = 0; m < 4; ++m) for (int k = 0; k < 2; ++k) \
;     dst[m][k] = *reinterpret_cast<const bf16x8*>((char*)SA(b, h) + lds_byte(wr * 64 + m * 16 + fr, k * 32 + fq * 8))
; #define LDB(dst, b, h) for (int n = 0; n < 2; ++n) for (int k = 0; k < 2; ++k) \
;     dst[n][k] = *reinterpret_cast<const bf16x8*>((char*)SB(b, h) + lds_byte(wc * 32 + n * 16 + fr, k * 32 + fq * 8))
; #define WAIT_V(n) asm volatile("s_waitcnt vmcnt(" #n ")" ::: "memory")
; #define WAIT_L(n) asm volatile("s_waitcnt lgkmcnt(" #n ")" ::: "memory")
; #define BAR __builtin_amdgcn_s_barrier()
; #define PRO_K0(brow_, bcol_) do { STAGE(SB(0, 0), Bt, bcol_, 0); STAGE(SA(0, 0), A, brow_, 0); STAGE(SB(0, 1), Bt, (bcol_) + HALF, 0); STAGE(SA(0, 1), A, (brow_) + HALF, 0); } while (0)
; template <class Epi>
; DEVI void gemm_phase(const Params& p, const u16* __restrict__ A, const u16* __restrict__ Bt, const int M, const int N, const int K, const int Msplit, const Epi& epi) {
;     ...
;       LDA(At, 0, 1); WAIT_V(4); BAR; WAIT_L(0); MMA(1, 0, At, B0); MMA(1, 1, At, B1); BAR; }
;     { LDB(B0, 1, 0); LDA(At, 1, 0); WAIT_V(2); BAR;
;       if (have2) { const u16* Asv = A; const u16* Bsv = Bt; A = An; Bt = Bn; PRO_K0(pm * BM, pn * BM); A = Asv; Bt = Bsv; }
;       WAIT_L(0); MMA(0, 0, At, B0); BAR;
;       LDB(B1, 1, 1); if (have2) { WAIT_V(8); } else { WAIT_V(0); } BAR; WAIT_L(0); MMA(0, 1, At, B1); BAR;
	s_nop 0
	ds_read_b128 v[64:67], v199 offset:16384
	ds_read_b128 v[72:75], v199 offset:17408
	ds_read_b128 v[80:83], v200 offset:16384
	ds_read_b128 v[88:91], v200 offset:17408
	ds_read_b128 v[172:175], v201 offset:16384
	ds_read_b128 v[192:195], v201 offset:17408
	ds_read_b128 v[206:209], v202 offset:16384
	ds_read_b128 v[214:217], v202 offset:17408
	s_waitcnt vmcnt(4)
	s_barrier
	s_waitcnt lgkmcnt(0)
	s_waitcnt lgkmcnt(0)
	v_mfma_f32_16x16x32_bf16 v[60:63], v[156:159], v[64:67], v[60:63]
	v_mfma_f32_16x16x32_bf16 v[56:59], v[164:167], v[64:67], v[56:59]
	v_mfma_f32_16x16x32_bf16 v[52:55], v[156:159], v[80:83], v[52:55]
	v_mfma_f32_16x16x32_bf16 v[48:51], v[164:167], v[80:83], v[48:51]
	v_mfma_f32_16x16x32_bf16 v[44:47], v[156:159], v[172:175], v[44:47]
	v_mfma_f32_16x16x32_bf16 v[40:43], v[164:167], v[172:175], v[40:43]
	v_mfma_f32_16x16x32_bf16 v[36:39], v[156:159], v[206:209], v[36:39]
	v_mfma_f32_16x16x32_bf16 v[32:35], v[164:167], v[206:209], v[32:35]
	v_mfma_f32_16x16x32_bf16 v[60:63], v[160:163], v[72:75], v[60:63]
	v_mfma_f32_16x16x32_bf16 v[144:147], v[168:171], v[72:75], v[56:59]
	v_mfma_f32_16x16x32_bf16 v[52:55], v[160:163], v[88:91], v[52:55]
	v_mfma_f32_16x16x32_bf16 v[148:151], v[168:171], v[88:91], v[48:51]
	v_mfma_f32_16x16x32_bf16 v[44:47], v[160:163], v[192:195], v[44:47]
	v_mfma_f32_16x16x32_bf16 v[152:155], v[168:171], v[192:195], v[40:43]
	v_mfma_f32_16x16x32_bf16 v[36:39], v[160:163], v[214:217], v[36:39]
	v_mfma_f32_16x16x32_bf16 v[156:159], v[168:171], v[214:217], v[32:35]
	v_mfma_f32_16x16x32_bf16 v[28:31], v[96:99], v[64:67], v[28:31]
	v_mfma_f32_16x16x32_bf16 v[24:27], v[112:115], v[64:67], v[24:27]
	v_mfma_f32_16x16x32_bf16 v[20:23], v[96:99], v[80:83], v[20:23]
	v_mfma_f32_16x16x32_bf16 v[16:19], v[112:115], v[80:83], v[16:19]
	v_mfma_f32_16x16x32_bf16 v[12:15], v[96:99], v[172:175], v[12:15]
	v_mfma_f32_16x16x32_bf16 v[8:11], v[112:115], v[172:175], v[8:11]
	v_mfma_f32_16x16x32_bf16 v[4:7], v[96:99], v[206:209], v[4:7]
	v_mfma_f32_16x16x32_bf16 v[0:3], v[112:115], v[206:209], v[0:3]
	v_mfma_f32_16x16x32_bf16 v[28:31], v[104:107], v[72:75], v[28:31]
	v_mfma_f32_16x16x32_bf16 v[160:163], v[120:123], v[72:75], v[24:27]
	v_mfma_f32_16x16x32_bf16 v[20:23], v[104:107], v[88:91], v[20:23]
	v_mfma_f32_16x16x32_bf16 v[164:167], v[120:123], v[88:91], v[16:19]
	v_mfma_f32_16x16x32_bf16 v[12:15], v[104:107], v[192:195], v[12:15]
	v_mfma_f32_16x16x32_bf16 v[168:171], v[120:123], v[192:195], v[8:11]
	v_mfma_f32_16x16x32_bf16 v[4:7], v[104:107], v[214:217], v[4:7]
	v_mfma_f32_16x16x32_bf16 v[172:175], v[120:123], v[214:217], v[0:3]
	s_barrier
	s_nop 0
	ds_read_b128 v[0:3], v204
	ds_read_b128 v[8:11], v204 offset:1024
	ds_read_b128 v[16:19], v204 offset:2048
	ds_read_b128 v[24:27], v204 offset:3072
	ds_read_b128 v[80:83], v199 offset:32768
	ds_read_b128 v[192:195], v199 offset:33792
	ds_read_b128 v[64:67], v200 offset:32768
	ds_read_b128 v[72:75], v200 offset:33792
	ds_read_b128 v[48:51], v201 offset:32768
	ds_read_b128 v[56:59], v201 offset:33792
	ds_read_b128 v[32:35], v202 offset:32768
	ds_read_b128 v[40:43], v202 offset:33792
	s_waitcnt vmcnt(2)
	v_cndmask_b32_e64 v88, 0, 1, s[12:13]
	v_cmp_ne_u32_e64 s[14:15], 1, v88
	s_andn2_b64 vcc, exec, s[12:13]
	s_barrier
	s_cbranch_vccnz .LBB0_1997
	s_lshl_b32 s12, s40, 8
	s_ashr_i32 s13, s12, 31
	s_lshl_b64 s[42:43], s[12:13], 11
	s_add_u32 s42, s1, s42
	s_addc_u32 s43, s2, s43
	s_mov_b32 m0, s16
	s_lshl_b32 s90, s41, 8
	v_lshl_add_u64 v[88:89], s[42:43], 0, v[212:213]
	global_load_lds_dwordx4 v[88:89], off
	v_lshl_add_u64 v[88:89], s[42:43], 0, v[196:197]
	s_lshl_b64 s[42:43], s[90:91], 11
	s_add_u32 s42, s68, s42
	s_addc_u32 s43, s69, s43
	s_bitset1_b32 s12, 7
	s_ashr_i32 s13, s12, 31
	s_mov_b32 m0, s89
	s_lshl_b64 s[12:13], s[12:13], 11
	global_load_lds_dwordx4 v[88:89], off
	s_mov_b32 m0, s19
	v_lshl_add_u64 v[88:89], s[42:43], 0, v[212:213]
	s_add_u32 s12, s1, s12
	global_load_lds_dwordx4 v[88:89], off
	v_lshl_add_u64 v[88:89], s[42:43], 0, v[196:197]
	s_mov_b32 m0, s24
	s_addc_u32 s13, s2, s13
	global_load_lds_dwordx4 v[88:89], off
	s_mov_b32 m0, s38
	v_lshl_add_u64 v[88:89], s[12:13], 0, v[212:213]
	s_bitset1_b32 s90, 7
	global_load_lds_dwordx4 v[88:89], off
	v_lshl_add_u64 v[88:89], s[12:13], 0, v[196:197]
	s_lshl_b64 s[12:13], s[90:91], 11
	s_add_u32 s12, s68, s12
	s_mov_b32 m0, s39
	s_addc_u32 s13, s69, s13
	global_load_lds_dwordx4 v[88:89], off
	s_mov_b32 m0, s25
	v_lshl_add_u64 v[88:89], s[12:13], 0, v[212:213]
	global_load_lds_dwordx4 v[88:89], off
	v_lshl_add_u64 v[88:89], s[12:13], 0, v[196:197]
	s_mov_b32 m0, s26
	s_nop 0
	global_load_lds_dwordx4 v[88:89], off
.LBB0_1997:
	s_waitcnt lgkmcnt(0)
	s_waitcnt lgkmcnt(0)
	v_mfma_f32_16x16x32_bf16 v[88:91], v[0:3], v[80:83], v[124:127]
	v_mfma_f32_16x16x32_bf16 v[120:123], v[8:11], v[192:195], v[88:91]
	v_mfma_f32_16x16x32_bf16 v[88:91], v[16:19], v[80:83], v[176:179]
	v_mfma_f32_16x16x32_bf16 v[124:127], v[24:27], v[192:195], v[88:91]
	v_mfma_f32_16x16x32_bf16 v[88:91], v[0:3], v[64:67], v[116:119]
	v_mfma_f32_16x16x32_bf16 v[112:115], v[8:11], v[72:75], v[88:91]
	v_mfma_f32_16x16x32_bf16 v[88:91], v[16:19], v[64:67], v[180:183]
	v_mfma_f32_16x16x32_bf16 v[116:119], v[24:27], v[72:75], v[88:91]
	v_mfma_f32_16x16x32_bf16 v[88:91], v[0:3], v[48:51], v[108:111]
	v_mfma_f32_16x16x32_bf16 v[104:107], v[8:11], v[56:59], v[88:91]
	v_mfma_f32_16x16x32_bf16 v[88:91], v[16:19], v[48:51], v[184:187]
	v_mfma_f32_16x16x32_bf16 v[108:111], v[24:27], v[56:59], v[88:91]
	v_mfma_f32_16x16x32_bf16 v[88:91], v[0:3], v[32:35], v[100:103]
	v_mfma_f32_16x16x32_bf16 v[96:99], v[8:11], v[40:43], v[88:91]
	v_mfma_f32_16x16x32_bf16 v[88:91], v[16:19], v[32:35], v[188:191]
	v_mfma_f32_16x16x32_bf16 v[100:103], v[24:27], v[40:43], v[88:91]
	s_barrier
	ds_read_b128 v[176:179], v205
	ds_read_b128 v[180:183], v205 offset:1024
	ds_read_b128 v[184:187], v205 offset:2048
	ds_read_b128 v[188:191], v205 offset:3072
	s_mov_b64 s[12:13], -1
	s_and_b64 vcc, exec, s[10:11]
	s_cbranch_vccz .LBB0_1999
	s_waitcnt vmcnt(0)
	s_mov_b64 s[12:13], 0

; #define LDA(dst, b, h) for (int m = 0; m < 4; ++m) for (int k = 0; k < 2; ++k) \
;     dst[m][k] = *reinterpret_cast<const bf16x8*>((char*)SA(b, h) + lds_byte(wr * 64 + m * 16 + fr, k * 32 + fq * 8))
; #define LDB(dst, b, h) for (int n = 0; n < 2; ++n) for (int k = 0; k < 2; ++k) \
;     dst[n][k] = *reinterpret_cast<const bf16x8*>((char*)SB(b, h) + lds_byte(wc * 32 + n * 16 + fr, k * 32 + fq * 8))
; #define WAIT_V(n) asm volatile("s_waitcnt vmcnt(" #n ")" ::: "memory")
; #define WAIT_L(n) asm volatile("s_waitcnt lgkmcnt(" #n ")" ::: "memory")
; #define BAR __builtin_amdgcn_s_barrier()
; template <class Epi>
; DEVI void gemm_phase(const Params& p, const u16* __restrict__ A, const u16* __restrict__ Bt, const int M, const int N, const int K, const int Msplit, const Epi& epi) {
;     ...
;       LDB(B1, 1, 1); if (have2) { WAIT_V(8); } else { WAIT_V(0); } BAR; WAIT_L(0); MMA(0, 1, At, B1); BAR;
;       LDA(At, 1, 1); BAR; WAIT_L(0); MMA(1, 0, At, B0); MMA(1, 1, At, B1); BAR; }
;     if (wr == 0) BAR;
.LBB0_2001:
	s_barrier
	s_waitcnt lgkmcnt(0)
	s_waitcnt lgkmcnt(0)
	v_mfma_f32_16x16x32_bf16 v[88:91], v[176:179], v[80:83], v[92:95]
	v_mfma_f32_16x16x32_bf16 v[80:83], v[184:187], v[80:83], v[128:131]
	v_mfma_f32_16x16x32_bf16 v[92:95], v[188:191], v[192:195], v[80:83]
	v_mfma_f32_16x16x32_bf16 v[80:83], v[176:179], v[64:67], v[84:87]
	v_mfma_f32_16x16x32_bf16 v[64:67], v[184:187], v[64:67], v[132:135]
	v_mfma_f32_16x16x32_bf16 v[84:87], v[188:191], v[72:75], v[64:67]
	v_mfma_f32_16x16x32_bf16 v[64:67], v[176:179], v[48:51], v[76:79]
	v_mfma_f32_16x16x32_bf16 v[48:51], v[184:187], v[48:51], v[136:139]
	v_mfma_f32_16x16x32_bf16 v[76:79], v[188:191], v[56:59], v[48:51]
	v_mfma_f32_16x16x32_bf16 v[48:51], v[176:179], v[32:35], v[68:71]
	v_mfma_f32_16x16x32_bf16 v[32:35], v[184:187], v[32:35], v[140:143]
	v_mfma_f32_16x16x32_bf16 v[88:91], v[180:183], v[192:195], v[88:91]
	v_mfma_f32_16x16x32_bf16 v[80:83], v[180:183], v[72:75], v[80:83]
	v_mfma_f32_16x16x32_bf16 v[72:75], v[180:183], v[56:59], v[64:67]
	v_mfma_f32_16x16x32_bf16 v[64:67], v[180:183], v[40:43], v[48:51]
	v_mfma_f32_16x16x32_bf16 v[68:71], v[188:191], v[40:43], v[32:35]
	s_barrier
	ds_read_b128 v[128:131], v199 offset:49152
	ds_read_b128 v[132:135], v199 offset:50176
	ds_read_b128 v[136:139], v200 offset:49152
	ds_read_b128 v[140:143], v200 offset:50176
	ds_read_b128 v[192:195], v201 offset:49152
	ds_read_b128 v[206:209], v201 offset:50176
	ds_read_b128 v[214:217], v202 offset:49152
	ds_read_b128 v[220:223], v202 offset:50176
	s_barrier
	s_waitcnt lgkmcnt(0)
	s_waitcnt lgkmcnt(0)
	v_mfma_f32_16x16x32_bf16 v[32:35], v[0:3], v[128:131], v[60:63]
	v_mfma_f32_16x16x32_bf16 v[56:59], v[8:11], v[132:135], v[32:35]
	v_mfma_f32_16x16x32_bf16 v[32:35], v[16:19], v[128:131], v[144:147]
	v_mfma_f32_16x16x32_bf16 v[60:63], v[24:27], v[132:135], v[32:35]
	v_mfma_f32_16x16x32_bf16 v[32:35], v[0:3], v[136:139], v[52:55]
	v_mfma_f32_16x16x32_bf16 v[48:51], v[8:11], v[140:143], v[32:35]
	v_mfma_f32_16x16x32_bf16 v[32:35], v[16:19], v[136:139], v[148:151]
	v_mfma_f32_16x16x32_bf16 v[52:55], v[24:27], v[140:143], v[32:35]
	v_mfma_f32_16x16x32_bf16 v[32:35], v[0:3], v[192:195], v[44:47]
	v_mfma_f32_16x16x32_bf16 v[40:43], v[8:11], v[206:209], v[32:35]
	v_mfma_f32_16x16x32_bf16 v[32:35], v[16:19], v[192:195], v[152:155]
	v_mfma_f32_16x16x32_bf16 v[0:3], v[0:3], v[214:217], v[36:39]
	v_mfma_f32_16x16x32_bf16 v[44:47], v[24:27], v[206:209], v[32:35]
	v_mfma_f32_16x16x32_bf16 v[32:35], v[8:11], v[220:223], v[0:3]
	v_mfma_f32_16x16x32_bf16 v[0:3], v[16:19], v[214:217], v[156:159]
	v_mfma_f32_16x16x32_bf16 v[36:39], v[24:27], v[220:223], v[0:3]
	v_mfma_f32_16x16x32_bf16 v[0:3], v[176:179], v[128:131], v[28:31]
	v_mfma_f32_16x16x32_bf16 v[24:27], v[180:183], v[132:135], v[0:3]
	v_mfma_f32_16x16x32_bf16 v[0:3], v[184:187], v[128:131], v[160:163]
	v_mfma_f32_16x16x32_bf16 v[28:31], v[188:191], v[132:135], v[0:3]
	v_mfma_f32_16x16x32_bf16 v[0:3], v[176:179], v[136:139], v[20:23]
	v_mfma_f32_16x16x32_bf16 v[16:19], v[180:183], v[140:143], v[0:3]
	v_mfma_f32_16x16x32_bf16 v[0:3], v[184:187], v[136:139], v[164:167]
	v_mfma_f32_16x16x32_bf16 v[20:23], v[188:191], v[140:143], v[0:3]
	v_mfma_f32_16x16x32_bf16 v[0:3], v[176:179], v[192:195], v[12:15]
	v_mfma_f32_16x16x32_bf16 v[8:11], v[180:183], v[206:209], v[0:3]
	v_mfma_f32_16x16x32_bf16 v[0:3], v[184:187], v[192:195], v[168:171]
	v_mfma_f32_16x16x32_bf16 v[12:15], v[188:191], v[206:209], v[0:3]
	v_mfma_f32_16x16x32_bf16 v[0:3], v[176:179], v[214:217], v[4:7]
	v_mfma_f32_16x16x32_bf16 v[4:7], v[184:187], v[214:217], v[172:175]
	v_mfma_f32_16x16x32_bf16 v[0:3], v[180:183], v[220:223], v[0:3]
	v_mfma_f32_16x16x32_bf16 v[4:7], v[188:191], v[220:223], v[4:7]
	s_barrier
	s_and_saveexec_b64 s[12:13], s[8:9]
	s_cbranch_execz .LBB0_2003
	s_barrier

; #define LDA(dst, b, h) for (int m = 0; m < 4; ++m) for (int k = 0; k < 2; ++k) \
;     dst[m][k] = *reinterpret_cast<const bf16x8*>((char*)SA(b, h) + lds_byte(wr * 64 + m * 16 + fr, k * 32 + fq * 8))
; #define LDB(dst, b, h) for (int n = 0; n < 2; ++n) for (int k = 0; k < 2; ++k) \
;     dst[n][k] = *reinterpret_cast<const bf16x8*>((char*)SB(b, h) + lds_byte(wc * 32 + n * 16 + fr, k * 32 + fq * 8))
; #define WAIT_V(n) asm volatile("s_waitcnt vmcnt(" #n ")" ::: "memory")
; #define WAIT_L(n) asm volatile("s_waitcnt lgkmcnt(" #n ")" ::: "memory")
; #define BAR __builtin_amdgcn_s_barrier()
; #define SCHED __builtin_amdgcn_sched_barrier(0)
; template <class Epi>
; DEVI void gemm_phase(const Params& p, const u16* __restrict__ A, const u16* __restrict__ Bt, const int M, const int N, const int K, const int Msplit, const Epi& epi) {
;     ...
;       LDB(B0, 0, 0); SCHED; LDA(At, 0, 0); STAGE(SA(1, 1), A, brow + HALF, t + 1);
;       WAIT_L(8); BAR; WAIT_L(0); MMA(0, 0, At, B0); BAR; SCHED;
;       LDB(B1, 0, 1); STAGE(SB(0, 0), Bt, bcol, t + 2);
;       BAR; WAIT_L(0); MMA(0, 1, At, B1); BAR;
;       LDA(At, 0, 1); STAGE(SA(0, 0), A, brow, t + 2);
;       BAR; WAIT_L(0); MMA(1, 0, At, B0); BAR; SCHED;
;       STAGE(SB(0, 1), Bt, bcol + HALF, t + 2);
;       WAIT_V(6); BAR; MMA(1, 1, At, B1); BAR;
.LBB0_2080:
	ds_read_b128 v[144:147], v226
	ds_read_b128 v[148:151], v226 offset:1024
	ds_read_b128 v[152:155], v226 offset:2048
	ds_read_b128 v[156:159], v226 offset:3072
	s_add_u32 s54, s40, s10
	s_addc_u32 s55, s41, s11
	s_add_u32 s16, s54, 0x80
	s_addc_u32 s17, s55, 0
	s_add_i32 s56, s78, 0
	s_add_i32 s47, s56, 0xc000
	ds_read_b128 v[160:163], v227
	ds_read_b128 v[164:167], v227 offset:1024
	ds_read_b128 v[168:171], v228
	ds_read_b128 v[172:175], v228 offset:1024
	ds_read_b128 v[176:179], v229
	ds_read_b128 v[180:183], v229 offset:1024
	ds_read_b128 v[184:187], v232
	ds_read_b128 v[188:191], v232 offset:1024
	s_mov_b32 m0, s47
	v_lshl_add_u64 v[192:193], s[16:17], 0, v[208:209]
	s_add_i32 s46, s56, 0xe000
	global_load_lds_dwordx4 v[192:193], off
	v_lshl_add_u64 v[192:193], s[16:17], 0, v[210:211]
	s_mov_b32 m0, s46
	s_nop 0
	global_load_lds_dwordx4 v[192:193], off
	s_waitcnt lgkmcnt(8)
	s_barrier
	s_waitcnt lgkmcnt(0)
	s_waitcnt lgkmcnt(0)
	v_mfma_f32_16x16x32_bf16 v[140:143], v[144:147], v[160:163], v[140:143]
	v_mfma_f32_16x16x32_bf16 v[136:139], v[152:155], v[160:163], v[136:139]
	v_mfma_f32_16x16x32_bf16 v[132:135], v[144:147], v[168:171], v[132:135]
	v_mfma_f32_16x16x32_bf16 v[128:131], v[152:155], v[168:171], v[128:131]
	v_mfma_f32_16x16x32_bf16 v[124:127], v[144:147], v[176:179], v[124:127]
	v_mfma_f32_16x16x32_bf16 v[120:123], v[152:155], v[176:179], v[120:123]
	v_mfma_f32_16x16x32_bf16 v[116:119], v[144:147], v[184:187], v[116:119]
	v_mfma_f32_16x16x32_bf16 v[112:115], v[152:155], v[184:187], v[112:115]
	v_mfma_f32_16x16x32_bf16 v[140:143], v[148:151], v[164:167], v[140:143]
	v_mfma_f32_16x16x32_bf16 v[136:139], v[156:159], v[164:167], v[136:139]
	v_mfma_f32_16x16x32_bf16 v[132:135], v[148:151], v[172:175], v[132:135]
	v_mfma_f32_16x16x32_bf16 v[128:131], v[156:159], v[172:175], v[128:131]
	v_mfma_f32_16x16x32_bf16 v[124:127], v[148:151], v[180:183], v[124:127]
	v_mfma_f32_16x16x32_bf16 v[120:123], v[156:159], v[180:183], v[120:123]
	v_mfma_f32_16x16x32_bf16 v[116:119], v[148:151], v[188:191], v[116:119]
	v_mfma_f32_16x16x32_bf16 v[112:115], v[156:159], v[188:191], v[112:115]
	s_barrier
	s_add_i32 s53, s53, 2
	s_add_u32 s57, s43, s10
	s_addc_u32 s58, s52, s11
	s_add_u32 s16, s57, 0x100
	s_addc_u32 s17, s58, 0
	s_add_i32 s88, s56, 0x10000
	ds_read_b128 v[192:195], v245
	ds_read_b128 v[196:199], v245 offset:1024
	ds_read_b128 v[200:203], v245 offset:2048
	ds_read_b128 v[204:207], v245 offset:3072
	s_mov_b32 m0, s88
	v_lshl_add_u64 v[214:215], s[16:17], 0, v[208:209]
	s_add_i32 s63, s56, 0x12000
	global_load_lds_dwordx4 v[214:215], off
	v_lshl_add_u64 v[214:215], s[16:17], 0, v[210:211]
	s_mov_b32 m0, s63
	s_nop 0
	global_load_lds_dwordx4 v[214:215], off
	s_barrier
	s_waitcnt lgkmcnt(0)
	s_waitcnt lgkmcnt(0)
	v_mfma_f32_16x16x32_bf16 v[108:111], v[192:195], v[160:163], v[108:111]
	v_mfma_f32_16x16x32_bf16 v[104:107], v[200:203], v[160:163], v[104:107]
	v_mfma_f32_16x16x32_bf16 v[100:103], v[192:195], v[168:171], v[100:103]
	v_mfma_f32_16x16x32_bf16 v[96:99], v[200:203], v[168:171], v[96:99]
	v_mfma_f32_16x16x32_bf16 v[92:95], v[192:195], v[176:179], v[92:95]
	v_mfma_f32_16x16x32_bf16 v[88:91], v[200:203], v[176:179], v[88:91]
	v_mfma_f32_16x16x32_bf16 v[84:87], v[192:195], v[184:187], v[84:87]
	v_mfma_f32_16x16x32_bf16 v[80:83], v[200:203], v[184:187], v[80:83]
	v_mfma_f32_16x16x32_bf16 v[108:111], v[196:199], v[164:167], v[108:111]
	v_mfma_f32_16x16x32_bf16 v[104:107], v[204:207], v[164:167], v[104:107]
	v_mfma_f32_16x16x32_bf16 v[100:103], v[196:199], v[172:175], v[100:103]
	v_mfma_f32_16x16x32_bf16 v[96:99], v[204:207], v[172:175], v[96:99]
	v_mfma_f32_16x16x32_bf16 v[92:95], v[196:199], v[180:183], v[92:95]
	v_mfma_f32_16x16x32_bf16 v[88:91], v[204:207], v[180:183], v[88:91]
	v_mfma_f32_16x16x32_bf16 v[84:87], v[196:199], v[188:191], v[84:87]
	v_mfma_f32_16x16x32_bf16 v[80:83], v[204:207], v[188:191], v[80:83]
	s_add_u32 s59, s24, s10
	s_addc_u32 s76, s25, s11
	s_add_u32 s16, s59, 0x100
	s_addc_u32 s17, s76, 0
	s_mov_b32 m0, s56
	s_barrier
	ds_read_b128 v[160:163], v227 offset:16384
	ds_read_b128 v[164:167], v227 offset:17408
	ds_read_b128 v[168:171], v228 offset:16384
	ds_read_b128 v[172:175], v228 offset:17408
	ds_read_b128 v[176:179], v229 offset:16384
	ds_read_b128 v[180:183], v229 offset:17408
	ds_read_b128 v[184:187], v232 offset:16384
	ds_read_b128 v[188:191], v232 offset:17408
	s_nop 0
	v_lshl_add_u64 v[214:215], s[16:17], 0, v[208:209]
	global_load_lds_dwordx4 v[214:215], off
	v_lshl_add_u64 v[214:215], s[16:17], 0, v[210:211]
	s_add_i32 s17, s56, 0x2000
	s_mov_b32 m0, s17
	s_nop 0
	global_load_lds_dwordx4 v[214:215], off
	s_barrier
	s_waitcnt lgkmcnt(0)
	s_waitcnt lgkmcnt(0)
	v_mfma_f32_16x16x32_bf16 v[76:79], v[144:147], v[160:163], v[76:79]
	v_mfma_f32_16x16x32_bf16 v[72:75], v[152:155], v[160:163], v[72:75]
	v_mfma_f32_16x16x32_bf16 v[68:71], v[144:147], v[168:171], v[68:71]
	v_mfma_f32_16x16x32_bf16 v[64:67], v[152:155], v[168:171], v[64:67]
	v_mfma_f32_16x16x32_bf16 v[60:63], v[144:147], v[176:179], v[60:63]
	v_mfma_f32_16x16x32_bf16 v[56:59], v[152:155], v[176:179], v[56:59]
	v_mfma_f32_16x16x32_bf16 v[52:55], v[144:147], v[184:187], v[52:55]
	v_mfma_f32_16x16x32_bf16 v[48:51], v[152:155], v[184:187], v[48:51]
	v_mfma_f32_16x16x32_bf16 v[76:79], v[148:151], v[164:167], v[76:79]
	v_mfma_f32_16x16x32_bf16 v[72:75], v[156:159], v[164:167], v[72:75]
	v_mfma_f32_16x16x32_bf16 v[68:71], v[148:151], v[172:175], v[68:71]
	v_mfma_f32_16x16x32_bf16 v[64:67], v[156:159], v[172:175], v[64:67]
	v_mfma_f32_16x16x32_bf16 v[60:63], v[148:151], v[180:183], v[60:63]
	v_mfma_f32_16x16x32_bf16 v[56:59], v[156:159], v[180:183], v[56:59]
	v_mfma_f32_16x16x32_bf16 v[52:55], v[148:151], v[188:191], v[52:55]
	v_mfma_f32_16x16x32_bf16 v[48:51], v[156:159], v[188:191], v[48:51]
	s_barrier
; #define LDA(dst, b, h) for (int m = 0; m < 4; ++m) for (int k = 0; k < 2; ++k) \
;     dst[m][k] = *reinterpret_cast<const bf16x8*>((char*)SA(b, h) + lds_byte(wr * 64 + m * 16 + fr, k * 32 + fq * 8))
; #define LDB(dst, b, h) for (int n = 0; n < 2; ++n) for (int k = 0; k < 2; ++k) \
;     dst[n][k] = *reinterpret_cast<const bf16x8*>((char*)SB(b, h) + lds_byte(wc * 32 + n * 16 + fr, k * 32 + fq * 8))
; #define WAIT_V(n) asm volatile("s_waitcnt vmcnt(" #n ")" ::: "memory")
; #define WAIT_L(n) asm volatile("s_waitcnt lgkmcnt(" #n ")" ::: "memory")
; #define BAR __builtin_amdgcn_s_barrier()
; #define SCHED __builtin_amdgcn_sched_barrier(0)
; template <class Epi>
; DEVI void gemm_phase(const Params& p, const u16* __restrict__ A, const u16* __restrict__ Bt, const int M, const int N, const int K, const int Msplit, const Epi& epi) {
;     ...
;       STAGE(SB(0, 1), Bt, bcol + HALF, t + 2);
;       WAIT_V(6); BAR; MMA(1, 1, At, B1); BAR;
;       LDB(B0, 1, 0); SCHED; LDA(At, 1, 0); STAGE(SA(0, 1), A, brow + HALF, t + 2);
;       WAIT_L(8); BAR; WAIT_L(0); MMA(0, 0, At, B0); BAR; SCHED;
;       LDB(B1, 1, 1); STAGE(SB(1, 0), Bt, bcol, t + 3);
;       BAR; WAIT_L(0); MMA(0, 1, At, B1); BAR;
;       LDA(At, 1, 1); STAGE(SA(1, 0), A, brow, t + 3);
	s_add_u32 s16, s26, s10
	s_addc_u32 s89, s27, s11
	s_add_u32 s38, s16, 0x100
	s_addc_u32 s39, s89, 0
	s_add_i32 s44, s56, 0x14000
	s_mov_b32 m0, s44
	v_lshl_add_u64 v[144:145], s[38:39], 0, v[208:209]
	s_add_i32 s45, s56, 0x16000
	global_load_lds_dwordx4 v[144:145], off
	v_lshl_add_u64 v[144:145], s[38:39], 0, v[210:211]
	s_mov_b32 m0, s45
	s_nop 0
	global_load_lds_dwordx4 v[144:145], off
	s_waitcnt vmcnt(6)
	s_barrier
	v_mfma_f32_16x16x32_bf16 v[44:47], v[192:195], v[160:163], v[44:47]
	v_mfma_f32_16x16x32_bf16 v[40:43], v[200:203], v[160:163], v[40:43]
	v_mfma_f32_16x16x32_bf16 v[36:39], v[192:195], v[168:171], v[36:39]
	v_mfma_f32_16x16x32_bf16 v[32:35], v[200:203], v[168:171], v[32:35]
	v_mfma_f32_16x16x32_bf16 v[28:31], v[192:195], v[176:179], v[28:31]
	v_mfma_f32_16x16x32_bf16 v[24:27], v[200:203], v[176:179], v[24:27]
	v_mfma_f32_16x16x32_bf16 v[20:23], v[192:195], v[184:187], v[20:23]
	v_mfma_f32_16x16x32_bf16 v[16:19], v[200:203], v[184:187], v[16:19]
	v_mfma_f32_16x16x32_bf16 v[44:47], v[196:199], v[164:167], v[44:47]
	v_mfma_f32_16x16x32_bf16 v[40:43], v[204:207], v[164:167], v[40:43]
	v_mfma_f32_16x16x32_bf16 v[36:39], v[196:199], v[172:175], v[36:39]
	v_mfma_f32_16x16x32_bf16 v[32:35], v[204:207], v[172:175], v[32:35]
	v_mfma_f32_16x16x32_bf16 v[28:31], v[196:199], v[180:183], v[28:31]
	v_mfma_f32_16x16x32_bf16 v[24:27], v[204:207], v[180:183], v[24:27]
	v_mfma_f32_16x16x32_bf16 v[20:23], v[196:199], v[188:191], v[20:23]
	v_mfma_f32_16x16x32_bf16 v[16:19], v[204:207], v[188:191], v[16:19]
	s_barrier
	ds_read_b128 v[144:147], v246
	ds_read_b128 v[148:151], v246 offset:1024
	ds_read_b128 v[152:155], v246 offset:2048
	ds_read_b128 v[156:159], v246 offset:3072
	s_add_u32 s54, s54, 0x100
	s_addc_u32 s55, s55, 0
	s_add_i32 s38, s56, 0x4000
	ds_read_b128 v[160:163], v227 offset:32768
	ds_read_b128 v[164:167], v227 offset:33792
	ds_read_b128 v[168:171], v228 offset:32768
	ds_read_b128 v[172:175], v228 offset:33792
	ds_read_b128 v[176:179], v229 offset:32768
	ds_read_b128 v[180:183], v229 offset:33792
	ds_read_b128 v[184:187], v232 offset:32768
	ds_read_b128 v[188:191], v232 offset:33792
	s_mov_b32 m0, s38
	v_lshl_add_u64 v[192:193], s[54:55], 0, v[208:209]
	s_add_i32 s39, s56, 0x6000
	global_load_lds_dwordx4 v[192:193], off
	v_lshl_add_u64 v[192:193], s[54:55], 0, v[210:211]
	s_mov_b32 m0, s39
	s_nop 0
	global_load_lds_dwordx4 v[192:193], off
	s_waitcnt lgkmcnt(8)
	s_barrier
	s_waitcnt lgkmcnt(0)
	s_waitcnt lgkmcnt(0)
	v_mfma_f32_16x16x32_bf16 v[140:143], v[144:147], v[160:163], v[140:143]
	v_mfma_f32_16x16x32_bf16 v[136:139], v[152:155], v[160:163], v[136:139]
	v_mfma_f32_16x16x32_bf16 v[132:135], v[144:147], v[168:171], v[132:135]
	v_mfma_f32_16x16x32_bf16 v[128:131], v[152:155], v[168:171], v[128:131]
	v_mfma_f32_16x16x32_bf16 v[124:127], v[144:147], v[176:179], v[124:127]
	v_mfma_f32_16x16x32_bf16 v[120:123], v[152:155], v[176:179], v[120:123]
	v_mfma_f32_16x16x32_bf16 v[116:119], v[144:147], v[184:187], v[116:119]
	v_mfma_f32_16x16x32_bf16 v[112:115], v[152:155], v[184:187], v[112:115]
	v_mfma_f32_16x16x32_bf16 v[140:143], v[148:151], v[164:167], v[140:143]
	v_mfma_f32_16x16x32_bf16 v[136:139], v[156:159], v[164:167], v[136:139]
	v_mfma_f32_16x16x32_bf16 v[132:135], v[148:151], v[172:175], v[132:135]
	v_mfma_f32_16x16x32_bf16 v[128:131], v[156:159], v[172:175], v[128:131]
	v_mfma_f32_16x16x32_bf16 v[124:127], v[148:151], v[180:183], v[124:127]
	v_mfma_f32_16x16x32_bf16 v[120:123], v[156:159], v[180:183], v[120:123]
	v_mfma_f32_16x16x32_bf16 v[116:119], v[148:151], v[188:191], v[116:119]
	v_mfma_f32_16x16x32_bf16 v[112:115], v[156:159], v[188:191], v[112:115]
	s_barrier
	s_add_u32 s54, s57, 0x180
	s_addc_u32 s55, s58, 0
	s_add_i32 s62, s56, 0x18000
	ds_read_b128 v[192:195], v247
	ds_read_b128 v[196:199], v247 offset:1024
	ds_read_b128 v[200:203], v247 offset:2048
	ds_read_b128 v[204:207], v247 offset:3072
	s_mov_b32 m0, s62
	v_lshl_add_u64 v[214:215], s[54:55], 0, v[208:209]
	s_add_i32 s57, s56, 0x1a000
	global_load_lds_dwordx4 v[214:215], off
	v_lshl_add_u64 v[214:215], s[54:55], 0, v[210:211]
	s_mov_b32 m0, s57
	s_nop 0
	global_load_lds_dwordx4 v[214:215], off
	s_barrier
	s_waitcnt lgkmcnt(0)
	s_waitcnt lgkmcnt(0)
	v_mfma_f32_16x16x32_bf16 v[108:111], v[192:195], v[160:163], v[108:111]
	v_mfma_f32_16x16x32_bf16 v[104:107], v[200:203], v[160:163], v[104:107]
	v_mfma_f32_16x16x32_bf16 v[100:103], v[192:195], v[168:171], v[100:103]
	v_mfma_f32_16x16x32_bf16 v[96:99], v[200:203], v[168:171], v[96:99]
	v_mfma_f32_16x16x32_bf16 v[92:95], v[192:195], v[176:179], v[92:95]
	v_mfma_f32_16x16x32_bf16 v[88:91], v[200:203], v[176:179], v[88:91]
	v_mfma_f32_16x16x32_bf16 v[84:87], v[192:195], v[184:187], v[84:87]
	v_mfma_f32_16x16x32_bf16 v[80:83], v[200:203], v[184:187], v[80:83]
	v_mfma_f32_16x16x32_bf16 v[108:111], v[196:199], v[164:167], v[108:111]
	v_mfma_f32_16x16x32_bf16 v[104:107], v[204:207], v[164:167], v[104:107]
	v_mfma_f32_16x16x32_bf16 v[100:103], v[196:199], v[172:175], v[100:103]
	v_mfma_f32_16x16x32_bf16 v[96:99], v[204:207], v[172:175], v[96:99]
	v_mfma_f32_16x16x32_bf16 v[92:95], v[196:199], v[180:183], v[92:95]
	v_mfma_f32_16x16x32_bf16 v[88:91], v[204:207], v[180:183], v[88:91]
	v_mfma_f32_16x16x32_bf16 v[84:87], v[196:199], v[188:191], v[84:87]
	v_mfma_f32_16x16x32_bf16 v[80:83], v[204:207], v[188:191], v[80:83]
	s_add_u32 s54, s59, 0x180
	s_addc_u32 s55, s76, 0
	s_add_i32 s76, s56, 0x8000
	s_barrier
; #define LDA(dst, b, h) for (int m = 0; m < 4; ++m) for (int k = 0; k < 2; ++k) \
;     dst[m][k] = *reinterpret_cast<const bf16x8*>((char*)SA(b, h) + lds_byte(wr * 64 + m * 16 + fr, k * 32 + fq * 8))
; #define LDB(dst, b, h) for (int n = 0; n < 2; ++n) for (int k = 0; k < 2; ++k) \
;     dst[n][k] = *reinterpret_cast<const bf16x8*>((char*)SB(b, h) + lds_byte(wc * 32 + n * 16 + fr, k * 32 + fq * 8))
; #define WAIT_V(n) asm volatile("s_waitcnt vmcnt(" #n ")" ::: "memory")
; #define WAIT_L(n) asm volatile("s_waitcnt lgkmcnt(" #n ")" ::: "memory")
; #define BAR __builtin_amdgcn_s_barrier()
; #define SCHED __builtin_amdgcn_sched_barrier(0)
; template <class Epi>
; DEVI void gemm_phase(const Params& p, const u16* __restrict__ A, const u16* __restrict__ Bt, const int M, const int N, const int K, const int Msplit, const Epi& epi) {
;     ...
;       LDA(At, 1, 1); STAGE(SA(1, 0), A, brow, t + 3);
;       BAR; WAIT_L(0); MMA(1, 0, At, B0); BAR; SCHED;
;       STAGE(SB(1, 1), Bt, bcol + HALF, t + 3);
;       WAIT_V(6); BAR; MMA(1, 1, At, B1); BAR;
;     }
;     { LDB(B0, 0, 0); LDA(At, 0, 0); STAGE(SA(1, 1), A, brow + HALF, nt - 1);
;       BAR; WAIT_L(0); MMA(0, 0, At, B0); BAR;
	ds_read_b128 v[160:163], v227 offset:49152
	ds_read_b128 v[164:167], v227 offset:50176
	ds_read_b128 v[168:171], v228 offset:49152
	ds_read_b128 v[172:175], v228 offset:50176
	ds_read_b128 v[176:179], v229 offset:49152
	ds_read_b128 v[180:183], v229 offset:50176
	ds_read_b128 v[184:187], v232 offset:49152
	ds_read_b128 v[188:191], v232 offset:50176
	s_mov_b32 m0, s76
	v_lshl_add_u64 v[214:215], s[54:55], 0, v[208:209]
	s_add_i32 s77, s56, 0xa000
	global_load_lds_dwordx4 v[214:215], off
	v_lshl_add_u64 v[214:215], s[54:55], 0, v[210:211]
	s_mov_b32 m0, s77
	s_nop 0
	global_load_lds_dwordx4 v[214:215], off
	s_barrier
	s_waitcnt lgkmcnt(0)
	s_waitcnt lgkmcnt(0)
	v_mfma_f32_16x16x32_bf16 v[76:79], v[144:147], v[160:163], v[76:79]
	v_mfma_f32_16x16x32_bf16 v[72:75], v[152:155], v[160:163], v[72:75]
	v_mfma_f32_16x16x32_bf16 v[68:71], v[144:147], v[168:171], v[68:71]
	v_mfma_f32_16x16x32_bf16 v[64:67], v[152:155], v[168:171], v[64:67]
	v_mfma_f32_16x16x32_bf16 v[60:63], v[144:147], v[176:179], v[60:63]
	v_mfma_f32_16x16x32_bf16 v[56:59], v[152:155], v[176:179], v[56:59]
	v_mfma_f32_16x16x32_bf16 v[52:55], v[144:147], v[184:187], v[52:55]
	v_mfma_f32_16x16x32_bf16 v[48:51], v[152:155], v[184:187], v[48:51]
	v_mfma_f32_16x16x32_bf16 v[76:79], v[148:151], v[164:167], v[76:79]
	v_mfma_f32_16x16x32_bf16 v[72:75], v[156:159], v[164:167], v[72:75]
	v_mfma_f32_16x16x32_bf16 v[68:71], v[148:151], v[172:175], v[68:71]
	v_mfma_f32_16x16x32_bf16 v[64:67], v[156:159], v[172:175], v[64:67]
	v_mfma_f32_16x16x32_bf16 v[60:63], v[148:151], v[180:183], v[60:63]
	v_mfma_f32_16x16x32_bf16 v[56:59], v[156:159], v[180:183], v[56:59]
	v_mfma_f32_16x16x32_bf16 v[52:55], v[148:151], v[188:191], v[52:55]
	v_mfma_f32_16x16x32_bf16 v[48:51], v[156:159], v[188:191], v[48:51]
	s_barrier
	s_add_u32 s54, s16, 0x180
	s_addc_u32 s55, s89, 0
	s_add_i32 s89, s56, 0x1c000
	s_mov_b32 m0, s89
	v_lshl_add_u64 v[144:145], s[54:55], 0, v[208:209]
	s_add_i32 s16, s56, 0x1e000
	global_load_lds_dwordx4 v[144:145], off
	v_lshl_add_u64 v[144:145], s[54:55], 0, v[210:211]
	s_mov_b32 m0, s16
	s_nop 0
	global_load_lds_dwordx4 v[144:145], off
	s_waitcnt vmcnt(6)
	s_barrier
	v_mfma_f32_16x16x32_bf16 v[44:47], v[192:195], v[160:163], v[44:47]
	v_mfma_f32_16x16x32_bf16 v[40:43], v[200:203], v[160:163], v[40:43]
	v_mfma_f32_16x16x32_bf16 v[36:39], v[192:195], v[168:171], v[36:39]
	v_mfma_f32_16x16x32_bf16 v[32:35], v[200:203], v[168:171], v[32:35]
	v_mfma_f32_16x16x32_bf16 v[28:31], v[192:195], v[176:179], v[28:31]
	v_mfma_f32_16x16x32_bf16 v[24:27], v[200:203], v[176:179], v[24:27]
	v_mfma_f32_16x16x32_bf16 v[20:23], v[192:195], v[184:187], v[20:23]
	v_mfma_f32_16x16x32_bf16 v[16:19], v[200:203], v[184:187], v[16:19]
	v_mfma_f32_16x16x32_bf16 v[44:47], v[196:199], v[164:167], v[44:47]
	v_mfma_f32_16x16x32_bf16 v[40:43], v[204:207], v[164:167], v[40:43]
	v_mfma_f32_16x16x32_bf16 v[36:39], v[196:199], v[172:175], v[36:39]
	v_mfma_f32_16x16x32_bf16 v[32:35], v[204:207], v[172:175], v[32:35]
	v_mfma_f32_16x16x32_bf16 v[28:31], v[196:199], v[180:183], v[28:31]
	v_mfma_f32_16x16x32_bf16 v[24:27], v[204:207], v[180:183], v[24:27]
	v_mfma_f32_16x16x32_bf16 v[20:23], v[196:199], v[188:191], v[20:23]
	v_mfma_f32_16x16x32_bf16 v[16:19], v[204:207], v[188:191], v[16:19]
	s_add_u32 s10, s10, 0x100
	s_addc_u32 s11, s11, 0
	s_cmp_ge_i32 s53, s42
	s_barrier
	s_cbranch_scc0 .LBB0_2080
	s_lshl_b64 s[10:11], s[90:91], 7
	s_add_u32 s24, s60, s10
	s_addc_u32 s25, s61, s11
	s_add_u32 s26, s12, s10
	s_addc_u32 s27, s13, s11
	s_add_i32 s10, s36, -1
	s_mov_b32 s11, s91
	s_lshl_b64 s[10:11], s[10:11], 7
	s_add_u32 s10, s40, s10
	s_addc_u32 s11, s41, s11
	s_mov_b32 m0, s47
	ds_read_b128 v[144:147], v226
	ds_read_b128 v[148:151], v226 offset:1024
	ds_read_b128 v[152:155], v226 offset:2048
	ds_read_b128 v[156:159], v226 offset:3072
	ds_read_b128 v[160:163], v227
	ds_read_b128 v[164:167], v227 offset:1024
	ds_read_b128 v[168:171], v228
	ds_read_b128 v[172:175], v228 offset:1024
	ds_read_b128 v[176:179], v229
	ds_read_b128 v[180:183], v229 offset:1024
	ds_read_b128 v[184:187], v232
	ds_read_b128 v[188:191], v232 offset:1024
	s_nop 0
	v_lshl_add_u64 v[192:193], s[10:11], 0, v[208:209]
	global_load_lds_dwordx4 v[192:193], off
	v_lshl_add_u64 v[192:193], s[10:11], 0, v[210:211]
	s_mov_b32 m0, s46
	s_nop 0
	global_load_lds_dwordx4 v[192:193], off
	s_barrier
	s_waitcnt lgkmcnt(0)
	s_waitcnt lgkmcnt(0)
	v_mfma_f32_16x16x32_bf16 v[140:143], v[144:147], v[160:163], v[140:143]
	v_mfma_f32_16x16x32_bf16 v[136:139], v[152:155], v[160:163], v[136:139]
	v_mfma_f32_16x16x32_bf16 v[132:135], v[144:147], v[168:171], v[132:135]
	v_mfma_f32_16x16x32_bf16 v[128:131], v[152:155], v[168:171], v[128:131]
	v_mfma_f32_16x16x32_bf16 v[124:127], v[144:147], v[176:179], v[124:127]
	v_mfma_f32_16x16x32_bf16 v[120:123], v[152:155], v[176:179], v[120:123]
	v_mfma_f32_16x16x32_bf16 v[116:119], v[144:147], v[184:187], v[116:119]
	v_mfma_f32_16x16x32_bf16 v[112:115], v[152:155], v[184:187], v[112:115]
	v_mfma_f32_16x16x32_bf16 v[140:143], v[148:151], v[164:167], v[140:143]
	v_mfma_f32_16x16x32_bf16 v[136:139], v[156:159], v[164:167], v[136:139]
	v_mfma_f32_16x16x32_bf16 v[132:135], v[148:151], v[172:175], v[132:135]
	v_mfma_f32_16x16x32_bf16 v[128:131], v[156:159], v[172:175], v[128:131]
	v_mfma_f32_16x16x32_bf16 v[124:127], v[148:151], v[180:183], v[124:127]
	v_mfma_f32_16x16x32_bf16 v[120:123], v[156:159], v[180:183], v[120:123]
	v_mfma_f32_16x16x32_bf16 v[116:119], v[148:151], v[188:191], v[116:119]
	v_mfma_f32_16x16x32_bf16 v[112:115], v[156:159], v[188:191], v[112:115]
	s_barrier
; #define LDA(dst, b, h) for (int m = 0; m < 4; ++m) for (int k = 0; k < 2; ++k) \
;     dst[m][k] = *reinterpret_cast<const bf16x8*>((char*)SA(b, h) + lds_byte(wr * 64 + m * 16 + fr, k * 32 + fq * 8))
; #define LDB(dst, b, h) for (int n = 0; n < 2; ++n) for (int k = 0; k < 2; ++k) \
;     dst[n][k] = *reinterpret_cast<const bf16x8*>((char*)SB(b, h) + lds_byte(wc * 32 + n * 16 + fr, k * 32 + fq * 8))
; #define WAIT_V(n) asm volatile("s_waitcnt vmcnt(" #n ")" ::: "memory")
; #define WAIT_L(n) asm volatile("s_waitcnt lgkmcnt(" #n ")" ::: "memory")
; #define BAR __builtin_amdgcn_s_barrier()
; #define PRO_K0(brow_, bcol_) do { STAGE(SB(0, 0), Bt, bcol_, 0); STAGE(SA(0, 0), A, brow_, 0); STAGE(SB(0, 1), Bt, (bcol_) + HALF, 0); STAGE(SA(0, 1), A, (brow_) + HALF, 0); } while (0)
; template <class Epi>
; DEVI void gemm_phase(const Params& p, const u16* __restrict__ A, const u16* __restrict__ Bt, const int M, const int N, const int K, const int Msplit, const Epi& epi) {
;     ...
;       LDB(B1, 0, 1); BAR; WAIT_L(0); MMA(0, 1, At, B1); BAR;
;       LDA(At, 0, 1); WAIT_V(4); BAR; WAIT_L(0); MMA(1, 0, At, B0); MMA(1, 1, At, B1); BAR; }
;     { LDB(B0, 1, 0); LDA(At, 1, 0); WAIT_V(2); BAR;
;       if (have2) { const u16* Asv = A; const u16* Bsv = Bt; A = An; Bt = Bn; PRO_K0(pm * BM, pn * BM); A = Asv; Bt = Bsv; }
	ds_read_b128 v[192:195], v245
	ds_read_b128 v[196:199], v245 offset:1024
	ds_read_b128 v[200:203], v245 offset:2048
	ds_read_b128 v[204:207], v245 offset:3072
	s_barrier
	s_waitcnt lgkmcnt(0)
	s_waitcnt lgkmcnt(0)
	v_mfma_f32_16x16x32_bf16 v[108:111], v[192:195], v[160:163], v[108:111]
	v_mfma_f32_16x16x32_bf16 v[104:107], v[200:203], v[160:163], v[104:107]
	v_mfma_f32_16x16x32_bf16 v[100:103], v[192:195], v[168:171], v[100:103]
	v_mfma_f32_16x16x32_bf16 v[96:99], v[200:203], v[168:171], v[96:99]
	v_mfma_f32_16x16x32_bf16 v[92:95], v[192:195], v[176:179], v[92:95]
	v_mfma_f32_16x16x32_bf16 v[88:91], v[200:203], v[176:179], v[88:91]
	v_mfma_f32_16x16x32_bf16 v[84:87], v[192:195], v[184:187], v[84:87]
	v_mfma_f32_16x16x32_bf16 v[80:83], v[200:203], v[184:187], v[80:83]
	v_mfma_f32_16x16x32_bf16 v[108:111], v[196:199], v[164:167], v[108:111]
	v_mfma_f32_16x16x32_bf16 v[104:107], v[204:207], v[164:167], v[104:107]
	v_mfma_f32_16x16x32_bf16 v[100:103], v[196:199], v[172:175], v[100:103]
	v_mfma_f32_16x16x32_bf16 v[96:99], v[204:207], v[172:175], v[96:99]
	v_mfma_f32_16x16x32_bf16 v[92:95], v[196:199], v[180:183], v[92:95]
	v_mfma_f32_16x16x32_bf16 v[88:91], v[204:207], v[180:183], v[88:91]
	v_mfma_f32_16x16x32_bf16 v[84:87], v[196:199], v[188:191], v[84:87]
	v_mfma_f32_16x16x32_bf16 v[80:83], v[204:207], v[188:191], v[80:83]
	s_barrier
	ds_read_b128 v[160:163], v227 offset:16384
	ds_read_b128 v[164:167], v227 offset:17408
	ds_read_b128 v[168:171], v228 offset:16384
	ds_read_b128 v[172:175], v228 offset:17408
	ds_read_b128 v[176:179], v229 offset:16384
	ds_read_b128 v[180:183], v229 offset:17408
	ds_read_b128 v[184:187], v232 offset:16384
	ds_read_b128 v[188:191], v232 offset:17408
	s_waitcnt vmcnt(4)
	s_barrier
	s_waitcnt lgkmcnt(0)
	s_waitcnt lgkmcnt(0)
	v_mfma_f32_16x16x32_bf16 v[76:79], v[144:147], v[160:163], v[76:79]
	v_mfma_f32_16x16x32_bf16 v[72:75], v[152:155], v[160:163], v[72:75]
	v_mfma_f32_16x16x32_bf16 v[68:71], v[144:147], v[168:171], v[68:71]
	v_mfma_f32_16x16x32_bf16 v[64:67], v[152:155], v[168:171], v[64:67]
	v_mfma_f32_16x16x32_bf16 v[60:63], v[144:147], v[176:179], v[60:63]
	v_mfma_f32_16x16x32_bf16 v[56:59], v[152:155], v[176:179], v[56:59]
	v_mfma_f32_16x16x32_bf16 v[52:55], v[144:147], v[184:187], v[52:55]
	v_mfma_f32_16x16x32_bf16 v[48:51], v[152:155], v[184:187], v[48:51]
	v_mfma_f32_16x16x32_bf16 v[76:79], v[148:151], v[164:167], v[76:79]
	v_mfma_f32_16x16x32_bf16 v[72:75], v[156:159], v[164:167], v[72:75]
	v_mfma_f32_16x16x32_bf16 v[68:71], v[148:151], v[172:175], v[68:71]
	v_mfma_f32_16x16x32_bf16 v[64:67], v[156:159], v[172:175], v[64:67]
	v_mfma_f32_16x16x32_bf16 v[60:63], v[148:151], v[180:183], v[60:63]
	v_mfma_f32_16x16x32_bf16 v[56:59], v[156:159], v[180:183], v[56:59]
	v_mfma_f32_16x16x32_bf16 v[52:55], v[148:151], v[188:191], v[52:55]
	v_mfma_f32_16x16x32_bf16 v[48:51], v[156:159], v[188:191], v[48:51]
	v_mfma_f32_16x16x32_bf16 v[44:47], v[192:195], v[160:163], v[44:47]
	v_mfma_f32_16x16x32_bf16 v[40:43], v[200:203], v[160:163], v[40:43]
	v_mfma_f32_16x16x32_bf16 v[36:39], v[192:195], v[168:171], v[36:39]
	v_mfma_f32_16x16x32_bf16 v[32:35], v[200:203], v[168:171], v[32:35]
	v_mfma_f32_16x16x32_bf16 v[28:31], v[192:195], v[176:179], v[28:31]
	v_mfma_f32_16x16x32_bf16 v[24:27], v[200:203], v[176:179], v[24:27]
	v_mfma_f32_16x16x32_bf16 v[20:23], v[192:195], v[184:187], v[20:23]
	v_mfma_f32_16x16x32_bf16 v[16:19], v[200:203], v[184:187], v[16:19]
	v_mfma_f32_16x16x32_bf16 v[44:47], v[196:199], v[164:167], v[44:47]
	v_mfma_f32_16x16x32_bf16 v[40:43], v[204:207], v[164:167], v[40:43]
	v_mfma_f32_16x16x32_bf16 v[36:39], v[196:199], v[172:175], v[36:39]
	v_mfma_f32_16x16x32_bf16 v[32:35], v[204:207], v[172:175], v[32:35]
	v_mfma_f32_16x16x32_bf16 v[28:31], v[196:199], v[180:183], v[28:31]
	v_mfma_f32_16x16x32_bf16 v[24:27], v[204:207], v[180:183], v[24:27]
	v_mfma_f32_16x16x32_bf16 v[20:23], v[196:199], v[188:191], v[20:23]
	v_mfma_f32_16x16x32_bf16 v[16:19], v[204:207], v[188:191], v[16:19]
	s_barrier
	ds_read_b128 v[144:147], v246
	ds_read_b128 v[148:151], v246 offset:1024
	ds_read_b128 v[152:155], v246 offset:2048
	ds_read_b128 v[156:159], v246 offset:3072
	ds_read_b128 v[184:187], v227 offset:32768
	ds_read_b128 v[188:191], v227 offset:33792
	ds_read_b128 v[176:179], v228 offset:32768
	ds_read_b128 v[180:183], v228 offset:33792
	ds_read_b128 v[168:171], v229 offset:32768
	ds_read_b128 v[172:175], v229 offset:33792
	ds_read_b128 v[160:163], v232 offset:32768
	ds_read_b128 v[164:167], v232 offset:33792
	s_waitcnt vmcnt(2)
	s_and_b64 vcc, exec, s[8:9]
	s_mul_i32 s40, s18, 0x160000
	s_mul_i32 s36, s49, 0x160000
	s_barrier
	s_cbranch_vccz .LBB0_2083
	s_lshl_b32 s41, s18, 8
	s_mul_hi_i32 s11, s41, 0x1600
	s_add_u32 s10, s26, s40
	s_addc_u32 s11, s27, s11
	s_mov_b32 m0, s88
	s_lshl_b32 s42, s49, 8
	v_lshl_add_u64 v[192:193], s[10:11], 0, v[208:209]
	global_load_lds_dwordx4 v[192:193], off
	v_lshl_add_u64 v[192:193], s[10:11], 0, v[210:211]
	s_mul_hi_i32 s11, s42, 0x1600
	s_add_u32 s10, s24, s36
	s_mov_b32 m0, s63
	s_addc_u32 s11, s25, s11
	global_load_lds_dwordx4 v[192:193], off
	s_mov_b32 m0, s56
	v_lshl_add_u64 v[192:193], s[10:11], 0, v[208:209]
	global_load_lds_dwordx4 v[192:193], off
	v_lshl_add_u64 v[192:193], s[10:11], 0, v[210:211]
	s_or_b32 s10, s41, 0x80
	s_mul_hi_i32 s11, s10, 0x1600
	s_mulk_i32 s10, 0x1600
	s_add_u32 s10, s26, s10
	s_mov_b32 m0, s17
	s_addc_u32 s11, s27, s11
	global_load_lds_dwordx4 v[192:193], off
	s_mov_b32 m0, s44
	v_lshl_add_u64 v[192:193], s[10:11], 0, v[208:209]
	global_load_lds_dwordx4 v[192:193], off
	v_lshl_add_u64 v[192:193], s[10:11], 0, v[210:211]
	s_or_b32 s10, s42, 0x80
	s_mul_hi_i32 s11, s10, 0x1600
	s_mulk_i32 s10, 0x1600
	s_add_u32 s10, s24, s10
	s_mov_b32 m0, s45
	s_addc_u32 s11, s25, s11
	global_load_lds_dwordx4 v[192:193], off
	s_mov_b32 m0, s38
	v_lshl_add_u64 v[192:193], s[10:11], 0, v[208:209]
	global_load_lds_dwordx4 v[192:193], off
	v_lshl_add_u64 v[192:193], s[10:11], 0, v[210:211]
	s_mov_b32 m0, s39
	s_nop 0
	global_load_lds_dwordx4 v[192:193], off
; #define LDB(dst, b, h) for (int n = 0; n < 2; ++n) for (int k = 0; k < 2; ++k) \
;     dst[n][k] = *reinterpret_cast<const bf16x8*>((char*)SB(b, h) + lds_byte(wc * 32 + n * 16 + fr, k * 32 + fq * 8))
; #define WAIT_V(n) asm volatile("s_waitcnt vmcnt(" #n ")" ::: "memory")
; #define WAIT_L(n) asm volatile("s_waitcnt lgkmcnt(" #n ")" ::: "memory")
; #define BAR __builtin_amdgcn_s_barrier()
; template <class Epi>
; DEVI void gemm_phase(const Params& p, const u16* __restrict__ A, const u16* __restrict__ Bt, const int M, const int N, const int K, const int Msplit, const Epi& epi) {
;     ...
;       WAIT_L(0); MMA(0, 0, At, B0); BAR;
;       LDB(B1, 1, 1); if (have2) { WAIT_V(8); } else { WAIT_V(0); } BAR; WAIT_L(0); MMA(0, 1, At, B1); BAR;
.LBB0_2083:
	s_waitcnt lgkmcnt(0)
	s_waitcnt lgkmcnt(0)
	v_mfma_f32_16x16x32_bf16 v[140:143], v[144:147], v[184:187], v[140:143]
	v_mfma_f32_16x16x32_bf16 v[136:139], v[152:155], v[184:187], v[136:139]
	v_mfma_f32_16x16x32_bf16 v[132:135], v[144:147], v[176:179], v[132:135]
	v_mfma_f32_16x16x32_bf16 v[128:131], v[152:155], v[176:179], v[128:131]
	v_mfma_f32_16x16x32_bf16 v[124:127], v[144:147], v[168:171], v[124:127]
	v_mfma_f32_16x16x32_bf16 v[120:123], v[152:155], v[168:171], v[120:123]
	v_mfma_f32_16x16x32_bf16 v[116:119], v[144:147], v[160:163], v[116:119]
	v_mfma_f32_16x16x32_bf16 v[112:115], v[152:155], v[160:163], v[112:115]
	v_mfma_f32_16x16x32_bf16 v[140:143], v[148:151], v[188:191], v[140:143]
	v_mfma_f32_16x16x32_bf16 v[136:139], v[156:159], v[188:191], v[136:139]
	v_mfma_f32_16x16x32_bf16 v[132:135], v[148:151], v[180:183], v[132:135]
	v_mfma_f32_16x16x32_bf16 v[128:131], v[156:159], v[180:183], v[128:131]
	v_mfma_f32_16x16x32_bf16 v[124:127], v[148:151], v[172:175], v[124:127]
	v_mfma_f32_16x16x32_bf16 v[120:123], v[156:159], v[172:175], v[120:123]
	v_mfma_f32_16x16x32_bf16 v[116:119], v[148:151], v[164:167], v[116:119]
	v_mfma_f32_16x16x32_bf16 v[112:115], v[156:159], v[164:167], v[112:115]
	s_barrier
	ds_read_b128 v[192:195], v247
	ds_read_b128 v[196:199], v247 offset:1024
	ds_read_b128 v[200:203], v247 offset:2048
	ds_read_b128 v[204:207], v247 offset:3072
	s_mov_b64 s[10:11], -1
	s_and_b64 vcc, exec, s[20:21]
	s_cbranch_vccz .LBB0_2085
	s_waitcnt vmcnt(0)
	s_mov_b64 s[10:11], 0

; #define LDA(dst, b, h) for (int m = 0; m < 4; ++m) for (int k = 0; k < 2; ++k) \
;     dst[m][k] = *reinterpret_cast<const bf16x8*>((char*)SA(b, h) + lds_byte(wr * 64 + m * 16 + fr, k * 32 + fq * 8))
; #define LDB(dst, b, h) for (int n = 0; n < 2; ++n) for (int k = 0; k < 2; ++k) \
;     dst[n][k] = *reinterpret_cast<const bf16x8*>((char*)SB(b, h) + lds_byte(wc * 32 + n * 16 + fr, k * 32 + fq * 8))
; #define WAIT_V(n) asm volatile("s_waitcnt vmcnt(" #n ")" ::: "memory")
; #define WAIT_L(n) asm volatile("s_waitcnt lgkmcnt(" #n ")" ::: "memory")
; #define BAR __builtin_amdgcn_s_barrier()
; template <class Epi>
; DEVI void gemm_phase(const Params& p, const u16* __restrict__ A, const u16* __restrict__ Bt, const int M, const int N, const int K, const int Msplit, const Epi& epi) {
;     ...
;       LDB(B1, 1, 1); if (have2) { WAIT_V(8); } else { WAIT_V(0); } BAR; WAIT_L(0); MMA(0, 1, At, B1); BAR;
;       LDA(At, 1, 1); BAR; WAIT_L(0); MMA(1, 0, At, B0); MMA(1, 1, At, B1); BAR; }
;     if (wr == 0) BAR;
.LBB0_2087:
	s_barrier
	s_waitcnt lgkmcnt(0)
	s_waitcnt lgkmcnt(0)
	v_mfma_f32_16x16x32_bf16 v[108:111], v[192:195], v[184:187], v[108:111]
	v_mfma_f32_16x16x32_bf16 v[104:107], v[200:203], v[184:187], v[104:107]
	v_mfma_f32_16x16x32_bf16 v[100:103], v[192:195], v[176:179], v[100:103]
	v_mfma_f32_16x16x32_bf16 v[96:99], v[200:203], v[176:179], v[96:99]
	v_mfma_f32_16x16x32_bf16 v[92:95], v[192:195], v[168:171], v[92:95]
	v_mfma_f32_16x16x32_bf16 v[88:91], v[200:203], v[168:171], v[88:91]
	v_mfma_f32_16x16x32_bf16 v[84:87], v[192:195], v[160:163], v[84:87]
	v_mfma_f32_16x16x32_bf16 v[80:83], v[200:203], v[160:163], v[80:83]
	v_mfma_f32_16x16x32_bf16 v[108:111], v[196:199], v[188:191], v[108:111]
	v_mfma_f32_16x16x32_bf16 v[104:107], v[204:207], v[188:191], v[104:107]
	v_mfma_f32_16x16x32_bf16 v[100:103], v[196:199], v[180:183], v[100:103]
	v_mfma_f32_16x16x32_bf16 v[96:99], v[204:207], v[180:183], v[96:99]
	v_mfma_f32_16x16x32_bf16 v[92:95], v[196:199], v[172:175], v[92:95]
	v_mfma_f32_16x16x32_bf16 v[88:91], v[204:207], v[172:175], v[88:91]
	v_mfma_f32_16x16x32_bf16 v[84:87], v[196:199], v[164:167], v[84:87]
	v_mfma_f32_16x16x32_bf16 v[80:83], v[204:207], v[164:167], v[80:83]
	s_barrier
	ds_read_b128 v[160:163], v227 offset:49152
	ds_read_b128 v[164:167], v227 offset:50176
	ds_read_b128 v[168:171], v228 offset:49152
	ds_read_b128 v[172:175], v228 offset:50176
	ds_read_b128 v[176:179], v229 offset:49152
	ds_read_b128 v[180:183], v229 offset:50176
	ds_read_b128 v[184:187], v232 offset:49152
	ds_read_b128 v[188:191], v232 offset:50176
	s_barrier
	s_waitcnt lgkmcnt(0)
	s_waitcnt lgkmcnt(0)
	v_mfma_f32_16x16x32_bf16 v[76:79], v[144:147], v[160:163], v[76:79]
	v_mfma_f32_16x16x32_bf16 v[72:75], v[152:155], v[160:163], v[72:75]
	v_mfma_f32_16x16x32_bf16 v[68:71], v[144:147], v[168:171], v[68:71]
	v_mfma_f32_16x16x32_bf16 v[64:67], v[152:155], v[168:171], v[64:67]
	v_mfma_f32_16x16x32_bf16 v[60:63], v[144:147], v[176:179], v[60:63]
	v_mfma_f32_16x16x32_bf16 v[56:59], v[152:155], v[176:179], v[56:59]
	v_mfma_f32_16x16x32_bf16 v[52:55], v[144:147], v[184:187], v[52:55]
	v_mfma_f32_16x16x32_bf16 v[48:51], v[152:155], v[184:187], v[48:51]
	v_mfma_f32_16x16x32_bf16 v[76:79], v[148:151], v[164:167], v[76:79]
	v_mfma_f32_16x16x32_bf16 v[72:75], v[156:159], v[164:167], v[72:75]
	v_mfma_f32_16x16x32_bf16 v[68:71], v[148:151], v[172:175], v[68:71]
	v_mfma_f32_16x16x32_bf16 v[64:67], v[156:159], v[172:175], v[64:67]
	v_mfma_f32_16x16x32_bf16 v[60:63], v[148:151], v[180:183], v[60:63]
	v_mfma_f32_16x16x32_bf16 v[56:59], v[156:159], v[180:183], v[56:59]
	v_mfma_f32_16x16x32_bf16 v[52:55], v[148:151], v[188:191], v[52:55]
	v_mfma_f32_16x16x32_bf16 v[48:51], v[156:159], v[188:191], v[48:51]
	v_mfma_f32_16x16x32_bf16 v[44:47], v[192:195], v[160:163], v[44:47]
	v_mfma_f32_16x16x32_bf16 v[40:43], v[200:203], v[160:163], v[40:43]
	v_mfma_f32_16x16x32_bf16 v[36:39], v[192:195], v[168:171], v[36:39]
	v_mfma_f32_16x16x32_bf16 v[32:35], v[200:203], v[168:171], v[32:35]
	v_mfma_f32_16x16x32_bf16 v[28:31], v[192:195], v[176:179], v[28:31]
	v_mfma_f32_16x16x32_bf16 v[24:27], v[200:203], v[176:179], v[24:27]
	v_mfma_f32_16x16x32_bf16 v[20:23], v[192:195], v[184:187], v[20:23]
	v_mfma_f32_16x16x32_bf16 v[16:19], v[200:203], v[184:187], v[16:19]
	v_mfma_f32_16x16x32_bf16 v[44:47], v[196:199], v[164:167], v[44:47]
	v_mfma_f32_16x16x32_bf16 v[40:43], v[204:207], v[164:167], v[40:43]
	v_mfma_f32_16x16x32_bf16 v[36:39], v[196:199], v[172:175], v[36:39]
	v_mfma_f32_16x16x32_bf16 v[32:35], v[204:207], v[172:175], v[32:35]
	v_mfma_f32_16x16x32_bf16 v[28:31], v[196:199], v[180:183], v[28:31]
	v_mfma_f32_16x16x32_bf16 v[24:27], v[204:207], v[180:183], v[24:27]
	v_mfma_f32_16x16x32_bf16 v[20:23], v[196:199], v[188:191], v[20:23]
	v_mfma_f32_16x16x32_bf16 v[16:19], v[204:207], v[188:191], v[16:19]
	s_barrier
	s_and_saveexec_b64 s[10:11], s[6:7]
	s_cbranch_execz .LBB0_2089
	s_barrier
